# epilogue memory-op restructuring: P6 stores widened via permlane16_swap + residual loads hoisted per row block; P8 residual loads hoisted; P5 G/bias loads hoisted per row block with counted vmcnt
# speedup vs baseline: 1.0166x; 1.0166x over previous
; __device__ __forceinline__ u32x2 pack4(f32x4 v) { u32x2 r; r.x = cvt_pk(v[0], v[1]); r.y = cvt_pk(v[2], v[3]); return r; }
; __device__ __forceinline__ float sigmoidf_(float x) { return __builtin_amdgcn_rcpf(1.0f + __builtin_amdgcn_exp2f(-1.4426950408889634f * x)); }
; #define FOR_AI_M _Pragma("unroll") for (int ai = 0; ai < 2; ++ai) _Pragma("unroll") for (int m = 0; m < 4; ++m)
; #define FOR_BJ_N _Pragma("unroll") for (int bj = 0; bj < 2; ++bj) _Pragma("unroll") for (int n = 0; n < 2; ++n)
;     __device__ __forceinline__ void operator()(EPI_ARGS) const {
;         FOR_AI_M {
;             const int row = u.pm * 256 + ai * 128 + wr * 64 + m * 16 + fr; float ss = 0.f;
;             FOR_BJ_N { const int col = u.pn * 256 + bj * 128 + wc * 32 + n * 16 + 4 * fq;
;                 const f32x4 gg = unpack4(*(const u32x2*)(G + ((size_t)row * 1024 + col))); const f32x4 bb = *(const f32x4*)(bglu + col); f32x4 o;
; #pragma unroll
;                 for (int e = 0; e < 4; ++e) { o[e] = gg[e] * sigmoidf_(acc[ai][bj][m][n][e] + bb[e]); ss += o[e] * o[e]; }
;                 *(u32x2*)(Y + ((size_t)row * 2048 + col)) = pack4(o); }
;             ss += __shfl_xor(ss, 16); ss += __shfl_xor(ss, 32);
;             if (fq == 0) atomicAdd(ssq_a + row, ss);
;         }
;     }
.LBB0_881:
	s_or_b64 exec, exec, s[6:7]
	global_load_dwordx4 v[176:179], v[140:141], off
	v_add_u32_e32 v182, 16, v146
	v_ashrrev_i32_e32 v183, 31, v182
	v_lshlrev_b64 v[184:185], 11, v[182:183]
	v_lshl_add_u64 v[186:187], s[60:61], 0, v[184:185]
	v_lshl_add_u64 v[188:189], v[186:187], 0, v[142:143]
	global_load_dwordx2 v[180:181], v[188:189], off
	global_load_dwordx4 v[182:185], v[140:141], off offset:64
	v_add_u32_e32 v188, 16, v146
	v_ashrrev_i32_e32 v189, 31, v188
	v_lshlrev_b64 v[190:191], 11, v[188:189]
	v_lshl_add_u64 v[192:193], s[60:61], 0, v[190:191]
	v_lshl_add_u64 v[194:195], v[192:193], 0, v[124:125]
	global_load_dwordx2 v[186:187], v[194:195], off
	v_add_u32_e32 v190, 16, v146
	v_ashrrev_i32_e32 v191, 31, v190
	v_lshlrev_b64 v[192:193], 11, v[190:191]
	v_lshl_add_u64 v[194:195], s[60:61], 0, v[192:193]
	v_lshl_add_u64 v[196:197], v[194:195], 0, v[120:121]
	global_load_dwordx2 v[188:189], v[196:197], off
	global_load_dwordx4 v[190:193], v[140:141], off offset:512
	v_add_u32_e32 v196, 16, v146
	v_ashrrev_i32_e32 v197, 31, v196
	v_lshlrev_b64 v[198:199], 11, v[196:197]
	v_lshl_add_u64 v[200:201], s[60:61], 0, v[198:199]
	v_lshl_add_u64 v[202:203], v[200:201], 0, v[116:117]
	global_load_dwordx2 v[194:195], v[202:203], off
	global_load_dwordx4 v[196:199], v[140:141], off offset:576
	s_waitcnt vmcnt(7)
	v_mov_b64_e32 v[148:149], v[176:177]
	v_mov_b64_e32 v[150:151], v[178:179]
	v_add_u32_e32 v112, 16, v146
	s_waitcnt lgkmcnt(0)
	v_ashrrev_i32_e32 v113, 31, v112
	v_lshlrev_b64 v[114:115], 11, v[112:113]
	v_lshl_add_u64 v[114:115], s[60:61], 0, v[114:115]
	v_lshl_add_u64 v[122:123], v[114:115], 0, v[142:143]
	s_waitcnt vmcnt(6)
	v_mov_b64_e32 v[122:123], v[180:181]
	v_lshlrev_b64 v[126:127], 12, v[112:113]
	v_add_f32_e32 v108, v108, v148
	v_add_f32_e32 v110, v110, v150
	v_mul_f32_e32 v108, 0xbfb8aa3b, v108
	v_mul_f32_e32 v110, 0xbfb8aa3b, v110
	v_exp_f32_e32 v108, v108
	v_exp_f32_e32 v110, v110
	v_add_f32_e32 v109, v109, v149
	v_lshlrev_b32_e32 v147, 16, v122
	v_add_f32_e32 v108, 1.0, v108
	v_add_f32_e32 v110, 1.0, v110
	v_rcp_f32_e32 v108, v108
	v_rcp_f32_e32 v110, v110
	v_lshlrev_b32_e32 v159, 16, v123
	v_mul_f32_e32 v109, 0xbfb8aa3b, v109
	v_mul_f32_e32 v108, v108, v147
	v_exp_f32_e32 v109, v109
	v_mul_f32_e32 v147, v110, v159
	v_add_f32_e32 v110, v111, v151
	v_mul_f32_e32 v110, 0xbfb8aa3b, v110
	v_exp_f32_e32 v110, v110
	v_add_f32_e32 v109, 1.0, v109
	v_rcp_f32_e32 v109, v109
	v_and_b32_e32 v122, 0xffff0000, v122
	v_add_f32_e32 v110, 1.0, v110
	v_rcp_f32_e32 v110, v110
	v_mul_f32_e32 v109, v109, v122
	v_and_b32_e32 v123, 0xffff0000, v123
	v_mul_f32_e32 v122, v109, v109
	v_fmac_f32_e32 v122, v108, v108
	v_mul_f32_e32 v111, v110, v123
	v_cvt_pk_bf16_f32 v110, v108, v109
	v_lshl_add_u64 v[108:109], s[58:59], 0, v[126:127]
	v_fmac_f32_e32 v122, v147, v147
	v_lshl_add_u64 v[126:127], v[108:109], 0, v[142:143]
	v_fmac_f32_e32 v122, v111, v111
	v_cvt_pk_bf16_f32 v111, v147, v111
	global_store_dwordx2 v[126:127], v[110:111], off
	s_waitcnt vmcnt(6)
	v_mov_b64_e32 v[148:149], v[182:183]
	v_mov_b64_e32 v[150:151], v[184:185]
	v_lshl_add_u64 v[110:111], v[114:115], 0, v[124:125]
	s_waitcnt vmcnt(5)
	v_mov_b64_e32 v[110:111], v[186:187]
	v_add_f32_e32 v104, v104, v148
	v_mul_f32_e32 v104, 0xbfb8aa3b, v104
	v_add_f32_e32 v105, v105, v149
	v_exp_f32_e32 v104, v104
	v_mul_f32_e32 v105, 0xbfb8aa3b, v105
	v_add_f32_e32 v106, v106, v150
	v_exp_f32_e32 v105, v105
	v_mul_f32_e32 v106, 0xbfb8aa3b, v106
	v_add_f32_e32 v107, v107, v151
	v_exp_f32_e32 v106, v106
	v_mul_f32_e32 v107, 0xbfb8aa3b, v107
	v_exp_f32_e32 v107, v107
	v_add_f32_e32 v104, 1.0, v104
	v_rcp_f32_e32 v104, v104
	v_add_f32_e32 v105, 1.0, v105
	v_rcp_f32_e32 v105, v105
	v_add_f32_e32 v106, 1.0, v106
	v_rcp_f32_e32 v106, v106
	v_add_f32_e32 v107, 1.0, v107
	v_lshlrev_b32_e32 v123, 16, v110
	v_rcp_f32_e32 v107, v107
	v_and_b32_e32 v110, 0xffff0000, v110
	v_mul_f32_e32 v104, v104, v123
	v_lshlrev_b32_e32 v126, 16, v111
	v_fmac_f32_e32 v122, v104, v104
	v_mul_f32_e32 v105, v105, v110
	v_and_b32_e32 v111, 0xffff0000, v111
	v_fmac_f32_e32 v122, v105, v105
	v_mul_f32_e32 v106, v106, v126
	v_fmac_f32_e32 v122, v106, v106
	v_mul_f32_e32 v107, v107, v111
	v_fmac_f32_e32 v122, v107, v107
	v_cvt_pk_bf16_f32 v104, v104, v105
	v_cvt_pk_bf16_f32 v105, v106, v107
	v_lshl_add_u64 v[106:107], v[108:109], 0, v[124:125]
	global_store_dwordx2 v[106:107], v[104:105], off
	v_lshl_add_u64 v[104:105], v[114:115], 0, v[120:121]
	s_waitcnt vmcnt(5)
	v_mov_b64_e32 v[104:105], v[188:189]
	v_lshlrev_b32_e32 v110, 16, v104
	v_and_b32_e32 v111, 0xffff0000, v104
	v_lshlrev_b32_e32 v123, 16, v105
	v_and_b32_e32 v126, 0xffff0000, v105
	s_waitcnt vmcnt(4)
	v_mov_b64_e32 v[104:105], v[190:191]
	v_mov_b64_e32 v[106:107], v[192:193]
	v_add_f32_e32 v100, v100, v104
	v_mul_f32_e32 v100, 0xbfb8aa3b, v100
	v_add_f32_e32 v101, v101, v105
	v_exp_f32_e32 v100, v100
	v_mul_f32_e32 v101, 0xbfb8aa3b, v101
	v_add_f32_e32 v102, v102, v106
	v_exp_f32_e32 v101, v101
	v_mul_f32_e32 v102, 0xbfb8aa3b, v102
	v_add_f32_e32 v103, v103, v107
	v_exp_f32_e32 v102, v102
	v_mul_f32_e32 v103, 0xbfb8aa3b, v103
	v_exp_f32_e32 v103, v103
	v_add_f32_e32 v100, 1.0, v100
	v_rcp_f32_e32 v100, v100
	v_add_f32_e32 v101, 1.0, v101
	v_rcp_f32_e32 v101, v101
	v_add_f32_e32 v102, 1.0, v102
	v_rcp_f32_e32 v102, v102
	v_add_f32_e32 v103, 1.0, v103
	v_rcp_f32_e32 v103, v103
	v_mul_f32_e32 v100, v100, v110
	v_fmac_f32_e32 v122, v100, v100
	v_mul_f32_e32 v101, v101, v111
	v_fmac_f32_e32 v122, v101, v101
	v_mul_f32_e32 v102, v102, v123
	v_fmac_f32_e32 v122, v102, v102
	v_mul_f32_e32 v103, v103, v126
	v_fmac_f32_e32 v122, v103, v103
	v_cvt_pk_bf16_f32 v100, v100, v101
	v_cvt_pk_bf16_f32 v101, v102, v103
	v_lshl_add_u64 v[102:103], v[108:109], 0, v[120:121]
	global_store_dwordx2 v[102:103], v[100:101], off
	v_lshl_add_u64 v[100:101], v[114:115], 0, v[116:117]
	s_waitcnt vmcnt(4)
; __device__ __forceinline__ u32x2 pack4(f32x4 v) { u32x2 r; r.x = cvt_pk(v[0], v[1]); r.y = cvt_pk(v[2], v[3]); return r; }
; __device__ __forceinline__ float sigmoidf_(float x) { return __builtin_amdgcn_rcpf(1.0f + __builtin_amdgcn_exp2f(-1.4426950408889634f * x)); }
; #define FOR_AI_M _Pragma("unroll") for (int ai = 0; ai < 2; ++ai) _Pragma("unroll") for (int m = 0; m < 4; ++m)
; #define FOR_BJ_N _Pragma("unroll") for (int bj = 0; bj < 2; ++bj) _Pragma("unroll") for (int n = 0; n < 2; ++n)
;     __device__ __forceinline__ void operator()(EPI_ARGS) const {
;         FOR_AI_M {
;             const int row = u.pm * 256 + ai * 128 + wr * 64 + m * 16 + fr; float ss = 0.f;
;             FOR_BJ_N { const int col = u.pn * 256 + bj * 128 + wc * 32 + n * 16 + 4 * fq;
;                 const f32x4 gg = unpack4(*(const u32x2*)(G + ((size_t)row * 1024 + col))); const f32x4 bb = *(const f32x4*)(bglu + col); f32x4 o;
; #pragma unroll
;                 for (int e = 0; e < 4; ++e) { o[e] = gg[e] * sigmoidf_(acc[ai][bj][m][n][e] + bb[e]); ss += o[e] * o[e]; }
;                 *(u32x2*)(Y + ((size_t)row * 2048 + col)) = pack4(o); }
;             ss += __shfl_xor(ss, 16); ss += __shfl_xor(ss, 32);
;             if (fq == 0) atomicAdd(ssq_a + row, ss);
;         }
;     }
	v_mov_b64_e32 v[100:101], v[194:195]
	v_lshlrev_b32_e32 v104, 16, v100
	v_and_b32_e32 v105, 0xffff0000, v100
	v_lshlrev_b32_e32 v106, 16, v101
	v_and_b32_e32 v107, 0xffff0000, v101
	s_waitcnt vmcnt(3)
	v_mov_b64_e32 v[100:101], v[196:197]
	v_mov_b64_e32 v[102:103], v[198:199]
	v_add_f32_e32 v96, v96, v100
	v_mul_f32_e32 v96, 0xbfb8aa3b, v96
	v_add_f32_e32 v97, v97, v101
	v_exp_f32_e32 v96, v96
	v_mul_f32_e32 v97, 0xbfb8aa3b, v97
	v_add_f32_e32 v98, v98, v102
	v_exp_f32_e32 v97, v97
	v_mul_f32_e32 v98, 0xbfb8aa3b, v98
	v_add_f32_e32 v99, v99, v103
	v_exp_f32_e32 v98, v98
	v_mul_f32_e32 v99, 0xbfb8aa3b, v99
	v_exp_f32_e32 v99, v99
	v_add_f32_e32 v96, 1.0, v96
	v_rcp_f32_e32 v96, v96
	v_add_f32_e32 v97, 1.0, v97
	v_rcp_f32_e32 v97, v97
	v_add_f32_e32 v98, 1.0, v98
	v_rcp_f32_e32 v98, v98
	v_add_f32_e32 v99, 1.0, v99
	v_rcp_f32_e32 v99, v99
	v_mul_f32_e32 v96, v96, v104
	v_fmac_f32_e32 v122, v96, v96
	v_mul_f32_e32 v97, v97, v105
	v_fmac_f32_e32 v122, v97, v97
	v_mul_f32_e32 v98, v98, v106
	v_fmac_f32_e32 v122, v98, v98
	v_mul_f32_e32 v99, v99, v107
	v_fmac_f32_e32 v122, v99, v99
	v_cvt_pk_bf16_f32 v96, v96, v97
	v_cvt_pk_bf16_f32 v97, v98, v99
	v_lshl_add_u64 v[98:99], v[108:109], 0, v[116:117]
	global_store_dwordx2 v[98:99], v[96:97], off
	ds_bpermute_b32 v96, v118, v122
	s_waitcnt lgkmcnt(0)
	v_add_f32_e32 v96, v122, v96
	ds_bpermute_b32 v97, v119, v96
	s_and_saveexec_b64 s[6:7], vcc
	s_cbranch_execz .LBB0_883
	v_lshl_add_u64 v[98:99], v[112:113], 2, s[4:5]
	s_waitcnt lgkmcnt(0)
	v_add_f32_e32 v96, v96, v97
	global_atomic_add_f32 v[98:99], v96, off
.LBB0_883:
	s_or_b64 exec, exec, s[6:7]
	v_add_u32_e32 v178, 32, v146
	v_ashrrev_i32_e32 v179, 31, v178
	v_lshlrev_b64 v[180:181], 11, v[178:179]
	v_lshl_add_u64 v[182:183], s[60:61], 0, v[180:181]
	v_lshl_add_u64 v[184:185], v[182:183], 0, v[142:143]
	global_load_dwordx2 v[176:177], v[184:185], off
	global_load_dwordx4 v[178:181], v[140:141], off
	global_load_dwordx4 v[182:185], v[140:141], off offset:64
	v_add_u32_e32 v188, 32, v146
	v_ashrrev_i32_e32 v189, 31, v188
	v_lshlrev_b64 v[190:191], 11, v[188:189]
	v_lshl_add_u64 v[192:193], s[60:61], 0, v[190:191]
	v_lshl_add_u64 v[194:195], v[192:193], 0, v[124:125]
	global_load_dwordx2 v[186:187], v[194:195], off
	v_add_u32_e32 v190, 32, v146
	v_ashrrev_i32_e32 v191, 31, v190
	v_lshlrev_b64 v[192:193], 11, v[190:191]
	v_lshl_add_u64 v[194:195], s[60:61], 0, v[192:193]
	v_lshl_add_u64 v[196:197], v[194:195], 0, v[120:121]
	global_load_dwordx2 v[188:189], v[196:197], off
	global_load_dwordx4 v[190:193], v[140:141], off offset:512
	v_add_u32_e32 v196, 32, v146
	v_ashrrev_i32_e32 v197, 31, v196
	v_lshlrev_b64 v[198:199], 11, v[196:197]
	v_lshl_add_u64 v[200:201], s[60:61], 0, v[198:199]
	v_lshl_add_u64 v[202:203], v[200:201], 0, v[116:117]
	global_load_dwordx2 v[194:195], v[202:203], off
	global_load_dwordx4 v[196:199], v[140:141], off offset:576
	v_add_u32_e32 v96, 32, v146
	s_waitcnt lgkmcnt(0)
	v_ashrrev_i32_e32 v97, 31, v96
	v_lshlrev_b64 v[98:99], 11, v[96:97]
	v_lshl_add_u64 v[98:99], s[60:61], 0, v[98:99]
	v_lshl_add_u64 v[100:101], v[98:99], 0, v[142:143]
	s_waitcnt vmcnt(7)
	v_mov_b64_e32 v[100:101], v[176:177]
	v_lshlrev_b64 v[104:105], 12, v[96:97]
	v_lshlrev_b32_e32 v106, 16, v100
	v_and_b32_e32 v107, 0xffff0000, v100
	v_lshlrev_b32_e32 v108, 16, v101
	v_and_b32_e32 v109, 0xffff0000, v101
	s_waitcnt vmcnt(6)
	v_mov_b64_e32 v[100:101], v[178:179]
	v_mov_b64_e32 v[102:103], v[180:181]
	v_add_f32_e32 v94, v94, v102
	v_mul_f32_e32 v94, 0xbfb8aa3b, v94
	v_exp_f32_e32 v94, v94
	v_add_f32_e32 v93, v93, v101
	v_add_f32_e32 v92, v92, v100
	v_mul_f32_e32 v93, 0xbfb8aa3b, v93
	v_add_f32_e32 v94, 1.0, v94
	v_rcp_f32_e32 v94, v94
	v_mul_f32_e32 v92, 0xbfb8aa3b, v92
	v_exp_f32_e32 v93, v93
	v_exp_f32_e32 v92, v92
	v_mul_f32_e32 v101, v94, v108
	v_add_f32_e32 v94, v95, v103
	v_mul_f32_e32 v94, 0xbfb8aa3b, v94
	v_exp_f32_e32 v94, v94
	v_add_f32_e32 v93, 1.0, v93
	v_add_f32_e32 v92, 1.0, v92
	v_rcp_f32_e32 v93, v93
	v_rcp_f32_e32 v92, v92
	v_add_f32_e32 v94, 1.0, v94
	v_rcp_f32_e32 v94, v94
	v_mul_f32_e32 v93, v93, v107
	v_mul_f32_e32 v92, v92, v106
	v_mul_f32_e32 v100, v93, v93
	v_fmac_f32_e32 v100, v92, v92
	v_mul_f32_e32 v95, v94, v109
	v_cvt_pk_bf16_f32 v94, v92, v93
	v_lshl_add_u64 v[92:93], s[58:59], 0, v[104:105]
	v_fmac_f32_e32 v100, v101, v101
	v_lshl_add_u64 v[102:103], v[92:93], 0, v[142:143]
	v_fmac_f32_e32 v100, v95, v95
	v_cvt_pk_bf16_f32 v95, v101, v95
	global_store_dwordx2 v[102:103], v[94:95], off
	s_waitcnt vmcnt(6)
	v_mov_b64_e32 v[102:103], v[182:183]
	v_mov_b64_e32 v[104:105], v[184:185]
	v_lshl_add_u64 v[94:95], v[98:99], 0, v[124:125]
	s_waitcnt vmcnt(5)
	v_mov_b64_e32 v[94:95], v[186:187]
	v_add_f32_e32 v88, v88, v102
	v_mul_f32_e32 v88, 0xbfb8aa3b, v88
	v_add_f32_e32 v89, v89, v103
	v_exp_f32_e32 v88, v88
	v_mul_f32_e32 v89, 0xbfb8aa3b, v89
	v_add_f32_e32 v90, v90, v104
	v_exp_f32_e32 v89, v89
	v_mul_f32_e32 v90, 0xbfb8aa3b, v90
	v_add_f32_e32 v91, v91, v105
	v_exp_f32_e32 v90, v90
	v_mul_f32_e32 v91, 0xbfb8aa3b, v91
	v_exp_f32_e32 v91, v91
	v_add_f32_e32 v88, 1.0, v88
	v_rcp_f32_e32 v88, v88
	v_add_f32_e32 v89, 1.0, v89
	v_rcp_f32_e32 v89, v89
	v_add_f32_e32 v90, 1.0, v90
	v_rcp_f32_e32 v90, v90
	v_add_f32_e32 v91, 1.0, v91
	v_lshlrev_b32_e32 v101, 16, v94
	v_rcp_f32_e32 v91, v91
	v_and_b32_e32 v94, 0xffff0000, v94
	v_mul_f32_e32 v88, v88, v101
	v_lshlrev_b32_e32 v106, 16, v95
	v_fmac_f32_e32 v100, v88, v88
	v_mul_f32_e32 v89, v89, v94
	v_and_b32_e32 v95, 0xffff0000, v95
	v_fmac_f32_e32 v100, v89, v89
	v_mul_f32_e32 v90, v90, v106
	v_fmac_f32_e32 v100, v90, v90
	v_mul_f32_e32 v91, v91, v95
	v_fmac_f32_e32 v100, v91, v91
	v_cvt_pk_bf16_f32 v88, v88, v89
	v_cvt_pk_bf16_f32 v89, v90, v91
	v_lshl_add_u64 v[90:91], v[92:93], 0, v[124:125]
	global_store_dwordx2 v[90:91], v[88:89], off
	v_lshl_add_u64 v[88:89], v[98:99], 0, v[120:121]
	s_waitcnt vmcnt(5)
; __device__ __forceinline__ u32x2 pack4(f32x4 v) { u32x2 r; r.x = cvt_pk(v[0], v[1]); r.y = cvt_pk(v[2], v[3]); return r; }
; __device__ __forceinline__ float sigmoidf_(float x) { return __builtin_amdgcn_rcpf(1.0f + __builtin_amdgcn_exp2f(-1.4426950408889634f * x)); }
; #define FOR_AI_M _Pragma("unroll") for (int ai = 0; ai < 2; ++ai) _Pragma("unroll") for (int m = 0; m < 4; ++m)
; #define FOR_BJ_N _Pragma("unroll") for (int bj = 0; bj < 2; ++bj) _Pragma("unroll") for (int n = 0; n < 2; ++n)
;     __device__ __forceinline__ void operator()(EPI_ARGS) const {
;         FOR_AI_M {
;             const int row = u.pm * 256 + ai * 128 + wr * 64 + m * 16 + fr; float ss = 0.f;
;             FOR_BJ_N { const int col = u.pn * 256 + bj * 128 + wc * 32 + n * 16 + 4 * fq;
;                 const f32x4 gg = unpack4(*(const u32x2*)(G + ((size_t)row * 1024 + col))); const f32x4 bb = *(const f32x4*)(bglu + col); f32x4 o;
; #pragma unroll
;                 for (int e = 0; e < 4; ++e) { o[e] = gg[e] * sigmoidf_(acc[ai][bj][m][n][e] + bb[e]); ss += o[e] * o[e]; }
;                 *(u32x2*)(Y + ((size_t)row * 2048 + col)) = pack4(o); }
;             ss += __shfl_xor(ss, 16); ss += __shfl_xor(ss, 32);
;             if (fq == 0) atomicAdd(ssq_a + row, ss);
;         }
;     }
	v_mov_b64_e32 v[88:89], v[188:189]
	v_lshlrev_b32_e32 v94, 16, v88
	v_and_b32_e32 v95, 0xffff0000, v88
	v_lshlrev_b32_e32 v101, 16, v89
	v_and_b32_e32 v102, 0xffff0000, v89
	s_waitcnt vmcnt(4)
	v_mov_b64_e32 v[88:89], v[190:191]
	v_mov_b64_e32 v[90:91], v[192:193]
	v_add_f32_e32 v84, v84, v88
	v_mul_f32_e32 v84, 0xbfb8aa3b, v84
	v_add_f32_e32 v85, v85, v89
	v_exp_f32_e32 v84, v84
	v_mul_f32_e32 v85, 0xbfb8aa3b, v85
	v_add_f32_e32 v86, v86, v90
	v_exp_f32_e32 v85, v85
	v_mul_f32_e32 v86, 0xbfb8aa3b, v86
	v_add_f32_e32 v87, v87, v91
	v_exp_f32_e32 v86, v86
	v_mul_f32_e32 v87, 0xbfb8aa3b, v87
	v_exp_f32_e32 v87, v87
	v_add_f32_e32 v84, 1.0, v84
	v_rcp_f32_e32 v84, v84
	v_add_f32_e32 v85, 1.0, v85
	v_rcp_f32_e32 v85, v85
	v_add_f32_e32 v86, 1.0, v86
	v_rcp_f32_e32 v86, v86
	v_add_f32_e32 v87, 1.0, v87
	v_rcp_f32_e32 v87, v87
	v_mul_f32_e32 v84, v84, v94
	v_fmac_f32_e32 v100, v84, v84
	v_mul_f32_e32 v85, v85, v95
	v_fmac_f32_e32 v100, v85, v85
	v_mul_f32_e32 v86, v86, v101
	v_fmac_f32_e32 v100, v86, v86
	v_mul_f32_e32 v87, v87, v102
	v_fmac_f32_e32 v100, v87, v87
	v_cvt_pk_bf16_f32 v84, v84, v85
	v_cvt_pk_bf16_f32 v85, v86, v87
	v_lshl_add_u64 v[86:87], v[92:93], 0, v[120:121]
	global_store_dwordx2 v[86:87], v[84:85], off
	v_lshl_add_u64 v[84:85], v[98:99], 0, v[116:117]
	s_waitcnt vmcnt(4)
	v_mov_b64_e32 v[84:85], v[194:195]
	v_lshlrev_b32_e32 v88, 16, v84
	v_and_b32_e32 v89, 0xffff0000, v84
	v_lshlrev_b32_e32 v90, 16, v85
	v_and_b32_e32 v91, 0xffff0000, v85
	s_waitcnt vmcnt(3)
	v_mov_b64_e32 v[84:85], v[196:197]
	v_mov_b64_e32 v[86:87], v[198:199]
	v_add_f32_e32 v80, v80, v84
	v_mul_f32_e32 v80, 0xbfb8aa3b, v80
	v_add_f32_e32 v81, v81, v85
	v_exp_f32_e32 v80, v80
	v_mul_f32_e32 v81, 0xbfb8aa3b, v81
	v_add_f32_e32 v82, v82, v86
	v_exp_f32_e32 v81, v81
	v_mul_f32_e32 v82, 0xbfb8aa3b, v82
	v_add_f32_e32 v83, v83, v87
	v_exp_f32_e32 v82, v82
	v_mul_f32_e32 v83, 0xbfb8aa3b, v83
	v_exp_f32_e32 v83, v83
	v_add_f32_e32 v80, 1.0, v80
	v_rcp_f32_e32 v80, v80
	v_add_f32_e32 v81, 1.0, v81
	v_rcp_f32_e32 v81, v81
	v_add_f32_e32 v82, 1.0, v82
	v_rcp_f32_e32 v82, v82
	v_add_f32_e32 v83, 1.0, v83
	v_rcp_f32_e32 v83, v83
	v_mul_f32_e32 v80, v80, v88
	v_fmac_f32_e32 v100, v80, v80
	v_mul_f32_e32 v81, v81, v89
	v_fmac_f32_e32 v100, v81, v81
	v_mul_f32_e32 v82, v82, v90
	v_fmac_f32_e32 v100, v82, v82
	v_mul_f32_e32 v83, v83, v91
	v_fmac_f32_e32 v100, v83, v83
	v_cvt_pk_bf16_f32 v80, v80, v81
	v_cvt_pk_bf16_f32 v81, v82, v83
	v_lshl_add_u64 v[82:83], v[92:93], 0, v[116:117]
	global_store_dwordx2 v[82:83], v[80:81], off
	ds_bpermute_b32 v80, v118, v100
	s_waitcnt lgkmcnt(0)
	v_add_f32_e32 v80, v100, v80
	ds_bpermute_b32 v81, v119, v80
	s_and_saveexec_b64 s[6:7], vcc
	s_cbranch_execz .LBB0_885
	v_lshl_add_u64 v[82:83], v[96:97], 2, s[4:5]
	s_waitcnt lgkmcnt(0)
	v_add_f32_e32 v80, v80, v81
	global_atomic_add_f32 v[82:83], v80, off
.LBB0_885:
	s_or_b64 exec, exec, s[6:7]
	v_add_u32_e32 v178, 48, v146
	v_ashrrev_i32_e32 v179, 31, v178
	v_lshlrev_b64 v[180:181], 11, v[178:179]
	v_lshl_add_u64 v[182:183], s[60:61], 0, v[180:181]
	v_lshl_add_u64 v[184:185], v[182:183], 0, v[142:143]
	global_load_dwordx2 v[176:177], v[184:185], off
	global_load_dwordx4 v[178:181], v[140:141], off
	global_load_dwordx4 v[182:185], v[140:141], off offset:64
	v_add_u32_e32 v188, 48, v146
	v_ashrrev_i32_e32 v189, 31, v188
	v_lshlrev_b64 v[190:191], 11, v[188:189]
	v_lshl_add_u64 v[192:193], s[60:61], 0, v[190:191]
	v_lshl_add_u64 v[194:195], v[192:193], 0, v[124:125]
	global_load_dwordx2 v[186:187], v[194:195], off
	v_add_u32_e32 v190, 48, v146
	v_ashrrev_i32_e32 v191, 31, v190
	v_lshlrev_b64 v[192:193], 11, v[190:191]
	v_lshl_add_u64 v[194:195], s[60:61], 0, v[192:193]
	v_lshl_add_u64 v[196:197], v[194:195], 0, v[120:121]
	global_load_dwordx2 v[188:189], v[196:197], off
	global_load_dwordx4 v[190:193], v[140:141], off offset:512
	v_add_u32_e32 v196, 48, v146
	v_ashrrev_i32_e32 v197, 31, v196
	v_lshlrev_b64 v[198:199], 11, v[196:197]
	v_lshl_add_u64 v[200:201], s[60:61], 0, v[198:199]
	v_lshl_add_u64 v[202:203], v[200:201], 0, v[116:117]
	global_load_dwordx2 v[194:195], v[202:203], off
	global_load_dwordx4 v[196:199], v[140:141], off offset:576
	v_add_u32_e32 v80, 48, v146
	s_waitcnt lgkmcnt(0)
	v_ashrrev_i32_e32 v81, 31, v80
	v_lshlrev_b64 v[82:83], 11, v[80:81]
	v_lshl_add_u64 v[82:83], s[60:61], 0, v[82:83]
	v_lshl_add_u64 v[84:85], v[82:83], 0, v[142:143]
	s_waitcnt vmcnt(7)
	v_mov_b64_e32 v[84:85], v[176:177]
	v_lshlrev_b64 v[88:89], 12, v[80:81]
	v_lshlrev_b32_e32 v90, 16, v84
	v_and_b32_e32 v91, 0xffff0000, v84
	v_lshlrev_b32_e32 v92, 16, v85
	v_and_b32_e32 v93, 0xffff0000, v85
	s_waitcnt vmcnt(6)
	v_mov_b64_e32 v[84:85], v[178:179]
	v_mov_b64_e32 v[86:87], v[180:181]
	v_add_f32_e32 v78, v78, v86
	v_mul_f32_e32 v78, 0xbfb8aa3b, v78
	v_exp_f32_e32 v78, v78
	v_add_f32_e32 v77, v77, v85
	v_add_f32_e32 v76, v76, v84
	v_mul_f32_e32 v77, 0xbfb8aa3b, v77
	v_add_f32_e32 v78, 1.0, v78
	v_rcp_f32_e32 v78, v78
	v_mul_f32_e32 v76, 0xbfb8aa3b, v76
	v_exp_f32_e32 v77, v77
	v_exp_f32_e32 v76, v76
	v_mul_f32_e32 v85, v78, v92
	v_add_f32_e32 v78, v79, v87
	v_mul_f32_e32 v78, 0xbfb8aa3b, v78
	v_exp_f32_e32 v78, v78
	v_add_f32_e32 v77, 1.0, v77
	v_add_f32_e32 v76, 1.0, v76
	v_rcp_f32_e32 v77, v77
	v_rcp_f32_e32 v76, v76
	v_add_f32_e32 v78, 1.0, v78
	v_rcp_f32_e32 v78, v78
	v_mul_f32_e32 v77, v77, v91
	v_mul_f32_e32 v76, v76, v90
	v_mul_f32_e32 v84, v77, v77
	v_fmac_f32_e32 v84, v76, v76
	v_mul_f32_e32 v79, v78, v93
	v_cvt_pk_bf16_f32 v78, v76, v77
	v_lshl_add_u64 v[76:77], s[58:59], 0, v[88:89]
	v_fmac_f32_e32 v84, v85, v85
	v_lshl_add_u64 v[86:87], v[76:77], 0, v[142:143]
	v_fmac_f32_e32 v84, v79, v79
	v_cvt_pk_bf16_f32 v79, v85, v79
	global_store_dwordx2 v[86:87], v[78:79], off
	s_waitcnt vmcnt(6)
; __device__ __forceinline__ u32x2 pack4(f32x4 v) { u32x2 r; r.x = cvt_pk(v[0], v[1]); r.y = cvt_pk(v[2], v[3]); return r; }
; __device__ __forceinline__ float sigmoidf_(float x) { return __builtin_amdgcn_rcpf(1.0f + __builtin_amdgcn_exp2f(-1.4426950408889634f * x)); }
; #define FOR_AI_M _Pragma("unroll") for (int ai = 0; ai < 2; ++ai) _Pragma("unroll") for (int m = 0; m < 4; ++m)
; #define FOR_BJ_N _Pragma("unroll") for (int bj = 0; bj < 2; ++bj) _Pragma("unroll") for (int n = 0; n < 2; ++n)
;     __device__ __forceinline__ void operator()(EPI_ARGS) const {
;         FOR_AI_M {
;             const int row = u.pm * 256 + ai * 128 + wr * 64 + m * 16 + fr; float ss = 0.f;
;             FOR_BJ_N { const int col = u.pn * 256 + bj * 128 + wc * 32 + n * 16 + 4 * fq;
;                 const f32x4 gg = unpack4(*(const u32x2*)(G + ((size_t)row * 1024 + col))); const f32x4 bb = *(const f32x4*)(bglu + col); f32x4 o;
; #pragma unroll
;                 for (int e = 0; e < 4; ++e) { o[e] = gg[e] * sigmoidf_(acc[ai][bj][m][n][e] + bb[e]); ss += o[e] * o[e]; }
;                 *(u32x2*)(Y + ((size_t)row * 2048 + col)) = pack4(o); }
;             ss += __shfl_xor(ss, 16); ss += __shfl_xor(ss, 32);
;             if (fq == 0) atomicAdd(ssq_a + row, ss);
;         }
;     }
	v_mov_b64_e32 v[86:87], v[182:183]
	v_mov_b64_e32 v[88:89], v[184:185]
	v_lshl_add_u64 v[78:79], v[82:83], 0, v[124:125]
	s_waitcnt vmcnt(5)
	v_mov_b64_e32 v[78:79], v[186:187]
	v_add_f32_e32 v72, v72, v86
	v_mul_f32_e32 v72, 0xbfb8aa3b, v72
	v_add_f32_e32 v73, v73, v87
	v_exp_f32_e32 v72, v72
	v_mul_f32_e32 v73, 0xbfb8aa3b, v73
	v_add_f32_e32 v74, v74, v88
	v_exp_f32_e32 v73, v73
	v_mul_f32_e32 v74, 0xbfb8aa3b, v74
	v_add_f32_e32 v75, v75, v89
	v_exp_f32_e32 v74, v74
	v_mul_f32_e32 v75, 0xbfb8aa3b, v75
	v_exp_f32_e32 v75, v75
	v_add_f32_e32 v72, 1.0, v72
	v_rcp_f32_e32 v72, v72
	v_add_f32_e32 v73, 1.0, v73
	v_rcp_f32_e32 v73, v73
	v_add_f32_e32 v74, 1.0, v74
	v_rcp_f32_e32 v74, v74
	v_add_f32_e32 v75, 1.0, v75
	v_lshlrev_b32_e32 v85, 16, v78
	v_rcp_f32_e32 v75, v75
	v_and_b32_e32 v78, 0xffff0000, v78
	v_mul_f32_e32 v72, v72, v85
	v_lshlrev_b32_e32 v90, 16, v79
	v_fmac_f32_e32 v84, v72, v72
	v_mul_f32_e32 v73, v73, v78
	v_and_b32_e32 v79, 0xffff0000, v79
	v_fmac_f32_e32 v84, v73, v73
	v_mul_f32_e32 v74, v74, v90
	v_fmac_f32_e32 v84, v74, v74
	v_mul_f32_e32 v75, v75, v79
	v_fmac_f32_e32 v84, v75, v75
	v_cvt_pk_bf16_f32 v72, v72, v73
	v_cvt_pk_bf16_f32 v73, v74, v75
	v_lshl_add_u64 v[74:75], v[76:77], 0, v[124:125]
	global_store_dwordx2 v[74:75], v[72:73], off
	v_lshl_add_u64 v[72:73], v[82:83], 0, v[120:121]
	s_waitcnt vmcnt(5)
	v_mov_b64_e32 v[72:73], v[188:189]
	v_lshlrev_b32_e32 v78, 16, v72
	v_and_b32_e32 v79, 0xffff0000, v72
	v_lshlrev_b32_e32 v85, 16, v73
	v_and_b32_e32 v86, 0xffff0000, v73
	s_waitcnt vmcnt(4)
	v_mov_b64_e32 v[72:73], v[190:191]
	v_mov_b64_e32 v[74:75], v[192:193]
	v_add_f32_e32 v68, v68, v72
	v_mul_f32_e32 v68, 0xbfb8aa3b, v68
	v_add_f32_e32 v69, v69, v73
	v_exp_f32_e32 v68, v68
	v_mul_f32_e32 v69, 0xbfb8aa3b, v69
	v_add_f32_e32 v70, v70, v74
	v_exp_f32_e32 v69, v69
	v_mul_f32_e32 v70, 0xbfb8aa3b, v70
	v_add_f32_e32 v71, v71, v75
	v_exp_f32_e32 v70, v70
	v_mul_f32_e32 v71, 0xbfb8aa3b, v71
	v_exp_f32_e32 v71, v71
	v_add_f32_e32 v68, 1.0, v68
	v_rcp_f32_e32 v68, v68
	v_add_f32_e32 v69, 1.0, v69
	v_rcp_f32_e32 v69, v69
	v_add_f32_e32 v70, 1.0, v70
	v_rcp_f32_e32 v70, v70
	v_add_f32_e32 v71, 1.0, v71
	v_rcp_f32_e32 v71, v71
	v_mul_f32_e32 v68, v68, v78
	v_fmac_f32_e32 v84, v68, v68
	v_mul_f32_e32 v69, v69, v79
	v_fmac_f32_e32 v84, v69, v69
	v_mul_f32_e32 v70, v70, v85
	v_fmac_f32_e32 v84, v70, v70
	v_mul_f32_e32 v71, v71, v86
	v_fmac_f32_e32 v84, v71, v71
	v_cvt_pk_bf16_f32 v68, v68, v69
	v_cvt_pk_bf16_f32 v69, v70, v71
	v_lshl_add_u64 v[70:71], v[76:77], 0, v[120:121]
	global_store_dwordx2 v[70:71], v[68:69], off
	v_lshl_add_u64 v[68:69], v[82:83], 0, v[116:117]
	s_waitcnt vmcnt(4)
	v_mov_b64_e32 v[68:69], v[194:195]
	v_lshlrev_b32_e32 v72, 16, v68
	v_and_b32_e32 v73, 0xffff0000, v68
	v_lshlrev_b32_e32 v74, 16, v69
	v_and_b32_e32 v75, 0xffff0000, v69
	s_waitcnt vmcnt(3)
	v_mov_b64_e32 v[68:69], v[196:197]
	v_mov_b64_e32 v[70:71], v[198:199]
	v_add_f32_e32 v64, v64, v68
	v_mul_f32_e32 v64, 0xbfb8aa3b, v64
	v_add_f32_e32 v65, v65, v69
	v_exp_f32_e32 v64, v64
	v_mul_f32_e32 v65, 0xbfb8aa3b, v65
	v_add_f32_e32 v66, v66, v70
	v_exp_f32_e32 v65, v65
	v_mul_f32_e32 v66, 0xbfb8aa3b, v66
	v_add_f32_e32 v67, v67, v71
	v_exp_f32_e32 v66, v66
	v_mul_f32_e32 v67, 0xbfb8aa3b, v67
	v_exp_f32_e32 v67, v67
	v_add_f32_e32 v64, 1.0, v64
	v_rcp_f32_e32 v64, v64
	v_add_f32_e32 v65, 1.0, v65
	v_rcp_f32_e32 v65, v65
	v_add_f32_e32 v66, 1.0, v66
	v_rcp_f32_e32 v66, v66
	v_add_f32_e32 v67, 1.0, v67
	v_rcp_f32_e32 v67, v67
	v_mul_f32_e32 v64, v64, v72
	v_fmac_f32_e32 v84, v64, v64
	v_mul_f32_e32 v65, v65, v73
	v_fmac_f32_e32 v84, v65, v65
	v_mul_f32_e32 v66, v66, v74
	v_fmac_f32_e32 v84, v66, v66
	v_mul_f32_e32 v67, v67, v75
	v_fmac_f32_e32 v84, v67, v67
	v_cvt_pk_bf16_f32 v64, v64, v65
	v_cvt_pk_bf16_f32 v65, v66, v67
	v_lshl_add_u64 v[66:67], v[76:77], 0, v[116:117]
	global_store_dwordx2 v[66:67], v[64:65], off
	ds_bpermute_b32 v64, v118, v84
	s_waitcnt lgkmcnt(0)
	v_add_f32_e32 v64, v84, v64
	ds_bpermute_b32 v65, v119, v64
	s_and_saveexec_b64 s[6:7], vcc
	s_cbranch_execz .LBB0_887
	v_lshl_add_u64 v[66:67], v[80:81], 2, s[4:5]
	s_waitcnt lgkmcnt(0)
	v_add_f32_e32 v64, v64, v65
	global_atomic_add_f32 v[66:67], v64, off
.LBB0_887:
	s_or_b64 exec, exec, s[6:7]
	v_add_u32_e32 v178, 0x80, v146
	v_ashrrev_i32_e32 v179, 31, v178
	v_lshlrev_b64 v[180:181], 11, v[178:179]
	v_lshl_add_u64 v[182:183], s[60:61], 0, v[180:181]
	v_lshl_add_u64 v[184:185], v[182:183], 0, v[142:143]
	global_load_dwordx2 v[176:177], v[184:185], off
	global_load_dwordx4 v[178:181], v[140:141], off
	global_load_dwordx4 v[182:185], v[140:141], off offset:64
	v_add_u32_e32 v188, 0x80, v146
	v_ashrrev_i32_e32 v189, 31, v188
	v_lshlrev_b64 v[190:191], 11, v[188:189]
	v_lshl_add_u64 v[192:193], s[60:61], 0, v[190:191]
	v_lshl_add_u64 v[194:195], v[192:193], 0, v[124:125]
	global_load_dwordx2 v[186:187], v[194:195], off
	v_add_u32_e32 v190, 0x80, v146
	v_ashrrev_i32_e32 v191, 31, v190
	v_lshlrev_b64 v[192:193], 11, v[190:191]
	v_lshl_add_u64 v[194:195], s[60:61], 0, v[192:193]
	v_lshl_add_u64 v[196:197], v[194:195], 0, v[120:121]
	global_load_dwordx2 v[188:189], v[196:197], off
	global_load_dwordx4 v[190:193], v[140:141], off offset:512
	v_add_u32_e32 v196, 0x80, v146
	v_ashrrev_i32_e32 v197, 31, v196
	v_lshlrev_b64 v[198:199], 11, v[196:197]
	v_lshl_add_u64 v[200:201], s[60:61], 0, v[198:199]
	v_lshl_add_u64 v[202:203], v[200:201], 0, v[116:117]
	global_load_dwordx2 v[194:195], v[202:203], off
	global_load_dwordx4 v[196:199], v[140:141], off offset:576
	v_add_u32_e32 v64, 0x80, v146
	s_waitcnt lgkmcnt(0)
; __device__ __forceinline__ u32x2 pack4(f32x4 v) { u32x2 r; r.x = cvt_pk(v[0], v[1]); r.y = cvt_pk(v[2], v[3]); return r; }
; __device__ __forceinline__ float sigmoidf_(float x) { return __builtin_amdgcn_rcpf(1.0f + __builtin_amdgcn_exp2f(-1.4426950408889634f * x)); }
; #define FOR_AI_M _Pragma("unroll") for (int ai = 0; ai < 2; ++ai) _Pragma("unroll") for (int m = 0; m < 4; ++m)
; #define FOR_BJ_N _Pragma("unroll") for (int bj = 0; bj < 2; ++bj) _Pragma("unroll") for (int n = 0; n < 2; ++n)
;     __device__ __forceinline__ void operator()(EPI_ARGS) const {
;         FOR_AI_M {
;             const int row = u.pm * 256 + ai * 128 + wr * 64 + m * 16 + fr; float ss = 0.f;
;             FOR_BJ_N { const int col = u.pn * 256 + bj * 128 + wc * 32 + n * 16 + 4 * fq;
;                 const f32x4 gg = unpack4(*(const u32x2*)(G + ((size_t)row * 1024 + col))); const f32x4 bb = *(const f32x4*)(bglu + col); f32x4 o;
; #pragma unroll
;                 for (int e = 0; e < 4; ++e) { o[e] = gg[e] * sigmoidf_(acc[ai][bj][m][n][e] + bb[e]); ss += o[e] * o[e]; }
;                 *(u32x2*)(Y + ((size_t)row * 2048 + col)) = pack4(o); }
;             ss += __shfl_xor(ss, 16); ss += __shfl_xor(ss, 32);
;             if (fq == 0) atomicAdd(ssq_a + row, ss);
;         }
;     }
	v_ashrrev_i32_e32 v65, 31, v64
	v_lshlrev_b64 v[66:67], 11, v[64:65]
	v_lshl_add_u64 v[66:67], s[60:61], 0, v[66:67]
	v_lshl_add_u64 v[68:69], v[66:67], 0, v[142:143]
	s_waitcnt vmcnt(7)
	v_mov_b64_e32 v[68:69], v[176:177]
	v_lshlrev_b64 v[72:73], 12, v[64:65]
	v_lshlrev_b32_e32 v74, 16, v68
	v_and_b32_e32 v75, 0xffff0000, v68
	v_lshlrev_b32_e32 v76, 16, v69
	v_and_b32_e32 v77, 0xffff0000, v69
	s_waitcnt vmcnt(6)
	v_mov_b64_e32 v[68:69], v[178:179]
	v_mov_b64_e32 v[70:71], v[180:181]
	v_add_f32_e32 v62, v62, v70
	v_mul_f32_e32 v62, 0xbfb8aa3b, v62
	v_exp_f32_e32 v62, v62
	v_add_f32_e32 v61, v61, v69
	v_add_f32_e32 v60, v60, v68
	v_mul_f32_e32 v61, 0xbfb8aa3b, v61
	v_add_f32_e32 v62, 1.0, v62
	v_rcp_f32_e32 v62, v62
	v_mul_f32_e32 v60, 0xbfb8aa3b, v60
	v_exp_f32_e32 v61, v61
	v_exp_f32_e32 v60, v60
	v_mul_f32_e32 v69, v62, v76
	v_add_f32_e32 v62, v63, v71
	v_mul_f32_e32 v62, 0xbfb8aa3b, v62
	v_exp_f32_e32 v62, v62
	v_add_f32_e32 v61, 1.0, v61
	v_add_f32_e32 v60, 1.0, v60
	v_rcp_f32_e32 v61, v61
	v_rcp_f32_e32 v60, v60
	v_add_f32_e32 v62, 1.0, v62
	v_rcp_f32_e32 v62, v62
	v_mul_f32_e32 v61, v61, v75
	v_mul_f32_e32 v60, v60, v74
	v_mul_f32_e32 v68, v61, v61
	v_fmac_f32_e32 v68, v60, v60
	v_mul_f32_e32 v63, v62, v77
	v_cvt_pk_bf16_f32 v62, v60, v61
	v_lshl_add_u64 v[60:61], s[58:59], 0, v[72:73]
	v_fmac_f32_e32 v68, v69, v69
	v_lshl_add_u64 v[70:71], v[60:61], 0, v[142:143]
	v_fmac_f32_e32 v68, v63, v63
	v_cvt_pk_bf16_f32 v63, v69, v63
	global_store_dwordx2 v[70:71], v[62:63], off
	s_waitcnt vmcnt(6)
	v_mov_b64_e32 v[70:71], v[182:183]
	v_mov_b64_e32 v[72:73], v[184:185]
	v_lshl_add_u64 v[62:63], v[66:67], 0, v[124:125]
	s_waitcnt vmcnt(5)
	v_mov_b64_e32 v[62:63], v[186:187]
	v_add_f32_e32 v56, v56, v70
	v_mul_f32_e32 v56, 0xbfb8aa3b, v56
	v_add_f32_e32 v57, v57, v71
	v_exp_f32_e32 v56, v56
	v_mul_f32_e32 v57, 0xbfb8aa3b, v57
	v_add_f32_e32 v58, v58, v72
	v_exp_f32_e32 v57, v57
	v_mul_f32_e32 v58, 0xbfb8aa3b, v58
	v_add_f32_e32 v59, v59, v73
	v_exp_f32_e32 v58, v58
	v_mul_f32_e32 v59, 0xbfb8aa3b, v59
	v_exp_f32_e32 v59, v59
	v_add_f32_e32 v56, 1.0, v56
	v_rcp_f32_e32 v56, v56
	v_add_f32_e32 v57, 1.0, v57
	v_rcp_f32_e32 v57, v57
	v_add_f32_e32 v58, 1.0, v58
	v_rcp_f32_e32 v58, v58
	v_add_f32_e32 v59, 1.0, v59
	v_lshlrev_b32_e32 v69, 16, v62
	v_rcp_f32_e32 v59, v59
	v_and_b32_e32 v62, 0xffff0000, v62
	v_mul_f32_e32 v56, v56, v69
	v_lshlrev_b32_e32 v74, 16, v63
	v_fmac_f32_e32 v68, v56, v56
	v_mul_f32_e32 v57, v57, v62
	v_and_b32_e32 v63, 0xffff0000, v63
	v_fmac_f32_e32 v68, v57, v57
	v_mul_f32_e32 v58, v58, v74
	v_fmac_f32_e32 v68, v58, v58
	v_mul_f32_e32 v59, v59, v63
	v_fmac_f32_e32 v68, v59, v59
	v_cvt_pk_bf16_f32 v56, v56, v57
	v_cvt_pk_bf16_f32 v57, v58, v59
	v_lshl_add_u64 v[58:59], v[60:61], 0, v[124:125]
	global_store_dwordx2 v[58:59], v[56:57], off
	v_lshl_add_u64 v[56:57], v[66:67], 0, v[120:121]
	s_waitcnt vmcnt(5)
	v_mov_b64_e32 v[56:57], v[188:189]
	v_lshlrev_b32_e32 v62, 16, v56
	v_and_b32_e32 v63, 0xffff0000, v56
	v_lshlrev_b32_e32 v69, 16, v57
	v_and_b32_e32 v70, 0xffff0000, v57
	s_waitcnt vmcnt(4)
	v_mov_b64_e32 v[56:57], v[190:191]
	v_mov_b64_e32 v[58:59], v[192:193]
	v_add_f32_e32 v52, v52, v56
	v_mul_f32_e32 v52, 0xbfb8aa3b, v52
	v_add_f32_e32 v53, v53, v57
	v_exp_f32_e32 v52, v52
	v_mul_f32_e32 v53, 0xbfb8aa3b, v53
	v_add_f32_e32 v54, v54, v58
	v_exp_f32_e32 v53, v53
	v_mul_f32_e32 v54, 0xbfb8aa3b, v54
	v_add_f32_e32 v55, v55, v59
	v_exp_f32_e32 v54, v54
	v_mul_f32_e32 v55, 0xbfb8aa3b, v55
	v_exp_f32_e32 v55, v55
	v_add_f32_e32 v52, 1.0, v52
	v_rcp_f32_e32 v52, v52
	v_add_f32_e32 v53, 1.0, v53
	v_rcp_f32_e32 v53, v53
	v_add_f32_e32 v54, 1.0, v54
	v_rcp_f32_e32 v54, v54
	v_add_f32_e32 v55, 1.0, v55
	v_rcp_f32_e32 v55, v55
	v_mul_f32_e32 v52, v52, v62
	v_fmac_f32_e32 v68, v52, v52
	v_mul_f32_e32 v53, v53, v63
	v_fmac_f32_e32 v68, v53, v53
	v_mul_f32_e32 v54, v54, v69
	v_fmac_f32_e32 v68, v54, v54
	v_mul_f32_e32 v55, v55, v70
	v_fmac_f32_e32 v68, v55, v55
	v_cvt_pk_bf16_f32 v52, v52, v53
	v_cvt_pk_bf16_f32 v53, v54, v55
	v_lshl_add_u64 v[54:55], v[60:61], 0, v[120:121]
	global_store_dwordx2 v[54:55], v[52:53], off
	v_lshl_add_u64 v[52:53], v[66:67], 0, v[116:117]
	s_waitcnt vmcnt(4)
	v_mov_b64_e32 v[52:53], v[194:195]
	v_lshlrev_b32_e32 v56, 16, v52
	v_and_b32_e32 v57, 0xffff0000, v52
	v_lshlrev_b32_e32 v58, 16, v53
	v_and_b32_e32 v59, 0xffff0000, v53
	s_waitcnt vmcnt(3)
	v_mov_b64_e32 v[52:53], v[196:197]
	v_mov_b64_e32 v[54:55], v[198:199]
	v_add_f32_e32 v48, v48, v52
	v_mul_f32_e32 v48, 0xbfb8aa3b, v48
	v_add_f32_e32 v49, v49, v53
	v_exp_f32_e32 v48, v48
	v_mul_f32_e32 v49, 0xbfb8aa3b, v49
	v_add_f32_e32 v50, v50, v54
	v_exp_f32_e32 v49, v49
	v_mul_f32_e32 v50, 0xbfb8aa3b, v50
	v_add_f32_e32 v51, v51, v55
	v_exp_f32_e32 v50, v50
	v_mul_f32_e32 v51, 0xbfb8aa3b, v51
	v_exp_f32_e32 v51, v51
	v_add_f32_e32 v48, 1.0, v48
	v_rcp_f32_e32 v48, v48
	v_add_f32_e32 v49, 1.0, v49
	v_rcp_f32_e32 v49, v49
	v_add_f32_e32 v50, 1.0, v50
	v_rcp_f32_e32 v50, v50
	v_add_f32_e32 v51, 1.0, v51
	v_rcp_f32_e32 v51, v51
	v_mul_f32_e32 v48, v48, v56
	v_fmac_f32_e32 v68, v48, v48
	v_mul_f32_e32 v49, v49, v57
	v_fmac_f32_e32 v68, v49, v49
	v_mul_f32_e32 v50, v50, v58
	v_fmac_f32_e32 v68, v50, v50
	v_mul_f32_e32 v51, v51, v59
	v_fmac_f32_e32 v68, v51, v51
	v_cvt_pk_bf16_f32 v48, v48, v49
	v_cvt_pk_bf16_f32 v49, v50, v51
	v_lshl_add_u64 v[50:51], v[60:61], 0, v[116:117]
	global_store_dwordx2 v[50:51], v[48:49], off
	ds_bpermute_b32 v48, v118, v68
	s_waitcnt lgkmcnt(0)
	v_add_f32_e32 v48, v68, v48
	ds_bpermute_b32 v49, v119, v48
	s_and_saveexec_b64 s[6:7], vcc
	s_cbranch_execz .LBB0_889
	v_lshl_add_u64 v[50:51], v[64:65], 2, s[4:5]
	s_waitcnt lgkmcnt(0)
	v_add_f32_e32 v48, v48, v49
	global_atomic_add_f32 v[50:51], v48, off
; __device__ __forceinline__ u32x2 pack4(f32x4 v) { u32x2 r; r.x = cvt_pk(v[0], v[1]); r.y = cvt_pk(v[2], v[3]); return r; }
; __device__ __forceinline__ float sigmoidf_(float x) { return __builtin_amdgcn_rcpf(1.0f + __builtin_amdgcn_exp2f(-1.4426950408889634f * x)); }
; #define FOR_AI_M _Pragma("unroll") for (int ai = 0; ai < 2; ++ai) _Pragma("unroll") for (int m = 0; m < 4; ++m)
; #define FOR_BJ_N _Pragma("unroll") for (int bj = 0; bj < 2; ++bj) _Pragma("unroll") for (int n = 0; n < 2; ++n)
;     __device__ __forceinline__ void operator()(EPI_ARGS) const {
;         FOR_AI_M {
;             const int row = u.pm * 256 + ai * 128 + wr * 64 + m * 16 + fr; float ss = 0.f;
;             FOR_BJ_N { const int col = u.pn * 256 + bj * 128 + wc * 32 + n * 16 + 4 * fq;
;                 const f32x4 gg = unpack4(*(const u32x2*)(G + ((size_t)row * 1024 + col))); const f32x4 bb = *(const f32x4*)(bglu + col); f32x4 o;
; #pragma unroll
;                 for (int e = 0; e < 4; ++e) { o[e] = gg[e] * sigmoidf_(acc[ai][bj][m][n][e] + bb[e]); ss += o[e] * o[e]; }
;                 *(u32x2*)(Y + ((size_t)row * 2048 + col)) = pack4(o); }
;             ss += __shfl_xor(ss, 16); ss += __shfl_xor(ss, 32);
;             if (fq == 0) atomicAdd(ssq_a + row, ss);
;         }
;     }
.LBB0_889:
	s_or_b64 exec, exec, s[6:7]
	v_add_u32_e32 v178, 0x90, v146
	v_ashrrev_i32_e32 v179, 31, v178
	v_lshlrev_b64 v[180:181], 11, v[178:179]
	v_lshl_add_u64 v[182:183], s[60:61], 0, v[180:181]
	v_lshl_add_u64 v[184:185], v[182:183], 0, v[142:143]
	global_load_dwordx2 v[176:177], v[184:185], off
	global_load_dwordx4 v[178:181], v[140:141], off
	global_load_dwordx4 v[182:185], v[140:141], off offset:64
	v_add_u32_e32 v188, 0x90, v146
	v_ashrrev_i32_e32 v189, 31, v188
	v_lshlrev_b64 v[190:191], 11, v[188:189]
	v_lshl_add_u64 v[192:193], s[60:61], 0, v[190:191]
	v_lshl_add_u64 v[194:195], v[192:193], 0, v[124:125]
	global_load_dwordx2 v[186:187], v[194:195], off
	v_add_u32_e32 v190, 0x90, v146
	v_ashrrev_i32_e32 v191, 31, v190
	v_lshlrev_b64 v[192:193], 11, v[190:191]
	v_lshl_add_u64 v[194:195], s[60:61], 0, v[192:193]
	v_lshl_add_u64 v[196:197], v[194:195], 0, v[120:121]
	global_load_dwordx2 v[188:189], v[196:197], off
	global_load_dwordx4 v[190:193], v[140:141], off offset:512
	v_add_u32_e32 v196, 0x90, v146
	v_ashrrev_i32_e32 v197, 31, v196
	v_lshlrev_b64 v[198:199], 11, v[196:197]
	v_lshl_add_u64 v[200:201], s[60:61], 0, v[198:199]
	v_lshl_add_u64 v[202:203], v[200:201], 0, v[116:117]
	global_load_dwordx2 v[194:195], v[202:203], off
	global_load_dwordx4 v[196:199], v[140:141], off offset:576
	v_add_u32_e32 v48, 0x90, v146
	s_waitcnt lgkmcnt(0)
	v_ashrrev_i32_e32 v49, 31, v48
	v_lshlrev_b64 v[50:51], 11, v[48:49]
	v_lshl_add_u64 v[50:51], s[60:61], 0, v[50:51]
	v_lshl_add_u64 v[52:53], v[50:51], 0, v[142:143]
	s_waitcnt vmcnt(7)
	v_mov_b64_e32 v[52:53], v[176:177]
	v_lshlrev_b64 v[56:57], 12, v[48:49]
	v_lshlrev_b32_e32 v58, 16, v52
	v_and_b32_e32 v59, 0xffff0000, v52
	v_lshlrev_b32_e32 v60, 16, v53
	v_and_b32_e32 v61, 0xffff0000, v53
	s_waitcnt vmcnt(6)
	v_mov_b64_e32 v[52:53], v[178:179]
	v_mov_b64_e32 v[54:55], v[180:181]
	v_add_f32_e32 v46, v46, v54
	v_mul_f32_e32 v46, 0xbfb8aa3b, v46
	v_exp_f32_e32 v46, v46
	v_add_f32_e32 v45, v45, v53
	v_add_f32_e32 v44, v44, v52
	v_mul_f32_e32 v45, 0xbfb8aa3b, v45
	v_add_f32_e32 v46, 1.0, v46
	v_rcp_f32_e32 v46, v46
	v_mul_f32_e32 v44, 0xbfb8aa3b, v44
	v_exp_f32_e32 v45, v45
	v_exp_f32_e32 v44, v44
	v_mul_f32_e32 v53, v46, v60
	v_add_f32_e32 v46, v47, v55
	v_mul_f32_e32 v46, 0xbfb8aa3b, v46
	v_exp_f32_e32 v46, v46
	v_add_f32_e32 v45, 1.0, v45
	v_add_f32_e32 v44, 1.0, v44
	v_rcp_f32_e32 v45, v45
	v_rcp_f32_e32 v44, v44
	v_add_f32_e32 v46, 1.0, v46
	v_rcp_f32_e32 v46, v46
	v_mul_f32_e32 v45, v45, v59
	v_mul_f32_e32 v44, v44, v58
	v_mul_f32_e32 v52, v45, v45
	v_fmac_f32_e32 v52, v44, v44
	v_mul_f32_e32 v47, v46, v61
	v_cvt_pk_bf16_f32 v46, v44, v45
	v_lshl_add_u64 v[44:45], s[58:59], 0, v[56:57]
	v_fmac_f32_e32 v52, v53, v53
	v_lshl_add_u64 v[54:55], v[44:45], 0, v[142:143]
	v_fmac_f32_e32 v52, v47, v47
	v_cvt_pk_bf16_f32 v47, v53, v47
	global_store_dwordx2 v[54:55], v[46:47], off
	s_waitcnt vmcnt(6)
	v_mov_b64_e32 v[54:55], v[182:183]
	v_mov_b64_e32 v[56:57], v[184:185]
	v_lshl_add_u64 v[46:47], v[50:51], 0, v[124:125]
	s_waitcnt vmcnt(5)
	v_mov_b64_e32 v[46:47], v[186:187]
	v_add_f32_e32 v40, v40, v54
	v_mul_f32_e32 v40, 0xbfb8aa3b, v40
	v_add_f32_e32 v41, v41, v55
	v_exp_f32_e32 v40, v40
	v_mul_f32_e32 v41, 0xbfb8aa3b, v41
	v_add_f32_e32 v42, v42, v56
	v_exp_f32_e32 v41, v41
	v_mul_f32_e32 v42, 0xbfb8aa3b, v42
	v_add_f32_e32 v43, v43, v57
	v_exp_f32_e32 v42, v42
	v_mul_f32_e32 v43, 0xbfb8aa3b, v43
	v_exp_f32_e32 v43, v43
	v_add_f32_e32 v40, 1.0, v40
	v_rcp_f32_e32 v40, v40
	v_add_f32_e32 v41, 1.0, v41
	v_rcp_f32_e32 v41, v41
	v_add_f32_e32 v42, 1.0, v42
	v_rcp_f32_e32 v42, v42
	v_add_f32_e32 v43, 1.0, v43
	v_lshlrev_b32_e32 v53, 16, v46
	v_rcp_f32_e32 v43, v43
	v_and_b32_e32 v46, 0xffff0000, v46
	v_mul_f32_e32 v40, v40, v53
	v_lshlrev_b32_e32 v58, 16, v47
	v_fmac_f32_e32 v52, v40, v40
	v_mul_f32_e32 v41, v41, v46
	v_and_b32_e32 v47, 0xffff0000, v47
	v_fmac_f32_e32 v52, v41, v41
	v_mul_f32_e32 v42, v42, v58
	v_fmac_f32_e32 v52, v42, v42
	v_mul_f32_e32 v43, v43, v47
	v_fmac_f32_e32 v52, v43, v43
	v_cvt_pk_bf16_f32 v40, v40, v41
	v_cvt_pk_bf16_f32 v41, v42, v43
	v_lshl_add_u64 v[42:43], v[44:45], 0, v[124:125]
	global_store_dwordx2 v[42:43], v[40:41], off
	v_lshl_add_u64 v[40:41], v[50:51], 0, v[120:121]
	s_waitcnt vmcnt(5)
	v_mov_b64_e32 v[40:41], v[188:189]
	v_lshlrev_b32_e32 v46, 16, v40
	v_and_b32_e32 v47, 0xffff0000, v40
	v_lshlrev_b32_e32 v53, 16, v41
	v_and_b32_e32 v54, 0xffff0000, v41
	s_waitcnt vmcnt(4)
	v_mov_b64_e32 v[40:41], v[190:191]
	v_mov_b64_e32 v[42:43], v[192:193]
	v_add_f32_e32 v36, v36, v40
	v_mul_f32_e32 v36, 0xbfb8aa3b, v36
	v_add_f32_e32 v37, v37, v41
	v_exp_f32_e32 v36, v36
	v_mul_f32_e32 v37, 0xbfb8aa3b, v37
	v_add_f32_e32 v38, v38, v42
	v_exp_f32_e32 v37, v37
	v_mul_f32_e32 v38, 0xbfb8aa3b, v38
	v_add_f32_e32 v39, v39, v43
	v_exp_f32_e32 v38, v38
	v_mul_f32_e32 v39, 0xbfb8aa3b, v39
	v_exp_f32_e32 v39, v39
	v_add_f32_e32 v36, 1.0, v36
	v_rcp_f32_e32 v36, v36
	v_add_f32_e32 v37, 1.0, v37
	v_rcp_f32_e32 v37, v37
	v_add_f32_e32 v38, 1.0, v38
	v_rcp_f32_e32 v38, v38
	v_add_f32_e32 v39, 1.0, v39
	v_rcp_f32_e32 v39, v39
	v_mul_f32_e32 v36, v36, v46
	v_fmac_f32_e32 v52, v36, v36
	v_mul_f32_e32 v37, v37, v47
	v_fmac_f32_e32 v52, v37, v37
	v_mul_f32_e32 v38, v38, v53
	v_fmac_f32_e32 v52, v38, v38
	v_mul_f32_e32 v39, v39, v54
	v_fmac_f32_e32 v52, v39, v39
	v_cvt_pk_bf16_f32 v36, v36, v37
	v_cvt_pk_bf16_f32 v37, v38, v39
	v_lshl_add_u64 v[38:39], v[44:45], 0, v[120:121]
	global_store_dwordx2 v[38:39], v[36:37], off
	v_lshl_add_u64 v[36:37], v[50:51], 0, v[116:117]
	s_waitcnt vmcnt(4)
	v_mov_b64_e32 v[36:37], v[194:195]
	v_lshlrev_b32_e32 v40, 16, v36
	v_and_b32_e32 v41, 0xffff0000, v36
	v_lshlrev_b32_e32 v42, 16, v37
	v_and_b32_e32 v43, 0xffff0000, v37
	s_waitcnt vmcnt(3)
	v_mov_b64_e32 v[36:37], v[196:197]
	v_mov_b64_e32 v[38:39], v[198:199]
	v_add_f32_e32 v32, v32, v36
	v_mul_f32_e32 v32, 0xbfb8aa3b, v32
	v_add_f32_e32 v33, v33, v37
	v_exp_f32_e32 v32, v32
	v_mul_f32_e32 v33, 0xbfb8aa3b, v33
	v_add_f32_e32 v34, v34, v38
	v_exp_f32_e32 v33, v33
	v_mul_f32_e32 v34, 0xbfb8aa3b, v34
	v_add_f32_e32 v35, v35, v39
	v_exp_f32_e32 v34, v34
	v_mul_f32_e32 v35, 0xbfb8aa3b, v35
	v_exp_f32_e32 v35, v35
	v_add_f32_e32 v32, 1.0, v32
	v_rcp_f32_e32 v32, v32
	v_add_f32_e32 v33, 1.0, v33
	v_rcp_f32_e32 v33, v33
	v_add_f32_e32 v34, 1.0, v34
	v_rcp_f32_e32 v34, v34
	v_add_f32_e32 v35, 1.0, v35
	v_rcp_f32_e32 v35, v35
	v_mul_f32_e32 v32, v32, v40
	v_fmac_f32_e32 v52, v32, v32
	v_mul_f32_e32 v33, v33, v41
	v_fmac_f32_e32 v52, v33, v33
	v_mul_f32_e32 v34, v34, v42
	v_fmac_f32_e32 v52, v34, v34
	v_mul_f32_e32 v35, v35, v43
	v_fmac_f32_e32 v52, v35, v35
	v_cvt_pk_bf16_f32 v32, v32, v33
	v_cvt_pk_bf16_f32 v33, v34, v35
	v_lshl_add_u64 v[34:35], v[44:45], 0, v[116:117]
	global_store_dwordx2 v[34:35], v[32:33], off
	ds_bpermute_b32 v32, v118, v52
	s_waitcnt lgkmcnt(0)
	v_add_f32_e32 v32, v52, v32
	ds_bpermute_b32 v33, v119, v32
	s_and_saveexec_b64 s[6:7], vcc
	s_cbranch_execz .LBB0_891
; __device__ __forceinline__ u32x2 pack4(f32x4 v) { u32x2 r; r.x = cvt_pk(v[0], v[1]); r.y = cvt_pk(v[2], v[3]); return r; }
; __device__ __forceinline__ float sigmoidf_(float x) { return __builtin_amdgcn_rcpf(1.0f + __builtin_amdgcn_exp2f(-1.4426950408889634f * x)); }
; #define FOR_AI_M _Pragma("unroll") for (int ai = 0; ai < 2; ++ai) _Pragma("unroll") for (int m = 0; m < 4; ++m)
; #define FOR_BJ_N _Pragma("unroll") for (int bj = 0; bj < 2; ++bj) _Pragma("unroll") for (int n = 0; n < 2; ++n)
;     __device__ __forceinline__ void operator()(EPI_ARGS) const {
;         FOR_AI_M {
;             const int row = u.pm * 256 + ai * 128 + wr * 64 + m * 16 + fr; float ss = 0.f;
;             FOR_BJ_N { const int col = u.pn * 256 + bj * 128 + wc * 32 + n * 16 + 4 * fq;
;                 const f32x4 gg = unpack4(*(const u32x2*)(G + ((size_t)row * 1024 + col))); const f32x4 bb = *(const f32x4*)(bglu + col); f32x4 o;
; #pragma unroll
;                 for (int e = 0; e < 4; ++e) { o[e] = gg[e] * sigmoidf_(acc[ai][bj][m][n][e] + bb[e]); ss += o[e] * o[e]; }
;                 *(u32x2*)(Y + ((size_t)row * 2048 + col)) = pack4(o); }
;             ss += __shfl_xor(ss, 16); ss += __shfl_xor(ss, 32);
;             if (fq == 0) atomicAdd(ssq_a + row, ss);
;         }
;     }
	v_lshl_add_u64 v[34:35], v[48:49], 2, s[4:5]
	s_waitcnt lgkmcnt(0)
	v_add_f32_e32 v32, v32, v33
	global_atomic_add_f32 v[34:35], v32, off
.LBB0_891:
	s_or_b64 exec, exec, s[6:7]
	v_add_u32_e32 v178, 0xa0, v146
	v_ashrrev_i32_e32 v179, 31, v178
	v_lshlrev_b64 v[180:181], 11, v[178:179]
	v_lshl_add_u64 v[182:183], s[60:61], 0, v[180:181]
	v_lshl_add_u64 v[184:185], v[182:183], 0, v[142:143]
	global_load_dwordx2 v[176:177], v[184:185], off
	global_load_dwordx4 v[178:181], v[140:141], off
	global_load_dwordx4 v[182:185], v[140:141], off offset:64
	v_add_u32_e32 v188, 0xa0, v146
	v_ashrrev_i32_e32 v189, 31, v188
	v_lshlrev_b64 v[190:191], 11, v[188:189]
	v_lshl_add_u64 v[192:193], s[60:61], 0, v[190:191]
	v_lshl_add_u64 v[194:195], v[192:193], 0, v[124:125]
	global_load_dwordx2 v[186:187], v[194:195], off
	v_add_u32_e32 v190, 0xa0, v146
	v_ashrrev_i32_e32 v191, 31, v190
	v_lshlrev_b64 v[192:193], 11, v[190:191]
	v_lshl_add_u64 v[194:195], s[60:61], 0, v[192:193]
	v_lshl_add_u64 v[196:197], v[194:195], 0, v[120:121]
	global_load_dwordx2 v[188:189], v[196:197], off
	global_load_dwordx4 v[190:193], v[140:141], off offset:512
	v_add_u32_e32 v196, 0xa0, v146
	v_ashrrev_i32_e32 v197, 31, v196
	v_lshlrev_b64 v[198:199], 11, v[196:197]
	v_lshl_add_u64 v[200:201], s[60:61], 0, v[198:199]
	v_lshl_add_u64 v[202:203], v[200:201], 0, v[116:117]
	global_load_dwordx2 v[194:195], v[202:203], off
	global_load_dwordx4 v[196:199], v[140:141], off offset:576
	v_add_u32_e32 v32, 0xa0, v146
	s_waitcnt lgkmcnt(0)
	v_ashrrev_i32_e32 v33, 31, v32
	v_lshlrev_b64 v[34:35], 11, v[32:33]
	v_lshl_add_u64 v[34:35], s[60:61], 0, v[34:35]
	v_lshl_add_u64 v[36:37], v[34:35], 0, v[142:143]
	s_waitcnt vmcnt(7)
	v_mov_b64_e32 v[36:37], v[176:177]
	v_lshlrev_b64 v[40:41], 12, v[32:33]
	v_lshlrev_b32_e32 v42, 16, v36
	v_and_b32_e32 v43, 0xffff0000, v36
	v_lshlrev_b32_e32 v44, 16, v37
	v_and_b32_e32 v45, 0xffff0000, v37
	s_waitcnt vmcnt(6)
	v_mov_b64_e32 v[36:37], v[178:179]
	v_mov_b64_e32 v[38:39], v[180:181]
	v_add_f32_e32 v30, v30, v38
	v_mul_f32_e32 v30, 0xbfb8aa3b, v30
	v_exp_f32_e32 v30, v30
	v_add_f32_e32 v29, v29, v37
	v_add_f32_e32 v28, v28, v36
	v_mul_f32_e32 v29, 0xbfb8aa3b, v29
	v_add_f32_e32 v30, 1.0, v30
	v_rcp_f32_e32 v30, v30
	v_mul_f32_e32 v28, 0xbfb8aa3b, v28
	v_exp_f32_e32 v29, v29
	v_exp_f32_e32 v28, v28
	v_mul_f32_e32 v37, v30, v44
	v_add_f32_e32 v30, v31, v39
	v_mul_f32_e32 v30, 0xbfb8aa3b, v30
	v_exp_f32_e32 v30, v30
	v_add_f32_e32 v29, 1.0, v29
	v_add_f32_e32 v28, 1.0, v28
	v_rcp_f32_e32 v29, v29
	v_rcp_f32_e32 v28, v28
	v_add_f32_e32 v30, 1.0, v30
	v_rcp_f32_e32 v30, v30
	v_mul_f32_e32 v29, v29, v43
	v_mul_f32_e32 v28, v28, v42
	v_mul_f32_e32 v36, v29, v29
	v_fmac_f32_e32 v36, v28, v28
	v_mul_f32_e32 v31, v30, v45
	v_cvt_pk_bf16_f32 v30, v28, v29
	v_lshl_add_u64 v[28:29], s[58:59], 0, v[40:41]
	v_fmac_f32_e32 v36, v37, v37
	v_lshl_add_u64 v[38:39], v[28:29], 0, v[142:143]
	v_fmac_f32_e32 v36, v31, v31
	v_cvt_pk_bf16_f32 v31, v37, v31
	global_store_dwordx2 v[38:39], v[30:31], off
	s_waitcnt vmcnt(6)
	v_mov_b64_e32 v[38:39], v[182:183]
	v_mov_b64_e32 v[40:41], v[184:185]
	v_lshl_add_u64 v[30:31], v[34:35], 0, v[124:125]
	s_waitcnt vmcnt(5)
	v_mov_b64_e32 v[30:31], v[186:187]
	v_add_f32_e32 v24, v24, v38
	v_mul_f32_e32 v24, 0xbfb8aa3b, v24
	v_add_f32_e32 v25, v25, v39
	v_exp_f32_e32 v24, v24
	v_mul_f32_e32 v25, 0xbfb8aa3b, v25
	v_add_f32_e32 v26, v26, v40
	v_exp_f32_e32 v25, v25
	v_mul_f32_e32 v26, 0xbfb8aa3b, v26
	v_add_f32_e32 v27, v27, v41
	v_exp_f32_e32 v26, v26
	v_mul_f32_e32 v27, 0xbfb8aa3b, v27
	v_exp_f32_e32 v27, v27
	v_add_f32_e32 v24, 1.0, v24
	v_rcp_f32_e32 v24, v24
	v_add_f32_e32 v25, 1.0, v25
	v_rcp_f32_e32 v25, v25
	v_add_f32_e32 v26, 1.0, v26
	v_rcp_f32_e32 v26, v26
	v_add_f32_e32 v27, 1.0, v27
	v_lshlrev_b32_e32 v37, 16, v30
	v_rcp_f32_e32 v27, v27
	v_and_b32_e32 v30, 0xffff0000, v30
	v_mul_f32_e32 v24, v24, v37
	v_lshlrev_b32_e32 v42, 16, v31
	v_fmac_f32_e32 v36, v24, v24
	v_mul_f32_e32 v25, v25, v30
	v_and_b32_e32 v31, 0xffff0000, v31
	v_fmac_f32_e32 v36, v25, v25
	v_mul_f32_e32 v26, v26, v42
	v_fmac_f32_e32 v36, v26, v26
	v_mul_f32_e32 v27, v27, v31
	v_fmac_f32_e32 v36, v27, v27
	v_cvt_pk_bf16_f32 v24, v24, v25
	v_cvt_pk_bf16_f32 v25, v26, v27
	v_lshl_add_u64 v[26:27], v[28:29], 0, v[124:125]
	global_store_dwordx2 v[26:27], v[24:25], off
	v_lshl_add_u64 v[24:25], v[34:35], 0, v[120:121]
	s_waitcnt vmcnt(5)
	v_mov_b64_e32 v[24:25], v[188:189]
	v_lshlrev_b32_e32 v30, 16, v24
	v_and_b32_e32 v31, 0xffff0000, v24
	v_lshlrev_b32_e32 v37, 16, v25
	v_and_b32_e32 v38, 0xffff0000, v25
	s_waitcnt vmcnt(4)
	v_mov_b64_e32 v[24:25], v[190:191]
	v_mov_b64_e32 v[26:27], v[192:193]
	v_add_f32_e32 v20, v20, v24
	v_mul_f32_e32 v20, 0xbfb8aa3b, v20
	v_add_f32_e32 v21, v21, v25
	v_exp_f32_e32 v20, v20
	v_mul_f32_e32 v21, 0xbfb8aa3b, v21
	v_add_f32_e32 v22, v22, v26
	v_exp_f32_e32 v21, v21
	v_mul_f32_e32 v22, 0xbfb8aa3b, v22
	v_add_f32_e32 v23, v23, v27
	v_exp_f32_e32 v22, v22
	v_mul_f32_e32 v23, 0xbfb8aa3b, v23
	v_exp_f32_e32 v23, v23
	v_add_f32_e32 v20, 1.0, v20
	v_rcp_f32_e32 v20, v20
	v_add_f32_e32 v21, 1.0, v21
	v_rcp_f32_e32 v21, v21
	v_add_f32_e32 v22, 1.0, v22
	v_rcp_f32_e32 v22, v22
	v_add_f32_e32 v23, 1.0, v23
	v_rcp_f32_e32 v23, v23
	v_mul_f32_e32 v20, v20, v30
	v_fmac_f32_e32 v36, v20, v20
	v_mul_f32_e32 v21, v21, v31
	v_fmac_f32_e32 v36, v21, v21
	v_mul_f32_e32 v22, v22, v37
	v_fmac_f32_e32 v36, v22, v22
	v_mul_f32_e32 v23, v23, v38
	v_fmac_f32_e32 v36, v23, v23
	v_cvt_pk_bf16_f32 v20, v20, v21
	v_cvt_pk_bf16_f32 v21, v22, v23
	v_lshl_add_u64 v[22:23], v[28:29], 0, v[120:121]
	global_store_dwordx2 v[22:23], v[20:21], off
	v_lshl_add_u64 v[20:21], v[34:35], 0, v[116:117]
	s_waitcnt vmcnt(4)
; __device__ __forceinline__ u32x2 pack4(f32x4 v) { u32x2 r; r.x = cvt_pk(v[0], v[1]); r.y = cvt_pk(v[2], v[3]); return r; }
; __device__ __forceinline__ float sigmoidf_(float x) { return __builtin_amdgcn_rcpf(1.0f + __builtin_amdgcn_exp2f(-1.4426950408889634f * x)); }
; #define FOR_AI_M _Pragma("unroll") for (int ai = 0; ai < 2; ++ai) _Pragma("unroll") for (int m = 0; m < 4; ++m)
; #define FOR_BJ_N _Pragma("unroll") for (int bj = 0; bj < 2; ++bj) _Pragma("unroll") for (int n = 0; n < 2; ++n)
;     __device__ __forceinline__ void operator()(EPI_ARGS) const {
;         FOR_AI_M {
;             const int row = u.pm * 256 + ai * 128 + wr * 64 + m * 16 + fr; float ss = 0.f;
;             FOR_BJ_N { const int col = u.pn * 256 + bj * 128 + wc * 32 + n * 16 + 4 * fq;
;                 const f32x4 gg = unpack4(*(const u32x2*)(G + ((size_t)row * 1024 + col))); const f32x4 bb = *(const f32x4*)(bglu + col); f32x4 o;
; #pragma unroll
;                 for (int e = 0; e < 4; ++e) { o[e] = gg[e] * sigmoidf_(acc[ai][bj][m][n][e] + bb[e]); ss += o[e] * o[e]; }
;                 *(u32x2*)(Y + ((size_t)row * 2048 + col)) = pack4(o); }
;             ss += __shfl_xor(ss, 16); ss += __shfl_xor(ss, 32);
;             if (fq == 0) atomicAdd(ssq_a + row, ss);
;         }
;     }
	v_mov_b64_e32 v[20:21], v[194:195]
	v_lshlrev_b32_e32 v24, 16, v20
	v_and_b32_e32 v25, 0xffff0000, v20
	v_lshlrev_b32_e32 v26, 16, v21
	v_and_b32_e32 v27, 0xffff0000, v21
	s_waitcnt vmcnt(3)
	v_mov_b64_e32 v[20:21], v[196:197]
	v_mov_b64_e32 v[22:23], v[198:199]
	v_add_f32_e32 v16, v16, v20
	v_mul_f32_e32 v16, 0xbfb8aa3b, v16
	v_add_f32_e32 v17, v17, v21
	v_exp_f32_e32 v16, v16
	v_mul_f32_e32 v17, 0xbfb8aa3b, v17
	v_add_f32_e32 v18, v18, v22
	v_exp_f32_e32 v17, v17
	v_mul_f32_e32 v18, 0xbfb8aa3b, v18
	v_add_f32_e32 v19, v19, v23
	v_exp_f32_e32 v18, v18
	v_mul_f32_e32 v19, 0xbfb8aa3b, v19
	v_exp_f32_e32 v19, v19
	v_add_f32_e32 v16, 1.0, v16
	v_rcp_f32_e32 v16, v16
	v_add_f32_e32 v17, 1.0, v17
	v_rcp_f32_e32 v17, v17
	v_add_f32_e32 v18, 1.0, v18
	v_rcp_f32_e32 v18, v18
	v_add_f32_e32 v19, 1.0, v19
	v_rcp_f32_e32 v19, v19
	v_mul_f32_e32 v16, v16, v24
	v_fmac_f32_e32 v36, v16, v16
	v_mul_f32_e32 v17, v17, v25
	v_fmac_f32_e32 v36, v17, v17
	v_mul_f32_e32 v18, v18, v26
	v_fmac_f32_e32 v36, v18, v18
	v_mul_f32_e32 v19, v19, v27
	v_fmac_f32_e32 v36, v19, v19
	v_cvt_pk_bf16_f32 v16, v16, v17
	v_cvt_pk_bf16_f32 v17, v18, v19
	v_lshl_add_u64 v[18:19], v[28:29], 0, v[116:117]
	global_store_dwordx2 v[18:19], v[16:17], off
	ds_bpermute_b32 v16, v118, v36
	s_waitcnt lgkmcnt(0)
	v_add_f32_e32 v16, v36, v16
	ds_bpermute_b32 v17, v119, v16
	s_and_saveexec_b64 s[6:7], vcc
	s_cbranch_execz .LBB0_893
	v_lshl_add_u64 v[18:19], v[32:33], 2, s[4:5]
	s_waitcnt lgkmcnt(0)
	v_add_f32_e32 v16, v16, v17
	global_atomic_add_f32 v[18:19], v16, off
; __device__ __forceinline__ u32x2 pack4(f32x4 v) { u32x2 r; r.x = cvt_pk(v[0], v[1]); r.y = cvt_pk(v[2], v[3]); return r; }
; __device__ __forceinline__ float sigmoidf_(float x) { return __builtin_amdgcn_rcpf(1.0f + __builtin_amdgcn_exp2f(-1.4426950408889634f * x)); }
; #define FOR_AI_M _Pragma("unroll") for (int ai = 0; ai < 2; ++ai) _Pragma("unroll") for (int m = 0; m < 4; ++m)
; #define FOR_BJ_N _Pragma("unroll") for (int bj = 0; bj < 2; ++bj) _Pragma("unroll") for (int n = 0; n < 2; ++n)
;     __device__ __forceinline__ void operator()(EPI_ARGS) const {
;         FOR_AI_M {
;             const int row = u.pm * 256 + ai * 128 + wr * 64 + m * 16 + fr; float ss = 0.f;
;             FOR_BJ_N { const int col = u.pn * 256 + bj * 128 + wc * 32 + n * 16 + 4 * fq;
;                 const f32x4 gg = unpack4(*(const u32x2*)(G + ((size_t)row * 1024 + col))); const f32x4 bb = *(const f32x4*)(bglu + col); f32x4 o;
; #pragma unroll
;                 for (int e = 0; e < 4; ++e) { o[e] = gg[e] * sigmoidf_(acc[ai][bj][m][n][e] + bb[e]); ss += o[e] * o[e]; }
;                 *(u32x2*)(Y + ((size_t)row * 2048 + col)) = pack4(o); }
;             ss += __shfl_xor(ss, 16); ss += __shfl_xor(ss, 32);
;             if (fq == 0) atomicAdd(ssq_a + row, ss);
;         }
;     }
.LBB0_893:
	s_or_b64 exec, exec, s[6:7]
	v_add_u32_e32 v178, 0xb0, v146
	v_ashrrev_i32_e32 v179, 31, v178
	v_lshlrev_b64 v[180:181], 11, v[178:179]
	v_lshl_add_u64 v[182:183], s[60:61], 0, v[180:181]
	v_lshl_add_u64 v[184:185], v[182:183], 0, v[142:143]
	global_load_dwordx2 v[176:177], v[184:185], off
	global_load_dwordx4 v[178:181], v[140:141], off
	global_load_dwordx4 v[182:185], v[140:141], off offset:64
	v_add_u32_e32 v188, 0xb0, v146
	v_ashrrev_i32_e32 v189, 31, v188
	v_lshlrev_b64 v[190:191], 11, v[188:189]
	v_lshl_add_u64 v[192:193], s[60:61], 0, v[190:191]
	v_lshl_add_u64 v[194:195], v[192:193], 0, v[124:125]
	global_load_dwordx2 v[186:187], v[194:195], off
	v_add_u32_e32 v190, 0xb0, v146
	v_ashrrev_i32_e32 v191, 31, v190
	v_lshlrev_b64 v[192:193], 11, v[190:191]
	v_lshl_add_u64 v[194:195], s[60:61], 0, v[192:193]
	v_lshl_add_u64 v[196:197], v[194:195], 0, v[120:121]
	global_load_dwordx2 v[188:189], v[196:197], off
	global_load_dwordx4 v[190:193], v[140:141], off offset:512
	v_add_u32_e32 v196, 0xb0, v146
	v_ashrrev_i32_e32 v197, 31, v196
	v_lshlrev_b64 v[198:199], 11, v[196:197]
	v_lshl_add_u64 v[200:201], s[60:61], 0, v[198:199]
	v_lshl_add_u64 v[202:203], v[200:201], 0, v[116:117]
	global_load_dwordx2 v[194:195], v[202:203], off
	global_load_dwordx4 v[196:199], v[140:141], off offset:576
	v_add_u32_e32 v16, 0xb0, v146
	s_waitcnt lgkmcnt(0)
	v_ashrrev_i32_e32 v17, 31, v16
	v_lshlrev_b64 v[18:19], 11, v[16:17]
	v_lshl_add_u64 v[18:19], s[60:61], 0, v[18:19]
	v_lshl_add_u64 v[20:21], v[18:19], 0, v[142:143]
	s_waitcnt vmcnt(7)
	v_mov_b64_e32 v[20:21], v[176:177]
	v_lshlrev_b64 v[24:25], 12, v[16:17]
	v_lshlrev_b32_e32 v26, 16, v20
	v_and_b32_e32 v27, 0xffff0000, v20
	v_lshlrev_b32_e32 v28, 16, v21
	v_and_b32_e32 v29, 0xffff0000, v21
	s_waitcnt vmcnt(6)
	v_mov_b64_e32 v[20:21], v[178:179]
	v_mov_b64_e32 v[22:23], v[180:181]
	v_add_f32_e32 v14, v14, v22
	v_mul_f32_e32 v14, 0xbfb8aa3b, v14
	v_exp_f32_e32 v14, v14
	v_add_f32_e32 v13, v13, v21
	v_add_f32_e32 v12, v12, v20
	v_mul_f32_e32 v13, 0xbfb8aa3b, v13
	v_add_f32_e32 v14, 1.0, v14
	v_rcp_f32_e32 v14, v14
	v_mul_f32_e32 v12, 0xbfb8aa3b, v12
	v_exp_f32_e32 v13, v13
	v_exp_f32_e32 v12, v12
	v_mul_f32_e32 v21, v14, v28
	v_add_f32_e32 v14, v15, v23
	v_mul_f32_e32 v14, 0xbfb8aa3b, v14
	v_exp_f32_e32 v14, v14
	v_add_f32_e32 v13, 1.0, v13
	v_add_f32_e32 v12, 1.0, v12
	v_rcp_f32_e32 v13, v13
	v_rcp_f32_e32 v12, v12
	v_add_f32_e32 v14, 1.0, v14
	v_rcp_f32_e32 v14, v14
	v_mul_f32_e32 v13, v13, v27
	v_mul_f32_e32 v12, v12, v26
	v_mul_f32_e32 v20, v13, v13
	v_fmac_f32_e32 v20, v12, v12
	v_mul_f32_e32 v15, v14, v29
	v_cvt_pk_bf16_f32 v14, v12, v13
	v_lshl_add_u64 v[12:13], s[58:59], 0, v[24:25]
	v_fmac_f32_e32 v20, v21, v21
	v_lshl_add_u64 v[22:23], v[12:13], 0, v[142:143]
	v_fmac_f32_e32 v20, v15, v15
	v_cvt_pk_bf16_f32 v15, v21, v15
	global_store_dwordx2 v[22:23], v[14:15], off
	s_waitcnt vmcnt(6)
	v_mov_b64_e32 v[22:23], v[182:183]
	v_mov_b64_e32 v[24:25], v[184:185]
	v_lshl_add_u64 v[14:15], v[18:19], 0, v[124:125]
	s_waitcnt vmcnt(5)
	v_mov_b64_e32 v[14:15], v[186:187]
	v_add_f32_e32 v8, v8, v22
	v_mul_f32_e32 v8, 0xbfb8aa3b, v8
	v_add_f32_e32 v9, v9, v23
	v_exp_f32_e32 v8, v8
	v_mul_f32_e32 v9, 0xbfb8aa3b, v9
	v_add_f32_e32 v10, v10, v24
	v_exp_f32_e32 v9, v9
	v_mul_f32_e32 v10, 0xbfb8aa3b, v10
	v_add_f32_e32 v11, v11, v25
	v_exp_f32_e32 v10, v10
	v_mul_f32_e32 v11, 0xbfb8aa3b, v11
	v_exp_f32_e32 v11, v11
	v_add_f32_e32 v8, 1.0, v8
	v_rcp_f32_e32 v8, v8
	v_add_f32_e32 v9, 1.0, v9
	v_rcp_f32_e32 v9, v9
	v_add_f32_e32 v10, 1.0, v10
	v_rcp_f32_e32 v10, v10
	v_add_f32_e32 v11, 1.0, v11
	v_lshlrev_b32_e32 v21, 16, v14
	v_rcp_f32_e32 v11, v11
	v_and_b32_e32 v14, 0xffff0000, v14
	v_mul_f32_e32 v8, v8, v21
	v_lshlrev_b32_e32 v26, 16, v15
	v_fmac_f32_e32 v20, v8, v8
	v_mul_f32_e32 v9, v9, v14
	v_and_b32_e32 v15, 0xffff0000, v15
	v_fmac_f32_e32 v20, v9, v9
	v_mul_f32_e32 v10, v10, v26
	v_fmac_f32_e32 v20, v10, v10
	v_mul_f32_e32 v11, v11, v15
	v_fmac_f32_e32 v20, v11, v11
	v_cvt_pk_bf16_f32 v8, v8, v9
	v_cvt_pk_bf16_f32 v9, v10, v11
	v_lshl_add_u64 v[10:11], v[12:13], 0, v[124:125]
	global_store_dwordx2 v[10:11], v[8:9], off
	v_lshl_add_u64 v[8:9], v[18:19], 0, v[120:121]
	s_waitcnt vmcnt(5)
	v_mov_b64_e32 v[8:9], v[188:189]
	v_lshlrev_b32_e32 v14, 16, v8
	v_and_b32_e32 v15, 0xffff0000, v8
	v_lshlrev_b32_e32 v21, 16, v9
	v_and_b32_e32 v22, 0xffff0000, v9
	s_waitcnt vmcnt(4)
	v_mov_b64_e32 v[8:9], v[190:191]
	v_mov_b64_e32 v[10:11], v[192:193]
	v_add_f32_e32 v4, v4, v8
	v_mul_f32_e32 v4, 0xbfb8aa3b, v4
	v_add_f32_e32 v5, v5, v9
	v_exp_f32_e32 v4, v4
	v_mul_f32_e32 v5, 0xbfb8aa3b, v5
	v_add_f32_e32 v6, v6, v10
	v_exp_f32_e32 v5, v5
	v_mul_f32_e32 v6, 0xbfb8aa3b, v6
	v_add_f32_e32 v7, v7, v11
	v_exp_f32_e32 v6, v6
	v_mul_f32_e32 v7, 0xbfb8aa3b, v7
	v_exp_f32_e32 v7, v7
	v_add_f32_e32 v4, 1.0, v4
	v_rcp_f32_e32 v4, v4
	v_add_f32_e32 v5, 1.0, v5
	v_rcp_f32_e32 v5, v5
	v_add_f32_e32 v6, 1.0, v6
	v_rcp_f32_e32 v6, v6
	v_add_f32_e32 v7, 1.0, v7
	v_rcp_f32_e32 v7, v7
	v_mul_f32_e32 v4, v4, v14
	v_fmac_f32_e32 v20, v4, v4
	v_mul_f32_e32 v5, v5, v15
	v_fmac_f32_e32 v20, v5, v5
	v_mul_f32_e32 v6, v6, v21
	v_fmac_f32_e32 v20, v6, v6
	v_mul_f32_e32 v7, v7, v22
	v_fmac_f32_e32 v20, v7, v7
	v_cvt_pk_bf16_f32 v4, v4, v5
	v_cvt_pk_bf16_f32 v5, v6, v7
	v_lshl_add_u64 v[6:7], v[12:13], 0, v[120:121]
	global_store_dwordx2 v[6:7], v[4:5], off
	v_lshl_add_u64 v[4:5], v[18:19], 0, v[116:117]
	s_waitcnt vmcnt(4)
	v_mov_b64_e32 v[4:5], v[194:195]
	v_lshlrev_b32_e32 v8, 16, v4
	v_and_b32_e32 v9, 0xffff0000, v4
	v_lshlrev_b32_e32 v10, 16, v5
	v_and_b32_e32 v11, 0xffff0000, v5
	s_waitcnt vmcnt(3)
	v_mov_b64_e32 v[4:5], v[196:197]
	v_mov_b64_e32 v[6:7], v[198:199]
	v_add_f32_e32 v0, v0, v4
	v_mul_f32_e32 v0, 0xbfb8aa3b, v0
	v_add_f32_e32 v1, v1, v5
	v_exp_f32_e32 v0, v0
	v_mul_f32_e32 v1, 0xbfb8aa3b, v1
	v_add_f32_e32 v2, v2, v6
	v_exp_f32_e32 v1, v1
	v_mul_f32_e32 v2, 0xbfb8aa3b, v2
	v_add_f32_e32 v3, v3, v7
	v_exp_f32_e32 v2, v2
	v_mul_f32_e32 v3, 0xbfb8aa3b, v3
	v_exp_f32_e32 v3, v3
	v_add_f32_e32 v0, 1.0, v0
	v_rcp_f32_e32 v0, v0
	v_add_f32_e32 v1, 1.0, v1
	v_rcp_f32_e32 v1, v1
	v_add_f32_e32 v2, 1.0, v2
	v_rcp_f32_e32 v2, v2
	v_add_f32_e32 v3, 1.0, v3
	v_rcp_f32_e32 v3, v3
	v_mul_f32_e32 v0, v0, v8
	v_fmac_f32_e32 v20, v0, v0
	v_mul_f32_e32 v1, v1, v9
	v_fmac_f32_e32 v20, v1, v1
	v_mul_f32_e32 v2, v2, v10
	v_fmac_f32_e32 v20, v2, v2
	v_mul_f32_e32 v3, v3, v11
	v_fmac_f32_e32 v20, v3, v3
	v_cvt_pk_bf16_f32 v0, v0, v1
	v_cvt_pk_bf16_f32 v1, v2, v3
	v_lshl_add_u64 v[2:3], v[12:13], 0, v[116:117]
	global_store_dwordx2 v[2:3], v[0:1], off
	ds_bpermute_b32 v0, v118, v20
	s_waitcnt lgkmcnt(0)
	v_add_f32_e32 v0, v20, v0
	ds_bpermute_b32 v1, v119, v0
	s_and_saveexec_b64 s[6:7], vcc
	s_cbranch_execz .LBB0_895
	v_lshl_add_u64 v[2:3], v[16:17], 2, s[4:5]
	s_waitcnt lgkmcnt(0)
	v_add_f32_e32 v0, v0, v1
	global_atomic_add_f32 v[2:3], v0, off

; __device__ __forceinline__ u32x2 pack4(f32x4 v) { u32x2 r; r.x = cvt_pk(v[0], v[1]); r.y = cvt_pk(v[2], v[3]); return r; }
; #define FOR_AI_M _Pragma("unroll") for (int ai = 0; ai < 2; ++ai) _Pragma("unroll") for (int m = 0; m < 4; ++m)
; #define FOR_BJ_N _Pragma("unroll") for (int bj = 0; bj < 2; ++bj) _Pragma("unroll") for (int n = 0; n < 2; ++n)
;     __device__ __forceinline__ void operator()(EPI_ARGS) const {
;         f32x4 ginv[2][2];
;         FOR_BJ_N { const f32x4 gg = *(const f32x4*)(gmix + u.pn * 256 + bj * 128 + wc * 32 + n * 16 + 4 * fq);
; #pragma unroll
;             for (int e = 0; e < 4; ++e) ginv[bj][n][e] = __builtin_amdgcn_rcpf(gg[e]); }
;         FOR_AI_M {
;             const int row = u.pm * 256 + ai * 128 + wr * 64 + m * 16 + fr;
;             const float rb = rsqrtf(ssq_b[row] * (1.0f / 1024.0f) + EPS), ri = rinvx[row];
;             const int b = row >> 11, tp = row & 2047;
;             const bf16_t* hrow = XN + (size_t)row * 2048;
;             float ss = 0.f;
;             FOR_BJ_N { const int col = u.pn * 256 + bj * 128 + wc * 32 + n * 16 + 4 * fq;
;                 const f32x4 v = acc[ai][bj][m][n] * rb + unpack4(*(const u32x2*)(hrow + col)) * (ginv[bj][n] * ri);
;                 ss += v[0] * v[0] + v[1] * v[1] + v[2] * v[2] + v[3] * v[3];
;                 *(u32x2*)(XH + ((size_t)(b * XHB + tp + 2) * 2048 + col)) = pack4(v); }
;             ss += __shfl_xor(ss, 16); ss += __shfl_xor(ss, 32);
;             if (fq == 0) atomicAdd(ssq_h + b * XHB + tp + 2, ss);
;         }
;     }
.LBB0_980:
	v_mbcnt_lo_u32_b32 v254, -1, 0
	v_mbcnt_hi_u32_b32 v254, -1, v254
	v_and_b32_e32 v254, 16, v254
	v_lshrrev_b32_e32 v255, 1, v254
	v_add_u32_e32 v254, v254, v255
	v_mov_b32_e32 v255, 0
	s_lshl_b32 s6, s44, 8
	v_readlane_b32 s64, v241, 44
	s_ashr_i32 s7, s6, 31
	v_readlane_b32 s68, v241, 48
	v_readlane_b32 s69, v241, 49
	s_lshl_b64 s[8:9], s[6:7], 2
	s_mov_b64 s[56:57], s[68:69]
	v_mov_b32_e32 v1, v165
	v_mov_b32_e32 v164, v169
	s_mov_b32 s35, s12
	s_mov_b32 s10, s49
	s_add_u32 s7, s56, s8
	s_addc_u32 s42, s57, s9
	s_lshl_b32 s8, s10, 5
	s_ashr_i32 s9, s8, 31
	s_lshl_b64 s[10:11], s[8:9], 2
	s_add_u32 s10, s7, s10
	v_lshlrev_b32_e32 v162, 2, v164
	s_addc_u32 s11, s42, s11
	v_ashrrev_i32_e32 v163, 31, v162
	v_lshl_add_u64 v[2:3], v[162:163], 2, s[10:11]
	global_load_dwordx4 v[144:147], v[2:3], off
	global_load_dwordx4 v[158:161], v[2:3], off offset:576
	s_lshl_b32 s7, s35, 6
	s_add_i32 s7, s7, s31
	s_add_i32 s6, s8, s6
	v_add_u32_e32 v166, s6, v162
	v_cmp_eq_u32_e32 vcc, 0, v164
	v_ashrrev_i32_e32 v167, 31, v166
	v_readlane_b32 s65, v241, 45
	v_readlane_b32 s66, v241, 46
	v_readlane_b32 s67, v241, 47
	v_readlane_b32 s70, v241, 50
	v_readlane_b32 s71, v241, 51
	v_readlane_b32 s72, v241, 52
	v_readlane_b32 s73, v241, 53
	v_readlane_b32 s74, v241, 54
	v_readlane_b32 s75, v241, 55
	v_readlane_b32 s76, v241, 56
	v_readlane_b32 s77, v241, 57
	v_readlane_b32 s78, v241, 58
	v_readlane_b32 s79, v241, 59
	s_waitcnt vmcnt(0)
	v_rcp_f32_e32 v154, v144
	v_rcp_f32_e32 v155, v145
	v_rcp_f32_e32 v156, v146
	v_rcp_f32_e32 v157, v147
	global_load_dwordx4 v[144:147], v[2:3], off offset:64
	s_waitcnt vmcnt(0)
	v_rcp_f32_e32 v152, v146
	v_rcp_f32_e32 v153, v147
	global_load_dwordx4 v[146:149], v[2:3], off offset:512
	v_rcp_f32_e32 v2, v158
	v_add_u32_e32 v158, s7, v1
	v_rcp_f32_e32 v3, v159
	v_ashrrev_i32_e32 v159, 31, v158
	v_rcp_f32_e32 v150, v144
	v_rcp_f32_e32 v151, v145
	v_rcp_f32_e32 v144, v160
	v_rcp_f32_e32 v145, v161
	v_lshlrev_b64 v[160:161], 2, v[158:159]
	v_lshl_add_u64 v[162:163], s[62:63], 0, v[160:161]
	global_load_dword v1, v[162:163], off
	v_lshl_add_u64 v[160:161], s[20:21], 0, v[160:161]
	global_load_dword v168, v[160:161], off
	v_and_b32_e32 v179, 0x7ff, v158
	v_lshlrev_b64 v[160:161], 12, v[158:159]
	v_lshl_add_u64 v[176:177], s[0:1], 0, v[160:161]
	s_waitcnt vmcnt(2)
	v_rcp_f32_e32 v146, v146
	v_rcp_f32_e32 v147, v147
	v_rcp_f32_e32 v148, v148
	v_rcp_f32_e32 v149, v149
	s_waitcnt vmcnt(1)
	v_fmamk_f32 v1, v1, 0x3a800000, v175
	v_cmp_gt_f32_e64 s[42:43], s52, v1
	v_mul_f32_e32 v162, 0x4b800000, v1
	s_waitcnt vmcnt(0)
	v_pk_mul_f32 v[188:189], v[154:155], v[168:169] op_sel_hi:[1,0]
	v_cndmask_b32_e64 v1, v1, v162, s[42:43]
	v_rsq_f32_e32 v1, v1
	v_pk_mul_f32 v[186:187], v[156:157], v[168:169] op_sel_hi:[1,0]
	v_mul_f32_e32 v162, 0x45800000, v1
	v_cndmask_b32_e64 v164, v1, v162, s[42:43]
	v_ashrrev_i32_e32 v1, 11, v158
	v_mul_i32_i24_e32 v162, 0x802, v1
	v_add3_u32 v160, v179, v162, 2
	v_ashrrev_i32_e32 v161, 31, v160
	v_lshlrev_b64 v[180:181], 12, v[160:161]
	v_lshlrev_b64 v[160:161], 1, v[166:167]
	v_lshl_add_u64 v[176:177], v[176:177], 0, v[160:161]
	global_load_dwordx2 v[182:183], v[176:177], off
	global_load_dwordx2 v[192:193], v[176:177], off offset:32
	global_load_dwordx2 v[194:195], v[176:177], off offset:256
	global_load_dwordx2 v[196:197], v[176:177], off offset:288
	s_waitcnt vmcnt(3)
	v_lshlrev_b32_e32 v184, 16, v182
	v_and_b32_e32 v185, 0xffff0000, v182
	v_pk_mul_f32 v[184:185], v[188:189], v[184:185]
	v_lshlrev_b32_e32 v182, 16, v183
	v_and_b32_e32 v183, 0xffff0000, v183
	v_pk_fma_f32 v[128:129], v[128:129], v[164:165], v[184:185] op_sel_hi:[1,0,1]
	v_pk_mul_f32 v[182:183], v[186:187], v[182:183]
	v_mul_f32_e32 v1, v129, v129
	v_pk_fma_f32 v[130:131], v[130:131], v[164:165], v[182:183] op_sel_hi:[1,0,1]
	v_fmac_f32_e32 v1, v128, v128
	v_fmac_f32_e32 v1, v130, v130
	v_fmac_f32_e32 v1, v131, v131
	v_cvt_pk_bf16_f32 v244, v128, v129
	v_cvt_pk_bf16_f32 v245, v130, v131
	v_lshl_add_u64 v[130:131], s[14:15], 0, v[180:181]
	v_lshl_add_u64 v[180:181], v[130:131], 0, v[160:161]
	v_lshl_add_u64 v[252:253], v[180:181], 0, v[254:255]
	s_waitcnt vmcnt(2)
	v_mov_b64_e32 v[180:181], v[192:193]
	v_pk_mul_f32 v[186:187], v[150:151], v[168:169] op_sel_hi:[1,0]
	v_pk_mul_f32 v[184:185], v[152:153], v[168:169] op_sel_hi:[1,0]
	v_add_u32_e32 v128, 16, v166
	v_ashrrev_i32_e32 v129, 31, v128
	v_lshlrev_b32_e32 v182, 16, v180
	v_and_b32_e32 v183, 0xffff0000, v180
	v_pk_mul_f32 v[182:183], v[186:187], v[182:183]
	v_lshlrev_b32_e32 v180, 16, v181
	v_and_b32_e32 v181, 0xffff0000, v181
	v_pk_fma_f32 v[124:125], v[124:125], v[164:165], v[182:183] op_sel_hi:[1,0,1]
	v_pk_mul_f32 v[180:181], v[184:185], v[180:181]
	v_mul_f32_e32 v159, v125, v125
	v_pk_fma_f32 v[126:127], v[126:127], v[164:165], v[180:181] op_sel_hi:[1,0,1]
	v_fmac_f32_e32 v159, v124, v124
	v_fmac_f32_e32 v159, v126, v126
	v_fmac_f32_e32 v159, v127, v127
	v_cvt_pk_bf16_f32 v246, v124, v125
	v_cvt_pk_bf16_f32 v247, v126, v127
	v_lshl_add_u64 v[126:127], v[128:129], 1, v[130:131]
	s_nop 1
	v_permlane16_swap_b32_e32 v244, v246
	v_permlane16_swap_b32_e32 v245, v247
	global_store_dwordx4 v[252:253], v[244:247], off
	s_waitcnt vmcnt(2)
; __device__ __forceinline__ u32x2 pack4(f32x4 v) { u32x2 r; r.x = cvt_pk(v[0], v[1]); r.y = cvt_pk(v[2], v[3]); return r; }
; #define FOR_AI_M _Pragma("unroll") for (int ai = 0; ai < 2; ++ai) _Pragma("unroll") for (int m = 0; m < 4; ++m)
; #define FOR_BJ_N _Pragma("unroll") for (int bj = 0; bj < 2; ++bj) _Pragma("unroll") for (int n = 0; n < 2; ++n)
;     __device__ __forceinline__ void operator()(EPI_ARGS) const {
;     ...
;         FOR_AI_M {
;             const int row = u.pm * 256 + ai * 128 + wr * 64 + m * 16 + fr;
;             const float rb = rsqrtf(ssq_b[row] * (1.0f / 1024.0f) + EPS), ri = rinvx[row];
;             const int b = row >> 11, tp = row & 2047;
;             const bf16_t* hrow = XN + (size_t)row * 2048;
;             float ss = 0.f;
;             FOR_BJ_N { const int col = u.pn * 256 + bj * 128 + wc * 32 + n * 16 + 4 * fq;
;                 const f32x4 v = acc[ai][bj][m][n] * rb + unpack4(*(const u32x2*)(hrow + col)) * (ginv[bj][n] * ri);
;                 ss += v[0] * v[0] + v[1] * v[1] + v[2] * v[2] + v[3] * v[3];
;                 *(u32x2*)(XH + ((size_t)(b * XHB + tp + 2) * 2048 + col)) = pack4(v); }
;             ss += __shfl_xor(ss, 16); ss += __shfl_xor(ss, 32);
;             if (fq == 0) atomicAdd(ssq_h + b * XHB + tp + 2, ss);
;         }
	v_mov_b64_e32 v[126:127], v[194:195]
	v_pk_mul_f32 v[184:185], v[168:169], v[146:147] op_sel_hi:[0,1]
	v_pk_mul_f32 v[182:183], v[168:169], v[148:149] op_sel_hi:[0,1]
	v_add_u32_e32 v124, 0x80, v166
	v_ashrrev_i32_e32 v125, 31, v124
	v_add_f32_e32 v1, v1, v159
	v_lshlrev_b32_e32 v180, 16, v126
	v_and_b32_e32 v181, 0xffff0000, v126
	v_lshlrev_b32_e32 v126, 16, v127
	v_and_b32_e32 v127, 0xffff0000, v127
	v_pk_mul_f32 v[180:181], v[184:185], v[180:181]
	v_pk_mul_f32 v[126:127], v[182:183], v[126:127]
	v_pk_fma_f32 v[120:121], v[120:121], v[164:165], v[180:181] op_sel_hi:[1,0,1]
	v_pk_fma_f32 v[122:123], v[122:123], v[164:165], v[126:127] op_sel_hi:[1,0,1]
	v_mul_f32_e32 v126, v121, v121
	v_fmac_f32_e32 v126, v120, v120
	v_fmac_f32_e32 v126, v122, v122
	v_fmac_f32_e32 v126, v123, v123
	v_cvt_pk_bf16_f32 v248, v120, v121
	v_cvt_pk_bf16_f32 v249, v122, v123
	v_lshl_add_u64 v[122:123], v[124:125], 1, v[130:131]
	v_lshl_add_u64 v[252:253], v[122:123], 0, v[254:255]
	s_waitcnt vmcnt(1)
	v_mov_b64_e32 v[122:123], v[196:197]
	v_add_f32_e32 v1, v1, v126
	v_pk_mul_f32 v[176:177], v[168:169], v[2:3] op_sel_hi:[0,1]
	v_add_u32_e32 v120, 0x90, v166
	v_pk_mul_f32 v[166:167], v[168:169], v[144:145] op_sel_hi:[0,1]
	v_ashrrev_i32_e32 v121, 31, v120
	v_lshlrev_b32_e32 v126, 16, v122
	v_and_b32_e32 v127, 0xffff0000, v122
	v_lshlrev_b32_e32 v122, 16, v123
	v_and_b32_e32 v123, 0xffff0000, v123
	v_pk_mul_f32 v[126:127], v[176:177], v[126:127]
	v_pk_mul_f32 v[122:123], v[166:167], v[122:123]
	v_pk_fma_f32 v[116:117], v[116:117], v[164:165], v[126:127] op_sel_hi:[1,0,1]
	v_pk_fma_f32 v[118:119], v[118:119], v[164:165], v[122:123] op_sel_hi:[1,0,1]
	v_mul_f32_e32 v122, v117, v117
	v_fmac_f32_e32 v122, v116, v116
	v_fmac_f32_e32 v122, v118, v118
	v_fmac_f32_e32 v122, v119, v119
	v_cvt_pk_bf16_f32 v250, v116, v117
	v_cvt_pk_bf16_f32 v251, v118, v119
	v_lshl_add_u64 v[118:119], v[120:121], 1, v[130:131]
	s_nop 1
	v_permlane16_swap_b32_e32 v248, v250
	v_permlane16_swap_b32_e32 v249, v251
	global_store_dwordx4 v[252:253], v[248:251], off
	v_and_b32_e32 v116, 64, v178
	v_add_f32_e32 v122, v1, v122
	v_xor_b32_e32 v1, 16, v178
	v_add_u32_e32 v117, 64, v116
	v_cmp_lt_i32_e64 s[42:43], v1, v117
	v_xor_b32_e32 v118, 32, v178
	s_nop 0
	v_cndmask_b32_e64 v1, v178, v1, s[42:43]
	v_lshlrev_b32_e32 v1, 2, v1
	ds_bpermute_b32 v116, v1, v122
	v_cmp_lt_i32_e64 s[42:43], v118, v117
	s_waitcnt lgkmcnt(0)
	v_add_f32_e32 v116, v122, v116
	v_cndmask_b32_e64 v117, v178, v118, s[42:43]
	v_lshlrev_b32_e32 v119, 2, v117
	ds_bpermute_b32 v117, v119, v116
	s_and_saveexec_b64 s[6:7], vcc
	s_cbranch_execz .LBB0_982
	v_ashrrev_i32_e32 v163, 31, v162
	v_lshl_add_u64 v[122:123], v[162:163], 2, s[16:17]
	v_lshlrev_b32_e32 v126, 2, v179
	v_mov_b32_e32 v127, v0
	v_lshl_add_u64 v[122:123], v[122:123], 0, v[126:127]
	s_waitcnt lgkmcnt(0)
	v_add_f32_e32 v116, v116, v117
	global_atomic_add_f32 v[122:123], v116, off offset:8
.LBB0_982:
	s_or_b64 exec, exec, s[6:7]
	v_add_u32_e32 v116, 16, v158
	s_waitcnt lgkmcnt(0)
	v_ashrrev_i32_e32 v117, 31, v116
	v_lshlrev_b64 v[122:123], 2, v[116:117]
	v_lshl_add_u64 v[126:127], s[62:63], 0, v[122:123]
	global_load_dword v118, v[126:127], off
	v_lshl_add_u64 v[122:123], s[20:21], 0, v[122:123]
	global_load_dword v122, v[122:123], off
	v_ashrrev_i32_e32 v130, 11, v116
	v_and_b32_e32 v123, 0x7ff, v116
	v_lshlrev_b64 v[116:117], 12, v[116:117]
	s_waitcnt vmcnt(1)
	v_fmamk_f32 v118, v118, 0x3a800000, v175
	v_cmp_gt_f32_e64 s[42:43], s52, v118
	v_mul_f32_e32 v126, 0x4b800000, v118
	s_waitcnt vmcnt(0)
	v_pk_mul_f32 v[180:181], v[154:155], v[122:123] op_sel_hi:[1,0]
	v_cndmask_b32_e64 v118, v118, v126, s[42:43]
	v_rsq_f32_e32 v118, v118
	v_pk_mul_f32 v[176:177], v[156:157], v[122:123] op_sel_hi:[1,0]
	v_mul_f32_e32 v126, 0x45800000, v118
	v_cndmask_b32_e64 v118, v118, v126, s[42:43]
	v_lshl_add_u64 v[126:127], s[0:1], 0, v[116:117]
	v_lshl_add_u64 v[126:127], v[126:127], 0, v[160:161]
	global_load_dwordx2 v[162:163], v[126:127], off
	global_load_dwordx2 v[192:193], v[126:127], off offset:32
	global_load_dwordx2 v[194:195], v[126:127], off offset:256
	global_load_dwordx2 v[196:197], v[126:127], off offset:288
	v_mul_i32_i24_e32 v116, 0x802, v130
	v_add3_u32 v130, v123, v116, 2
	v_ashrrev_i32_e32 v131, 31, v130
	v_lshlrev_b64 v[130:131], 12, v[130:131]
	s_waitcnt vmcnt(3)
	v_lshlrev_b32_e32 v166, 16, v162
	v_and_b32_e32 v167, 0xffff0000, v162
	v_pk_mul_f32 v[166:167], v[180:181], v[166:167]
	v_lshlrev_b32_e32 v162, 16, v163
	v_and_b32_e32 v163, 0xffff0000, v163
	v_pk_fma_f32 v[112:113], v[112:113], v[118:119], v[166:167] op_sel_hi:[1,0,1]
	v_pk_mul_f32 v[162:163], v[176:177], v[162:163]
	v_mul_f32_e32 v117, v113, v113
	v_pk_fma_f32 v[114:115], v[114:115], v[118:119], v[162:163] op_sel_hi:[1,0,1]
	v_fmac_f32_e32 v117, v112, v112
	v_fmac_f32_e32 v117, v114, v114
	v_cvt_pk_bf16_f32 v244, v112, v113
	v_lshl_add_u64 v[112:113], s[14:15], 0, v[130:131]
	v_fmac_f32_e32 v117, v115, v115
	v_cvt_pk_bf16_f32 v245, v114, v115
	v_lshl_add_u64 v[114:115], v[112:113], 0, v[160:161]
	v_lshl_add_u64 v[252:253], v[114:115], 0, v[254:255]
	s_waitcnt vmcnt(2)
	v_mov_b64_e32 v[114:115], v[192:193]
	v_pk_mul_f32 v[166:167], v[150:151], v[122:123] op_sel_hi:[1,0]
	v_pk_mul_f32 v[162:163], v[152:153], v[122:123] op_sel_hi:[1,0]
	v_lshlrev_b32_e32 v130, 16, v114
	v_and_b32_e32 v131, 0xffff0000, v114
	v_lshlrev_b32_e32 v114, 16, v115
	v_and_b32_e32 v115, 0xffff0000, v115
	v_pk_mul_f32 v[130:131], v[166:167], v[130:131]
	v_pk_mul_f32 v[114:115], v[162:163], v[114:115]
	v_pk_fma_f32 v[108:109], v[108:109], v[118:119], v[130:131] op_sel_hi:[1,0,1]
	v_pk_fma_f32 v[110:111], v[110:111], v[118:119], v[114:115] op_sel_hi:[1,0,1]
	v_mul_f32_e32 v114, v109, v109
	v_fmac_f32_e32 v114, v108, v108
	v_fmac_f32_e32 v114, v110, v110
	v_fmac_f32_e32 v114, v111, v111
	v_cvt_pk_bf16_f32 v246, v108, v109
	v_cvt_pk_bf16_f32 v247, v110, v111
	v_lshl_add_u64 v[110:111], v[128:129], 1, v[112:113]
	s_nop 1
	v_permlane16_swap_b32_e32 v244, v246
	v_permlane16_swap_b32_e32 v245, v247
	global_store_dwordx4 v[252:253], v[244:247], off
	s_waitcnt vmcnt(2)
; __device__ __forceinline__ u32x2 pack4(f32x4 v) { u32x2 r; r.x = cvt_pk(v[0], v[1]); r.y = cvt_pk(v[2], v[3]); return r; }
; #define FOR_AI_M _Pragma("unroll") for (int ai = 0; ai < 2; ++ai) _Pragma("unroll") for (int m = 0; m < 4; ++m)
; #define FOR_BJ_N _Pragma("unroll") for (int bj = 0; bj < 2; ++bj) _Pragma("unroll") for (int n = 0; n < 2; ++n)
;     __device__ __forceinline__ void operator()(EPI_ARGS) const {
;     ...
;         FOR_AI_M {
;             const int row = u.pm * 256 + ai * 128 + wr * 64 + m * 16 + fr;
;             const float rb = rsqrtf(ssq_b[row] * (1.0f / 1024.0f) + EPS), ri = rinvx[row];
;             const int b = row >> 11, tp = row & 2047;
;             const bf16_t* hrow = XN + (size_t)row * 2048;
;             float ss = 0.f;
;             FOR_BJ_N { const int col = u.pn * 256 + bj * 128 + wc * 32 + n * 16 + 4 * fq;
;                 const f32x4 v = acc[ai][bj][m][n] * rb + unpack4(*(const u32x2*)(hrow + col)) * (ginv[bj][n] * ri);
;                 ss += v[0] * v[0] + v[1] * v[1] + v[2] * v[2] + v[3] * v[3];
;                 *(u32x2*)(XH + ((size_t)(b * XHB + tp + 2) * 2048 + col)) = pack4(v); }
;             ss += __shfl_xor(ss, 16); ss += __shfl_xor(ss, 32);
;             if (fq == 0) atomicAdd(ssq_h + b * XHB + tp + 2, ss);
;         }
	v_mov_b64_e32 v[108:109], v[194:195]
	v_pk_mul_f32 v[130:131], v[146:147], v[122:123] op_sel_hi:[1,0]
	v_add_f32_e32 v117, v117, v114
	v_pk_mul_f32 v[114:115], v[148:149], v[122:123] op_sel_hi:[1,0]
	v_lshlrev_b32_e32 v110, 16, v108
	v_and_b32_e32 v111, 0xffff0000, v108
	v_lshlrev_b32_e32 v108, 16, v109
	v_and_b32_e32 v109, 0xffff0000, v109
	v_pk_mul_f32 v[110:111], v[130:131], v[110:111]
	v_pk_mul_f32 v[108:109], v[114:115], v[108:109]
	v_pk_fma_f32 v[104:105], v[104:105], v[118:119], v[110:111] op_sel_hi:[1,0,1]
	v_pk_fma_f32 v[106:107], v[106:107], v[118:119], v[108:109] op_sel_hi:[1,0,1]
	v_mul_f32_e32 v108, v105, v105
	v_fmac_f32_e32 v108, v104, v104
	v_fmac_f32_e32 v108, v106, v106
	v_fmac_f32_e32 v108, v107, v107
	v_cvt_pk_bf16_f32 v248, v104, v105
	v_cvt_pk_bf16_f32 v249, v106, v107
	v_lshl_add_u64 v[106:107], v[124:125], 1, v[112:113]
	v_lshl_add_u64 v[252:253], v[106:107], 0, v[254:255]
	s_waitcnt vmcnt(1)
	v_mov_b64_e32 v[104:105], v[196:197]
	v_pk_mul_f32 v[110:111], v[2:3], v[122:123] op_sel_hi:[1,0]
	v_add_f32_e32 v114, v117, v108
	v_pk_mul_f32 v[108:109], v[144:145], v[122:123] op_sel_hi:[1,0]
	v_lshlrev_b32_e32 v106, 16, v104
	v_and_b32_e32 v107, 0xffff0000, v104
	v_lshlrev_b32_e32 v104, 16, v105
	v_and_b32_e32 v105, 0xffff0000, v105
	v_pk_mul_f32 v[106:107], v[110:111], v[106:107]
	v_pk_mul_f32 v[104:105], v[108:109], v[104:105]
	v_pk_fma_f32 v[100:101], v[100:101], v[118:119], v[106:107] op_sel_hi:[1,0,1]
	v_pk_fma_f32 v[102:103], v[102:103], v[118:119], v[104:105] op_sel_hi:[1,0,1]
	v_mul_f32_e32 v104, v101, v101
	v_fmac_f32_e32 v104, v100, v100
	v_fmac_f32_e32 v104, v102, v102
	v_fmac_f32_e32 v104, v103, v103
	v_add_f32_e32 v104, v114, v104
	v_cvt_pk_bf16_f32 v250, v100, v101
	v_cvt_pk_bf16_f32 v251, v102, v103
	v_lshl_add_u64 v[102:103], v[120:121], 1, v[112:113]
	s_nop 1
	v_permlane16_swap_b32_e32 v248, v250
	v_permlane16_swap_b32_e32 v249, v251
	global_store_dwordx4 v[252:253], v[248:251], off
	ds_bpermute_b32 v100, v1, v104
	s_waitcnt lgkmcnt(0)
	v_add_f32_e32 v100, v104, v100
	ds_bpermute_b32 v101, v119, v100
	s_and_saveexec_b64 s[6:7], vcc
	s_cbranch_execz .LBB0_984
	v_ashrrev_i32_e32 v117, 31, v116
	v_lshl_add_u64 v[102:103], v[116:117], 2, s[16:17]
	v_lshlrev_b32_e32 v104, 2, v123
	v_mov_b32_e32 v105, v0
	v_lshl_add_u64 v[102:103], v[102:103], 0, v[104:105]
	s_waitcnt lgkmcnt(0)
	v_add_f32_e32 v100, v100, v101
	global_atomic_add_f32 v[102:103], v100, off offset:8
.LBB0_984:
	s_or_b64 exec, exec, s[6:7]
	v_add_u32_e32 v100, 32, v158
	s_waitcnt lgkmcnt(0)
	v_ashrrev_i32_e32 v101, 31, v100
	v_lshlrev_b64 v[104:105], 2, v[100:101]
	v_lshl_add_u64 v[102:103], s[62:63], 0, v[104:105]
	global_load_dword v102, v[102:103], off
	v_lshl_add_u64 v[104:105], s[20:21], 0, v[104:105]
	global_load_dword v104, v[104:105], off
	v_ashrrev_i32_e32 v105, 11, v100
	s_waitcnt vmcnt(1)
	v_fmamk_f32 v102, v102, 0x3a800000, v175
	v_cmp_gt_f32_e64 s[42:43], s52, v102
	v_mul_f32_e32 v103, 0x4b800000, v102
	s_waitcnt vmcnt(0)
	v_pk_mul_f32 v[116:117], v[154:155], v[104:105] op_sel_hi:[1,0]
	v_cndmask_b32_e64 v102, v102, v103, s[42:43]
	v_rsq_f32_e32 v102, v102
	v_pk_mul_f32 v[114:115], v[156:157], v[104:105] op_sel_hi:[1,0]
	v_mul_f32_e32 v103, 0x45800000, v102
	v_cndmask_b32_e64 v102, v102, v103, s[42:43]
	v_and_b32_e32 v103, 0x7ff, v100
	v_lshlrev_b64 v[100:101], 12, v[100:101]
	v_lshl_add_u64 v[106:107], s[0:1], 0, v[100:101]
	v_lshl_add_u64 v[106:107], v[106:107], 0, v[160:161]
	global_load_dwordx2 v[110:111], v[106:107], off
	global_load_dwordx2 v[192:193], v[106:107], off offset:32
	global_load_dwordx2 v[194:195], v[106:107], off offset:256
	global_load_dwordx2 v[196:197], v[106:107], off offset:288
	v_mul_i32_i24_e32 v100, 0x802, v105
	v_add3_u32 v108, v103, v100, 2
	v_ashrrev_i32_e32 v109, 31, v108
	v_lshlrev_b64 v[108:109], 12, v[108:109]
	s_waitcnt vmcnt(3)
	v_lshlrev_b32_e32 v112, 16, v110
	v_and_b32_e32 v113, 0xffff0000, v110
	v_pk_mul_f32 v[112:113], v[116:117], v[112:113]
	v_lshlrev_b32_e32 v110, 16, v111
	v_and_b32_e32 v111, 0xffff0000, v111
	v_pk_fma_f32 v[96:97], v[96:97], v[102:103], v[112:113] op_sel_hi:[1,0,1]
	v_pk_mul_f32 v[110:111], v[114:115], v[110:111]
	v_mul_f32_e32 v101, v97, v97
	v_pk_fma_f32 v[98:99], v[98:99], v[102:103], v[110:111] op_sel_hi:[1,0,1]
	v_fmac_f32_e32 v101, v96, v96
	v_fmac_f32_e32 v101, v98, v98
	v_cvt_pk_bf16_f32 v244, v96, v97
	v_lshl_add_u64 v[96:97], s[14:15], 0, v[108:109]
	v_fmac_f32_e32 v101, v99, v99
	v_cvt_pk_bf16_f32 v245, v98, v99
	v_lshl_add_u64 v[98:99], v[96:97], 0, v[160:161]
	v_lshl_add_u64 v[252:253], v[98:99], 0, v[254:255]
	s_waitcnt vmcnt(2)
	v_mov_b64_e32 v[98:99], v[192:193]
	v_pk_mul_f32 v[112:113], v[150:151], v[104:105] op_sel_hi:[1,0]
	v_pk_mul_f32 v[110:111], v[152:153], v[104:105] op_sel_hi:[1,0]
	v_lshlrev_b32_e32 v108, 16, v98
	v_and_b32_e32 v109, 0xffff0000, v98
	v_lshlrev_b32_e32 v98, 16, v99
	v_and_b32_e32 v99, 0xffff0000, v99
	v_pk_mul_f32 v[108:109], v[112:113], v[108:109]
	v_pk_mul_f32 v[98:99], v[110:111], v[98:99]
	v_pk_fma_f32 v[92:93], v[92:93], v[102:103], v[108:109] op_sel_hi:[1,0,1]
	v_pk_fma_f32 v[94:95], v[94:95], v[102:103], v[98:99] op_sel_hi:[1,0,1]
	v_mul_f32_e32 v98, v93, v93
	v_fmac_f32_e32 v98, v92, v92
	v_fmac_f32_e32 v98, v94, v94
	v_fmac_f32_e32 v98, v95, v95
	v_cvt_pk_bf16_f32 v246, v92, v93
	v_cvt_pk_bf16_f32 v247, v94, v95
	v_lshl_add_u64 v[94:95], v[128:129], 1, v[96:97]
	s_nop 1
	v_permlane16_swap_b32_e32 v244, v246
	v_permlane16_swap_b32_e32 v245, v247
	global_store_dwordx4 v[252:253], v[244:247], off
	s_waitcnt vmcnt(2)
; __device__ __forceinline__ u32x2 pack4(f32x4 v) { u32x2 r; r.x = cvt_pk(v[0], v[1]); r.y = cvt_pk(v[2], v[3]); return r; }
; #define FOR_AI_M _Pragma("unroll") for (int ai = 0; ai < 2; ++ai) _Pragma("unroll") for (int m = 0; m < 4; ++m)
; #define FOR_BJ_N _Pragma("unroll") for (int bj = 0; bj < 2; ++bj) _Pragma("unroll") for (int n = 0; n < 2; ++n)
;     __device__ __forceinline__ void operator()(EPI_ARGS) const {
;     ...
;         FOR_AI_M {
;             const int row = u.pm * 256 + ai * 128 + wr * 64 + m * 16 + fr;
;             const float rb = rsqrtf(ssq_b[row] * (1.0f / 1024.0f) + EPS), ri = rinvx[row];
;             const int b = row >> 11, tp = row & 2047;
;             const bf16_t* hrow = XN + (size_t)row * 2048;
;             float ss = 0.f;
;             FOR_BJ_N { const int col = u.pn * 256 + bj * 128 + wc * 32 + n * 16 + 4 * fq;
;                 const f32x4 v = acc[ai][bj][m][n] * rb + unpack4(*(const u32x2*)(hrow + col)) * (ginv[bj][n] * ri);
;                 ss += v[0] * v[0] + v[1] * v[1] + v[2] * v[2] + v[3] * v[3];
;                 *(u32x2*)(XH + ((size_t)(b * XHB + tp + 2) * 2048 + col)) = pack4(v); }
;             ss += __shfl_xor(ss, 16); ss += __shfl_xor(ss, 32);
;             if (fq == 0) atomicAdd(ssq_h + b * XHB + tp + 2, ss);
;         }
	v_mov_b64_e32 v[92:93], v[194:195]
	v_pk_mul_f32 v[108:109], v[146:147], v[104:105] op_sel_hi:[1,0]
	v_add_f32_e32 v101, v101, v98
	v_pk_mul_f32 v[98:99], v[148:149], v[104:105] op_sel_hi:[1,0]
	v_lshlrev_b32_e32 v94, 16, v92
	v_and_b32_e32 v95, 0xffff0000, v92
	v_lshlrev_b32_e32 v92, 16, v93
	v_and_b32_e32 v93, 0xffff0000, v93
	v_pk_mul_f32 v[94:95], v[108:109], v[94:95]
	v_pk_mul_f32 v[92:93], v[98:99], v[92:93]
	v_pk_fma_f32 v[88:89], v[88:89], v[102:103], v[94:95] op_sel_hi:[1,0,1]
	v_pk_fma_f32 v[90:91], v[90:91], v[102:103], v[92:93] op_sel_hi:[1,0,1]
	v_mul_f32_e32 v92, v89, v89
	v_fmac_f32_e32 v92, v88, v88
	v_fmac_f32_e32 v92, v90, v90
	v_fmac_f32_e32 v92, v91, v91
	v_cvt_pk_bf16_f32 v248, v88, v89
	v_cvt_pk_bf16_f32 v249, v90, v91
	v_lshl_add_u64 v[90:91], v[124:125], 1, v[96:97]
	v_lshl_add_u64 v[252:253], v[90:91], 0, v[254:255]
	s_waitcnt vmcnt(1)
	v_mov_b64_e32 v[88:89], v[196:197]
	v_pk_mul_f32 v[94:95], v[2:3], v[104:105] op_sel_hi:[1,0]
	v_add_f32_e32 v98, v101, v92
	v_pk_mul_f32 v[92:93], v[144:145], v[104:105] op_sel_hi:[1,0]
	v_lshlrev_b32_e32 v90, 16, v88
	v_and_b32_e32 v91, 0xffff0000, v88
	v_lshlrev_b32_e32 v88, 16, v89
	v_and_b32_e32 v89, 0xffff0000, v89
	v_pk_mul_f32 v[90:91], v[94:95], v[90:91]
	v_pk_mul_f32 v[88:89], v[92:93], v[88:89]
	v_pk_fma_f32 v[84:85], v[84:85], v[102:103], v[90:91] op_sel_hi:[1,0,1]
	v_pk_fma_f32 v[86:87], v[86:87], v[102:103], v[88:89] op_sel_hi:[1,0,1]
	v_mul_f32_e32 v88, v85, v85
	v_fmac_f32_e32 v88, v84, v84
	v_fmac_f32_e32 v88, v86, v86
	v_fmac_f32_e32 v88, v87, v87
	v_add_f32_e32 v88, v98, v88
	v_cvt_pk_bf16_f32 v250, v84, v85
	v_cvt_pk_bf16_f32 v251, v86, v87
	v_lshl_add_u64 v[86:87], v[120:121], 1, v[96:97]
	s_nop 1
	v_permlane16_swap_b32_e32 v248, v250
	v_permlane16_swap_b32_e32 v249, v251
	global_store_dwordx4 v[252:253], v[248:251], off
	ds_bpermute_b32 v84, v1, v88
	s_waitcnt lgkmcnt(0)
	v_add_f32_e32 v84, v88, v84
	ds_bpermute_b32 v85, v119, v84
	s_and_saveexec_b64 s[6:7], vcc
	s_cbranch_execz .LBB0_986
	v_ashrrev_i32_e32 v101, 31, v100
	v_lshl_add_u64 v[86:87], v[100:101], 2, s[16:17]
	v_lshlrev_b32_e32 v88, 2, v103
	v_mov_b32_e32 v89, v0
	v_lshl_add_u64 v[86:87], v[86:87], 0, v[88:89]
	s_waitcnt lgkmcnt(0)
	v_add_f32_e32 v84, v84, v85
	global_atomic_add_f32 v[86:87], v84, off offset:8
.LBB0_986:
	s_or_b64 exec, exec, s[6:7]
	v_add_u32_e32 v84, 48, v158
	s_waitcnt lgkmcnt(0)
	v_ashrrev_i32_e32 v85, 31, v84
	v_lshlrev_b64 v[88:89], 2, v[84:85]
	v_lshl_add_u64 v[86:87], s[62:63], 0, v[88:89]
	global_load_dword v86, v[86:87], off
	v_lshl_add_u64 v[88:89], s[20:21], 0, v[88:89]
	global_load_dword v88, v[88:89], off
	v_ashrrev_i32_e32 v89, 11, v84
	s_waitcnt vmcnt(1)
	v_fmamk_f32 v86, v86, 0x3a800000, v175
	v_cmp_gt_f32_e64 s[42:43], s52, v86
	v_mul_f32_e32 v87, 0x4b800000, v86
	s_waitcnt vmcnt(0)
	v_pk_mul_f32 v[100:101], v[154:155], v[88:89] op_sel_hi:[1,0]
	v_cndmask_b32_e64 v86, v86, v87, s[42:43]
	v_rsq_f32_e32 v86, v86
	v_pk_mul_f32 v[98:99], v[156:157], v[88:89] op_sel_hi:[1,0]
	v_mul_f32_e32 v87, 0x45800000, v86
	v_cndmask_b32_e64 v86, v86, v87, s[42:43]
	v_and_b32_e32 v87, 0x7ff, v84
	v_lshlrev_b64 v[84:85], 12, v[84:85]
	v_lshl_add_u64 v[90:91], s[0:1], 0, v[84:85]
	v_lshl_add_u64 v[90:91], v[90:91], 0, v[160:161]
	global_load_dwordx2 v[94:95], v[90:91], off
	global_load_dwordx2 v[192:193], v[90:91], off offset:32
	global_load_dwordx2 v[194:195], v[90:91], off offset:256
	global_load_dwordx2 v[196:197], v[90:91], off offset:288
	v_mul_i32_i24_e32 v84, 0x802, v89
	v_add3_u32 v92, v87, v84, 2
	v_ashrrev_i32_e32 v93, 31, v92
	v_lshlrev_b64 v[92:93], 12, v[92:93]
	s_waitcnt vmcnt(3)
	v_lshlrev_b32_e32 v96, 16, v94
	v_and_b32_e32 v97, 0xffff0000, v94
	v_pk_mul_f32 v[96:97], v[100:101], v[96:97]
	v_lshlrev_b32_e32 v94, 16, v95
	v_and_b32_e32 v95, 0xffff0000, v95
	v_pk_fma_f32 v[80:81], v[80:81], v[86:87], v[96:97] op_sel_hi:[1,0,1]
	v_pk_mul_f32 v[94:95], v[98:99], v[94:95]
	v_mul_f32_e32 v85, v81, v81
	v_pk_fma_f32 v[82:83], v[82:83], v[86:87], v[94:95] op_sel_hi:[1,0,1]
	v_fmac_f32_e32 v85, v80, v80
	v_fmac_f32_e32 v85, v82, v82
	v_cvt_pk_bf16_f32 v244, v80, v81
	v_lshl_add_u64 v[80:81], s[14:15], 0, v[92:93]
	v_fmac_f32_e32 v85, v83, v83
	v_cvt_pk_bf16_f32 v245, v82, v83
	v_lshl_add_u64 v[82:83], v[80:81], 0, v[160:161]
	v_lshl_add_u64 v[252:253], v[82:83], 0, v[254:255]
	s_waitcnt vmcnt(2)
	v_mov_b64_e32 v[82:83], v[192:193]
	v_pk_mul_f32 v[96:97], v[150:151], v[88:89] op_sel_hi:[1,0]
	v_pk_mul_f32 v[94:95], v[152:153], v[88:89] op_sel_hi:[1,0]
	v_lshlrev_b32_e32 v92, 16, v82
	v_and_b32_e32 v93, 0xffff0000, v82
	v_lshlrev_b32_e32 v82, 16, v83
	v_and_b32_e32 v83, 0xffff0000, v83
	v_pk_mul_f32 v[92:93], v[96:97], v[92:93]
	v_pk_mul_f32 v[82:83], v[94:95], v[82:83]
	v_pk_fma_f32 v[76:77], v[76:77], v[86:87], v[92:93] op_sel_hi:[1,0,1]
	v_pk_fma_f32 v[78:79], v[78:79], v[86:87], v[82:83] op_sel_hi:[1,0,1]
	v_mul_f32_e32 v82, v77, v77
	v_fmac_f32_e32 v82, v76, v76
	v_fmac_f32_e32 v82, v78, v78
	v_fmac_f32_e32 v82, v79, v79
	v_cvt_pk_bf16_f32 v246, v76, v77
	v_cvt_pk_bf16_f32 v247, v78, v79
	v_lshl_add_u64 v[78:79], v[128:129], 1, v[80:81]
	s_nop 1
	v_permlane16_swap_b32_e32 v244, v246
	v_permlane16_swap_b32_e32 v245, v247
	global_store_dwordx4 v[252:253], v[244:247], off
	s_waitcnt vmcnt(2)
; __device__ __forceinline__ u32x2 pack4(f32x4 v) { u32x2 r; r.x = cvt_pk(v[0], v[1]); r.y = cvt_pk(v[2], v[3]); return r; }
; #define FOR_AI_M _Pragma("unroll") for (int ai = 0; ai < 2; ++ai) _Pragma("unroll") for (int m = 0; m < 4; ++m)
; #define FOR_BJ_N _Pragma("unroll") for (int bj = 0; bj < 2; ++bj) _Pragma("unroll") for (int n = 0; n < 2; ++n)
;     __device__ __forceinline__ void operator()(EPI_ARGS) const {
;     ...
;         FOR_AI_M {
;             const int row = u.pm * 256 + ai * 128 + wr * 64 + m * 16 + fr;
;             const float rb = rsqrtf(ssq_b[row] * (1.0f / 1024.0f) + EPS), ri = rinvx[row];
;             const int b = row >> 11, tp = row & 2047;
;             const bf16_t* hrow = XN + (size_t)row * 2048;
;             float ss = 0.f;
;             FOR_BJ_N { const int col = u.pn * 256 + bj * 128 + wc * 32 + n * 16 + 4 * fq;
;                 const f32x4 v = acc[ai][bj][m][n] * rb + unpack4(*(const u32x2*)(hrow + col)) * (ginv[bj][n] * ri);
;                 ss += v[0] * v[0] + v[1] * v[1] + v[2] * v[2] + v[3] * v[3];
;                 *(u32x2*)(XH + ((size_t)(b * XHB + tp + 2) * 2048 + col)) = pack4(v); }
;             ss += __shfl_xor(ss, 16); ss += __shfl_xor(ss, 32);
;             if (fq == 0) atomicAdd(ssq_h + b * XHB + tp + 2, ss);
;         }
	v_mov_b64_e32 v[76:77], v[194:195]
	v_pk_mul_f32 v[92:93], v[146:147], v[88:89] op_sel_hi:[1,0]
	v_add_f32_e32 v85, v85, v82
	v_pk_mul_f32 v[82:83], v[148:149], v[88:89] op_sel_hi:[1,0]
	v_lshlrev_b32_e32 v78, 16, v76
	v_and_b32_e32 v79, 0xffff0000, v76
	v_lshlrev_b32_e32 v76, 16, v77
	v_and_b32_e32 v77, 0xffff0000, v77
	v_pk_mul_f32 v[78:79], v[92:93], v[78:79]
	v_pk_mul_f32 v[76:77], v[82:83], v[76:77]
	v_pk_fma_f32 v[72:73], v[72:73], v[86:87], v[78:79] op_sel_hi:[1,0,1]
	v_pk_fma_f32 v[74:75], v[74:75], v[86:87], v[76:77] op_sel_hi:[1,0,1]
	v_mul_f32_e32 v76, v73, v73
	v_fmac_f32_e32 v76, v72, v72
	v_fmac_f32_e32 v76, v74, v74
	v_fmac_f32_e32 v76, v75, v75
	v_cvt_pk_bf16_f32 v248, v72, v73
	v_cvt_pk_bf16_f32 v249, v74, v75
	v_lshl_add_u64 v[74:75], v[124:125], 1, v[80:81]
	v_lshl_add_u64 v[252:253], v[74:75], 0, v[254:255]
	s_waitcnt vmcnt(1)
	v_mov_b64_e32 v[72:73], v[196:197]
	v_pk_mul_f32 v[78:79], v[2:3], v[88:89] op_sel_hi:[1,0]
	v_add_f32_e32 v82, v85, v76
	v_pk_mul_f32 v[76:77], v[144:145], v[88:89] op_sel_hi:[1,0]
	v_lshlrev_b32_e32 v74, 16, v72
	v_and_b32_e32 v75, 0xffff0000, v72
	v_lshlrev_b32_e32 v72, 16, v73
	v_and_b32_e32 v73, 0xffff0000, v73
	v_pk_mul_f32 v[74:75], v[78:79], v[74:75]
	v_pk_mul_f32 v[72:73], v[76:77], v[72:73]
	v_pk_fma_f32 v[68:69], v[68:69], v[86:87], v[74:75] op_sel_hi:[1,0,1]
	v_pk_fma_f32 v[70:71], v[70:71], v[86:87], v[72:73] op_sel_hi:[1,0,1]
	v_mul_f32_e32 v72, v69, v69
	v_fmac_f32_e32 v72, v68, v68
	v_fmac_f32_e32 v72, v70, v70
	v_fmac_f32_e32 v72, v71, v71
	v_add_f32_e32 v72, v82, v72
	v_cvt_pk_bf16_f32 v250, v68, v69
	v_cvt_pk_bf16_f32 v251, v70, v71
	v_lshl_add_u64 v[70:71], v[120:121], 1, v[80:81]
	s_nop 1
	v_permlane16_swap_b32_e32 v248, v250
	v_permlane16_swap_b32_e32 v249, v251
	global_store_dwordx4 v[252:253], v[248:251], off
	ds_bpermute_b32 v68, v1, v72
	s_waitcnt lgkmcnt(0)
	v_add_f32_e32 v68, v72, v68
	ds_bpermute_b32 v69, v119, v68
	s_and_saveexec_b64 s[6:7], vcc
	s_cbranch_execz .LBB0_988
	v_ashrrev_i32_e32 v85, 31, v84
	v_lshl_add_u64 v[70:71], v[84:85], 2, s[16:17]
	v_lshlrev_b32_e32 v72, 2, v87
	v_mov_b32_e32 v73, v0
	v_lshl_add_u64 v[70:71], v[70:71], 0, v[72:73]
	s_waitcnt lgkmcnt(0)
	v_add_f32_e32 v68, v68, v69
	global_atomic_add_f32 v[70:71], v68, off offset:8
.LBB0_988:
	s_or_b64 exec, exec, s[6:7]
	v_add_u32_e32 v68, 0x80, v158
	s_waitcnt lgkmcnt(0)
	v_ashrrev_i32_e32 v69, 31, v68
	v_lshlrev_b64 v[72:73], 2, v[68:69]
	v_lshl_add_u64 v[70:71], s[62:63], 0, v[72:73]
	global_load_dword v70, v[70:71], off
	v_lshl_add_u64 v[72:73], s[20:21], 0, v[72:73]
	global_load_dword v72, v[72:73], off
	v_ashrrev_i32_e32 v73, 11, v68
	s_waitcnt vmcnt(1)
	v_fmamk_f32 v70, v70, 0x3a800000, v175
	v_cmp_gt_f32_e64 s[42:43], s52, v70
	v_mul_f32_e32 v71, 0x4b800000, v70
	s_waitcnt vmcnt(0)
	v_pk_mul_f32 v[84:85], v[154:155], v[72:73] op_sel_hi:[1,0]
	v_cndmask_b32_e64 v70, v70, v71, s[42:43]
	v_rsq_f32_e32 v70, v70
	v_pk_mul_f32 v[82:83], v[156:157], v[72:73] op_sel_hi:[1,0]
	v_mul_f32_e32 v71, 0x45800000, v70
	v_cndmask_b32_e64 v70, v70, v71, s[42:43]
	v_and_b32_e32 v71, 0x7ff, v68
	v_lshlrev_b64 v[68:69], 12, v[68:69]
	v_lshl_add_u64 v[74:75], s[0:1], 0, v[68:69]
	v_lshl_add_u64 v[74:75], v[74:75], 0, v[160:161]
	global_load_dwordx2 v[78:79], v[74:75], off
	global_load_dwordx2 v[192:193], v[74:75], off offset:32
	global_load_dwordx2 v[194:195], v[74:75], off offset:256
	global_load_dwordx2 v[196:197], v[74:75], off offset:288
	v_mul_i32_i24_e32 v68, 0x802, v73
	v_add3_u32 v76, v71, v68, 2
	v_ashrrev_i32_e32 v77, 31, v76
	v_lshlrev_b64 v[76:77], 12, v[76:77]
	s_waitcnt vmcnt(3)
	v_lshlrev_b32_e32 v80, 16, v78
	v_and_b32_e32 v81, 0xffff0000, v78
	v_pk_mul_f32 v[80:81], v[84:85], v[80:81]
	v_lshlrev_b32_e32 v78, 16, v79
	v_and_b32_e32 v79, 0xffff0000, v79
	v_pk_fma_f32 v[64:65], v[64:65], v[70:71], v[80:81] op_sel_hi:[1,0,1]
	v_pk_mul_f32 v[78:79], v[82:83], v[78:79]
	v_mul_f32_e32 v69, v65, v65
	v_pk_fma_f32 v[66:67], v[66:67], v[70:71], v[78:79] op_sel_hi:[1,0,1]
	v_fmac_f32_e32 v69, v64, v64
	v_fmac_f32_e32 v69, v66, v66
	v_cvt_pk_bf16_f32 v244, v64, v65
	v_lshl_add_u64 v[64:65], s[14:15], 0, v[76:77]
	v_fmac_f32_e32 v69, v67, v67
	v_cvt_pk_bf16_f32 v245, v66, v67
	v_lshl_add_u64 v[66:67], v[64:65], 0, v[160:161]
	v_lshl_add_u64 v[252:253], v[66:67], 0, v[254:255]
	s_waitcnt vmcnt(2)
	v_mov_b64_e32 v[66:67], v[192:193]
	v_pk_mul_f32 v[80:81], v[150:151], v[72:73] op_sel_hi:[1,0]
	v_pk_mul_f32 v[78:79], v[152:153], v[72:73] op_sel_hi:[1,0]
	v_lshlrev_b32_e32 v76, 16, v66
	v_and_b32_e32 v77, 0xffff0000, v66
	v_lshlrev_b32_e32 v66, 16, v67
	v_and_b32_e32 v67, 0xffff0000, v67
	v_pk_mul_f32 v[76:77], v[80:81], v[76:77]
	v_pk_mul_f32 v[66:67], v[78:79], v[66:67]
	v_pk_fma_f32 v[60:61], v[60:61], v[70:71], v[76:77] op_sel_hi:[1,0,1]
	v_pk_fma_f32 v[62:63], v[62:63], v[70:71], v[66:67] op_sel_hi:[1,0,1]
	v_mul_f32_e32 v66, v61, v61
	v_fmac_f32_e32 v66, v60, v60
	v_fmac_f32_e32 v66, v62, v62
	v_fmac_f32_e32 v66, v63, v63
	v_cvt_pk_bf16_f32 v246, v60, v61
	v_cvt_pk_bf16_f32 v247, v62, v63
	v_lshl_add_u64 v[62:63], v[128:129], 1, v[64:65]
	s_nop 1
	v_permlane16_swap_b32_e32 v244, v246
	v_permlane16_swap_b32_e32 v245, v247
	global_store_dwordx4 v[252:253], v[244:247], off
	s_waitcnt vmcnt(2)
; __device__ __forceinline__ u32x2 pack4(f32x4 v) { u32x2 r; r.x = cvt_pk(v[0], v[1]); r.y = cvt_pk(v[2], v[3]); return r; }
; #define FOR_AI_M _Pragma("unroll") for (int ai = 0; ai < 2; ++ai) _Pragma("unroll") for (int m = 0; m < 4; ++m)
; #define FOR_BJ_N _Pragma("unroll") for (int bj = 0; bj < 2; ++bj) _Pragma("unroll") for (int n = 0; n < 2; ++n)
;     __device__ __forceinline__ void operator()(EPI_ARGS) const {
;     ...
;         FOR_AI_M {
;             const int row = u.pm * 256 + ai * 128 + wr * 64 + m * 16 + fr;
;             const float rb = rsqrtf(ssq_b[row] * (1.0f / 1024.0f) + EPS), ri = rinvx[row];
;             const int b = row >> 11, tp = row & 2047;
;             const bf16_t* hrow = XN + (size_t)row * 2048;
;             float ss = 0.f;
;             FOR_BJ_N { const int col = u.pn * 256 + bj * 128 + wc * 32 + n * 16 + 4 * fq;
;                 const f32x4 v = acc[ai][bj][m][n] * rb + unpack4(*(const u32x2*)(hrow + col)) * (ginv[bj][n] * ri);
;                 ss += v[0] * v[0] + v[1] * v[1] + v[2] * v[2] + v[3] * v[3];
;                 *(u32x2*)(XH + ((size_t)(b * XHB + tp + 2) * 2048 + col)) = pack4(v); }
;             ss += __shfl_xor(ss, 16); ss += __shfl_xor(ss, 32);
;             if (fq == 0) atomicAdd(ssq_h + b * XHB + tp + 2, ss);
;         }
	v_mov_b64_e32 v[60:61], v[194:195]
	v_pk_mul_f32 v[76:77], v[146:147], v[72:73] op_sel_hi:[1,0]
	v_add_f32_e32 v69, v69, v66
	v_pk_mul_f32 v[66:67], v[148:149], v[72:73] op_sel_hi:[1,0]
	v_lshlrev_b32_e32 v62, 16, v60
	v_and_b32_e32 v63, 0xffff0000, v60
	v_lshlrev_b32_e32 v60, 16, v61
	v_and_b32_e32 v61, 0xffff0000, v61
	v_pk_mul_f32 v[62:63], v[76:77], v[62:63]
	v_pk_mul_f32 v[60:61], v[66:67], v[60:61]
	v_pk_fma_f32 v[56:57], v[56:57], v[70:71], v[62:63] op_sel_hi:[1,0,1]
	v_pk_fma_f32 v[58:59], v[58:59], v[70:71], v[60:61] op_sel_hi:[1,0,1]
	v_mul_f32_e32 v60, v57, v57
	v_fmac_f32_e32 v60, v56, v56
	v_fmac_f32_e32 v60, v58, v58
	v_fmac_f32_e32 v60, v59, v59
	v_cvt_pk_bf16_f32 v248, v56, v57
	v_cvt_pk_bf16_f32 v249, v58, v59
	v_lshl_add_u64 v[58:59], v[124:125], 1, v[64:65]
	v_lshl_add_u64 v[252:253], v[58:59], 0, v[254:255]
	s_waitcnt vmcnt(1)
	v_mov_b64_e32 v[56:57], v[196:197]
	v_pk_mul_f32 v[62:63], v[2:3], v[72:73] op_sel_hi:[1,0]
	v_add_f32_e32 v66, v69, v60
	v_pk_mul_f32 v[60:61], v[144:145], v[72:73] op_sel_hi:[1,0]
	v_lshlrev_b32_e32 v58, 16, v56
	v_and_b32_e32 v59, 0xffff0000, v56
	v_lshlrev_b32_e32 v56, 16, v57
	v_and_b32_e32 v57, 0xffff0000, v57
	v_pk_mul_f32 v[58:59], v[62:63], v[58:59]
	v_pk_mul_f32 v[56:57], v[60:61], v[56:57]
	v_pk_fma_f32 v[52:53], v[52:53], v[70:71], v[58:59] op_sel_hi:[1,0,1]
	v_pk_fma_f32 v[54:55], v[54:55], v[70:71], v[56:57] op_sel_hi:[1,0,1]
	v_mul_f32_e32 v56, v53, v53
	v_fmac_f32_e32 v56, v52, v52
	v_fmac_f32_e32 v56, v54, v54
	v_fmac_f32_e32 v56, v55, v55
	v_add_f32_e32 v56, v66, v56
	v_cvt_pk_bf16_f32 v250, v52, v53
	v_cvt_pk_bf16_f32 v251, v54, v55
	v_lshl_add_u64 v[54:55], v[120:121], 1, v[64:65]
	s_nop 1
	v_permlane16_swap_b32_e32 v248, v250
	v_permlane16_swap_b32_e32 v249, v251
	global_store_dwordx4 v[252:253], v[248:251], off
	ds_bpermute_b32 v52, v1, v56
	s_waitcnt lgkmcnt(0)
	v_add_f32_e32 v52, v56, v52
	ds_bpermute_b32 v53, v119, v52
	s_and_saveexec_b64 s[6:7], vcc
	s_cbranch_execz .LBB0_990
	v_ashrrev_i32_e32 v69, 31, v68
	v_lshl_add_u64 v[54:55], v[68:69], 2, s[16:17]
	v_lshlrev_b32_e32 v56, 2, v71
	v_mov_b32_e32 v57, v0
	v_lshl_add_u64 v[54:55], v[54:55], 0, v[56:57]
	s_waitcnt lgkmcnt(0)
	v_add_f32_e32 v52, v52, v53
	global_atomic_add_f32 v[54:55], v52, off offset:8
.LBB0_990:
	s_or_b64 exec, exec, s[6:7]
	v_add_u32_e32 v52, 0x90, v158
	s_waitcnt lgkmcnt(0)
	v_ashrrev_i32_e32 v53, 31, v52
	v_lshlrev_b64 v[56:57], 2, v[52:53]
	v_lshl_add_u64 v[54:55], s[62:63], 0, v[56:57]
	global_load_dword v54, v[54:55], off
	v_lshl_add_u64 v[56:57], s[20:21], 0, v[56:57]
	global_load_dword v56, v[56:57], off
	v_ashrrev_i32_e32 v57, 11, v52
	s_waitcnt vmcnt(1)
	v_fmamk_f32 v54, v54, 0x3a800000, v175
	v_cmp_gt_f32_e64 s[42:43], s52, v54
	v_mul_f32_e32 v55, 0x4b800000, v54
	s_waitcnt vmcnt(0)
	v_pk_mul_f32 v[68:69], v[154:155], v[56:57] op_sel_hi:[1,0]
	v_cndmask_b32_e64 v54, v54, v55, s[42:43]
	v_rsq_f32_e32 v54, v54
	v_pk_mul_f32 v[66:67], v[156:157], v[56:57] op_sel_hi:[1,0]
	v_mul_f32_e32 v55, 0x45800000, v54
	v_cndmask_b32_e64 v54, v54, v55, s[42:43]
	v_and_b32_e32 v55, 0x7ff, v52
	v_lshlrev_b64 v[52:53], 12, v[52:53]
	v_lshl_add_u64 v[58:59], s[0:1], 0, v[52:53]
	v_lshl_add_u64 v[58:59], v[58:59], 0, v[160:161]
	global_load_dwordx2 v[62:63], v[58:59], off
	global_load_dwordx2 v[192:193], v[58:59], off offset:32
	global_load_dwordx2 v[194:195], v[58:59], off offset:256
	global_load_dwordx2 v[196:197], v[58:59], off offset:288
	v_mul_i32_i24_e32 v52, 0x802, v57
	v_add3_u32 v60, v55, v52, 2
	v_ashrrev_i32_e32 v61, 31, v60
	v_lshlrev_b64 v[60:61], 12, v[60:61]
	s_waitcnt vmcnt(3)
	v_lshlrev_b32_e32 v64, 16, v62
	v_and_b32_e32 v65, 0xffff0000, v62
	v_pk_mul_f32 v[64:65], v[68:69], v[64:65]
	v_lshlrev_b32_e32 v62, 16, v63
	v_and_b32_e32 v63, 0xffff0000, v63
	v_pk_fma_f32 v[48:49], v[48:49], v[54:55], v[64:65] op_sel_hi:[1,0,1]
	v_pk_mul_f32 v[62:63], v[66:67], v[62:63]
	v_mul_f32_e32 v53, v49, v49
	v_pk_fma_f32 v[50:51], v[50:51], v[54:55], v[62:63] op_sel_hi:[1,0,1]
	v_fmac_f32_e32 v53, v48, v48
	v_fmac_f32_e32 v53, v50, v50
	v_cvt_pk_bf16_f32 v244, v48, v49
	v_lshl_add_u64 v[48:49], s[14:15], 0, v[60:61]
	v_fmac_f32_e32 v53, v51, v51
	v_cvt_pk_bf16_f32 v245, v50, v51
	v_lshl_add_u64 v[50:51], v[48:49], 0, v[160:161]
	v_lshl_add_u64 v[252:253], v[50:51], 0, v[254:255]
	s_waitcnt vmcnt(2)
	v_mov_b64_e32 v[50:51], v[192:193]
	v_pk_mul_f32 v[64:65], v[150:151], v[56:57] op_sel_hi:[1,0]
	v_pk_mul_f32 v[62:63], v[152:153], v[56:57] op_sel_hi:[1,0]
	v_lshlrev_b32_e32 v60, 16, v50
	v_and_b32_e32 v61, 0xffff0000, v50
	v_lshlrev_b32_e32 v50, 16, v51
	v_and_b32_e32 v51, 0xffff0000, v51
	v_pk_mul_f32 v[60:61], v[64:65], v[60:61]
	v_pk_mul_f32 v[50:51], v[62:63], v[50:51]
	v_pk_fma_f32 v[44:45], v[44:45], v[54:55], v[60:61] op_sel_hi:[1,0,1]
	v_pk_fma_f32 v[46:47], v[46:47], v[54:55], v[50:51] op_sel_hi:[1,0,1]
	v_mul_f32_e32 v50, v45, v45
	v_fmac_f32_e32 v50, v44, v44
	v_fmac_f32_e32 v50, v46, v46
	v_fmac_f32_e32 v50, v47, v47
	v_cvt_pk_bf16_f32 v246, v44, v45
	v_cvt_pk_bf16_f32 v247, v46, v47
	v_lshl_add_u64 v[46:47], v[128:129], 1, v[48:49]
	s_nop 1
	v_permlane16_swap_b32_e32 v244, v246
	v_permlane16_swap_b32_e32 v245, v247
	global_store_dwordx4 v[252:253], v[244:247], off
	s_waitcnt vmcnt(2)
; __device__ __forceinline__ u32x2 pack4(f32x4 v) { u32x2 r; r.x = cvt_pk(v[0], v[1]); r.y = cvt_pk(v[2], v[3]); return r; }
; #define FOR_AI_M _Pragma("unroll") for (int ai = 0; ai < 2; ++ai) _Pragma("unroll") for (int m = 0; m < 4; ++m)
; #define FOR_BJ_N _Pragma("unroll") for (int bj = 0; bj < 2; ++bj) _Pragma("unroll") for (int n = 0; n < 2; ++n)
;     __device__ __forceinline__ void operator()(EPI_ARGS) const {
;     ...
;         FOR_AI_M {
;             const int row = u.pm * 256 + ai * 128 + wr * 64 + m * 16 + fr;
;             const float rb = rsqrtf(ssq_b[row] * (1.0f / 1024.0f) + EPS), ri = rinvx[row];
;             const int b = row >> 11, tp = row & 2047;
;             const bf16_t* hrow = XN + (size_t)row * 2048;
;             float ss = 0.f;
;             FOR_BJ_N { const int col = u.pn * 256 + bj * 128 + wc * 32 + n * 16 + 4 * fq;
;                 const f32x4 v = acc[ai][bj][m][n] * rb + unpack4(*(const u32x2*)(hrow + col)) * (ginv[bj][n] * ri);
;                 ss += v[0] * v[0] + v[1] * v[1] + v[2] * v[2] + v[3] * v[3];
;                 *(u32x2*)(XH + ((size_t)(b * XHB + tp + 2) * 2048 + col)) = pack4(v); }
;             ss += __shfl_xor(ss, 16); ss += __shfl_xor(ss, 32);
;             if (fq == 0) atomicAdd(ssq_h + b * XHB + tp + 2, ss);
;         }
	v_mov_b64_e32 v[44:45], v[194:195]
	v_pk_mul_f32 v[60:61], v[146:147], v[56:57] op_sel_hi:[1,0]
	v_add_f32_e32 v53, v53, v50
	v_pk_mul_f32 v[50:51], v[148:149], v[56:57] op_sel_hi:[1,0]
	v_lshlrev_b32_e32 v46, 16, v44
	v_and_b32_e32 v47, 0xffff0000, v44
	v_lshlrev_b32_e32 v44, 16, v45
	v_and_b32_e32 v45, 0xffff0000, v45
	v_pk_mul_f32 v[46:47], v[60:61], v[46:47]
	v_pk_mul_f32 v[44:45], v[50:51], v[44:45]
	v_pk_fma_f32 v[40:41], v[40:41], v[54:55], v[46:47] op_sel_hi:[1,0,1]
	v_pk_fma_f32 v[42:43], v[42:43], v[54:55], v[44:45] op_sel_hi:[1,0,1]
	v_mul_f32_e32 v44, v41, v41
	v_fmac_f32_e32 v44, v40, v40
	v_fmac_f32_e32 v44, v42, v42
	v_fmac_f32_e32 v44, v43, v43
	v_cvt_pk_bf16_f32 v248, v40, v41
	v_cvt_pk_bf16_f32 v249, v42, v43
	v_lshl_add_u64 v[42:43], v[124:125], 1, v[48:49]
	v_lshl_add_u64 v[252:253], v[42:43], 0, v[254:255]
	s_waitcnt vmcnt(1)
	v_mov_b64_e32 v[40:41], v[196:197]
	v_pk_mul_f32 v[46:47], v[2:3], v[56:57] op_sel_hi:[1,0]
	v_add_f32_e32 v50, v53, v44
	v_pk_mul_f32 v[44:45], v[144:145], v[56:57] op_sel_hi:[1,0]
	v_lshlrev_b32_e32 v42, 16, v40
	v_and_b32_e32 v43, 0xffff0000, v40
	v_lshlrev_b32_e32 v40, 16, v41
	v_and_b32_e32 v41, 0xffff0000, v41
	v_pk_mul_f32 v[42:43], v[46:47], v[42:43]
	v_pk_mul_f32 v[40:41], v[44:45], v[40:41]
	v_pk_fma_f32 v[36:37], v[36:37], v[54:55], v[42:43] op_sel_hi:[1,0,1]
	v_pk_fma_f32 v[38:39], v[38:39], v[54:55], v[40:41] op_sel_hi:[1,0,1]
	v_mul_f32_e32 v40, v37, v37
	v_fmac_f32_e32 v40, v36, v36
	v_fmac_f32_e32 v40, v38, v38
	v_fmac_f32_e32 v40, v39, v39
	v_add_f32_e32 v40, v50, v40
	v_cvt_pk_bf16_f32 v250, v36, v37
	v_cvt_pk_bf16_f32 v251, v38, v39
	v_lshl_add_u64 v[38:39], v[120:121], 1, v[48:49]
	s_nop 1
	v_permlane16_swap_b32_e32 v248, v250
	v_permlane16_swap_b32_e32 v249, v251
	global_store_dwordx4 v[252:253], v[248:251], off
	ds_bpermute_b32 v36, v1, v40
	s_waitcnt lgkmcnt(0)
	v_add_f32_e32 v36, v40, v36
	ds_bpermute_b32 v37, v119, v36
	s_and_saveexec_b64 s[6:7], vcc
	s_cbranch_execz .LBB0_992
	v_ashrrev_i32_e32 v53, 31, v52
	v_lshl_add_u64 v[38:39], v[52:53], 2, s[16:17]
	v_lshlrev_b32_e32 v40, 2, v55
	v_mov_b32_e32 v41, v0
	v_lshl_add_u64 v[38:39], v[38:39], 0, v[40:41]
	s_waitcnt lgkmcnt(0)
	v_add_f32_e32 v36, v36, v37
	global_atomic_add_f32 v[38:39], v36, off offset:8
; __device__ __forceinline__ u32x2 pack4(f32x4 v) { u32x2 r; r.x = cvt_pk(v[0], v[1]); r.y = cvt_pk(v[2], v[3]); return r; }
; #define FOR_AI_M _Pragma("unroll") for (int ai = 0; ai < 2; ++ai) _Pragma("unroll") for (int m = 0; m < 4; ++m)
; #define FOR_BJ_N _Pragma("unroll") for (int bj = 0; bj < 2; ++bj) _Pragma("unroll") for (int n = 0; n < 2; ++n)
;     __device__ __forceinline__ void operator()(EPI_ARGS) const {
;     ...
;         FOR_AI_M {
;             const int row = u.pm * 256 + ai * 128 + wr * 64 + m * 16 + fr;
;             const float rb = rsqrtf(ssq_b[row] * (1.0f / 1024.0f) + EPS), ri = rinvx[row];
;             const int b = row >> 11, tp = row & 2047;
;             const bf16_t* hrow = XN + (size_t)row * 2048;
;             float ss = 0.f;
;             FOR_BJ_N { const int col = u.pn * 256 + bj * 128 + wc * 32 + n * 16 + 4 * fq;
;                 const f32x4 v = acc[ai][bj][m][n] * rb + unpack4(*(const u32x2*)(hrow + col)) * (ginv[bj][n] * ri);
;                 ss += v[0] * v[0] + v[1] * v[1] + v[2] * v[2] + v[3] * v[3];
;                 *(u32x2*)(XH + ((size_t)(b * XHB + tp + 2) * 2048 + col)) = pack4(v); }
;             ss += __shfl_xor(ss, 16); ss += __shfl_xor(ss, 32);
;             if (fq == 0) atomicAdd(ssq_h + b * XHB + tp + 2, ss);
;         }
.LBB0_992:
	s_or_b64 exec, exec, s[6:7]
	v_add_u32_e32 v36, 0xa0, v158
	s_waitcnt lgkmcnt(0)
	v_ashrrev_i32_e32 v37, 31, v36
	v_lshlrev_b64 v[40:41], 2, v[36:37]
	v_lshl_add_u64 v[38:39], s[62:63], 0, v[40:41]
	global_load_dword v38, v[38:39], off
	v_lshl_add_u64 v[40:41], s[20:21], 0, v[40:41]
	global_load_dword v40, v[40:41], off
	v_ashrrev_i32_e32 v41, 11, v36
	s_waitcnt vmcnt(1)
	v_fmamk_f32 v38, v38, 0x3a800000, v175
	v_cmp_gt_f32_e64 s[42:43], s52, v38
	v_mul_f32_e32 v39, 0x4b800000, v38
	s_waitcnt vmcnt(0)
	v_pk_mul_f32 v[52:53], v[154:155], v[40:41] op_sel_hi:[1,0]
	v_cndmask_b32_e64 v38, v38, v39, s[42:43]
	v_rsq_f32_e32 v38, v38
	v_pk_mul_f32 v[50:51], v[156:157], v[40:41] op_sel_hi:[1,0]
	v_mul_f32_e32 v39, 0x45800000, v38
	v_cndmask_b32_e64 v38, v38, v39, s[42:43]
	v_and_b32_e32 v39, 0x7ff, v36
	v_lshlrev_b64 v[36:37], 12, v[36:37]
	v_lshl_add_u64 v[42:43], s[0:1], 0, v[36:37]
	v_lshl_add_u64 v[42:43], v[42:43], 0, v[160:161]
	global_load_dwordx2 v[46:47], v[42:43], off
	global_load_dwordx2 v[192:193], v[42:43], off offset:32
	global_load_dwordx2 v[194:195], v[42:43], off offset:256
	global_load_dwordx2 v[196:197], v[42:43], off offset:288
	v_mul_i32_i24_e32 v36, 0x802, v41
	v_add3_u32 v44, v39, v36, 2
	v_ashrrev_i32_e32 v45, 31, v44
	v_lshlrev_b64 v[44:45], 12, v[44:45]
	s_waitcnt vmcnt(3)
	v_lshlrev_b32_e32 v48, 16, v46
	v_and_b32_e32 v49, 0xffff0000, v46
	v_pk_mul_f32 v[48:49], v[52:53], v[48:49]
	v_lshlrev_b32_e32 v46, 16, v47
	v_and_b32_e32 v47, 0xffff0000, v47
	v_pk_fma_f32 v[32:33], v[32:33], v[38:39], v[48:49] op_sel_hi:[1,0,1]
	v_pk_mul_f32 v[46:47], v[50:51], v[46:47]
	v_mul_f32_e32 v37, v33, v33
	v_pk_fma_f32 v[34:35], v[34:35], v[38:39], v[46:47] op_sel_hi:[1,0,1]
	v_fmac_f32_e32 v37, v32, v32
	v_fmac_f32_e32 v37, v34, v34
	v_cvt_pk_bf16_f32 v244, v32, v33
	v_lshl_add_u64 v[32:33], s[14:15], 0, v[44:45]
	v_fmac_f32_e32 v37, v35, v35
	v_cvt_pk_bf16_f32 v245, v34, v35
	v_lshl_add_u64 v[34:35], v[32:33], 0, v[160:161]
	v_lshl_add_u64 v[252:253], v[34:35], 0, v[254:255]
	s_waitcnt vmcnt(2)
	v_mov_b64_e32 v[34:35], v[192:193]
	v_pk_mul_f32 v[48:49], v[150:151], v[40:41] op_sel_hi:[1,0]
	v_pk_mul_f32 v[46:47], v[152:153], v[40:41] op_sel_hi:[1,0]
	v_lshlrev_b32_e32 v44, 16, v34
	v_and_b32_e32 v45, 0xffff0000, v34
	v_lshlrev_b32_e32 v34, 16, v35
	v_and_b32_e32 v35, 0xffff0000, v35
	v_pk_mul_f32 v[44:45], v[48:49], v[44:45]
	v_pk_mul_f32 v[34:35], v[46:47], v[34:35]
	v_pk_fma_f32 v[28:29], v[28:29], v[38:39], v[44:45] op_sel_hi:[1,0,1]
	v_pk_fma_f32 v[30:31], v[30:31], v[38:39], v[34:35] op_sel_hi:[1,0,1]
	v_mul_f32_e32 v34, v29, v29
	v_fmac_f32_e32 v34, v28, v28
	v_fmac_f32_e32 v34, v30, v30
	v_fmac_f32_e32 v34, v31, v31
	v_cvt_pk_bf16_f32 v246, v28, v29
	v_cvt_pk_bf16_f32 v247, v30, v31
	v_lshl_add_u64 v[30:31], v[128:129], 1, v[32:33]
	s_nop 1
	v_permlane16_swap_b32_e32 v244, v246
	v_permlane16_swap_b32_e32 v245, v247
	global_store_dwordx4 v[252:253], v[244:247], off
	s_waitcnt vmcnt(2)
	v_mov_b64_e32 v[28:29], v[194:195]
	v_pk_mul_f32 v[44:45], v[146:147], v[40:41] op_sel_hi:[1,0]
	v_add_f32_e32 v37, v37, v34
	v_pk_mul_f32 v[34:35], v[148:149], v[40:41] op_sel_hi:[1,0]
	v_lshlrev_b32_e32 v30, 16, v28
	v_and_b32_e32 v31, 0xffff0000, v28
	v_lshlrev_b32_e32 v28, 16, v29
	v_and_b32_e32 v29, 0xffff0000, v29
	v_pk_mul_f32 v[30:31], v[44:45], v[30:31]
	v_pk_mul_f32 v[28:29], v[34:35], v[28:29]
	v_pk_fma_f32 v[24:25], v[24:25], v[38:39], v[30:31] op_sel_hi:[1,0,1]
	v_pk_fma_f32 v[26:27], v[26:27], v[38:39], v[28:29] op_sel_hi:[1,0,1]
	v_mul_f32_e32 v28, v25, v25
	v_fmac_f32_e32 v28, v24, v24
	v_fmac_f32_e32 v28, v26, v26
	v_fmac_f32_e32 v28, v27, v27
	v_cvt_pk_bf16_f32 v248, v24, v25
	v_cvt_pk_bf16_f32 v249, v26, v27
	v_lshl_add_u64 v[26:27], v[124:125], 1, v[32:33]
	v_lshl_add_u64 v[252:253], v[26:27], 0, v[254:255]
	s_waitcnt vmcnt(1)
	v_mov_b64_e32 v[24:25], v[196:197]
	v_pk_mul_f32 v[30:31], v[2:3], v[40:41] op_sel_hi:[1,0]
	v_add_f32_e32 v34, v37, v28
	v_pk_mul_f32 v[28:29], v[144:145], v[40:41] op_sel_hi:[1,0]
	v_lshlrev_b32_e32 v26, 16, v24
	v_and_b32_e32 v27, 0xffff0000, v24
	v_lshlrev_b32_e32 v24, 16, v25
	v_and_b32_e32 v25, 0xffff0000, v25
	v_pk_mul_f32 v[26:27], v[30:31], v[26:27]
	v_pk_mul_f32 v[24:25], v[28:29], v[24:25]
	v_pk_fma_f32 v[20:21], v[20:21], v[38:39], v[26:27] op_sel_hi:[1,0,1]
	v_pk_fma_f32 v[22:23], v[22:23], v[38:39], v[24:25] op_sel_hi:[1,0,1]
	v_mul_f32_e32 v24, v21, v21
	v_fmac_f32_e32 v24, v20, v20
	v_fmac_f32_e32 v24, v22, v22
	v_fmac_f32_e32 v24, v23, v23
	v_add_f32_e32 v24, v34, v24
	v_cvt_pk_bf16_f32 v250, v20, v21
	v_cvt_pk_bf16_f32 v251, v22, v23
	v_lshl_add_u64 v[22:23], v[120:121], 1, v[32:33]
	s_nop 1
	v_permlane16_swap_b32_e32 v248, v250
	v_permlane16_swap_b32_e32 v249, v251
	global_store_dwordx4 v[252:253], v[248:251], off
	ds_bpermute_b32 v20, v1, v24
	s_waitcnt lgkmcnt(0)
	v_add_f32_e32 v20, v24, v20
	ds_bpermute_b32 v21, v119, v20
	s_and_saveexec_b64 s[6:7], vcc
	s_cbranch_execz .LBB0_994
	v_ashrrev_i32_e32 v37, 31, v36
	v_lshl_add_u64 v[22:23], v[36:37], 2, s[16:17]
	v_lshlrev_b32_e32 v24, 2, v39
	v_mov_b32_e32 v25, v0
	v_lshl_add_u64 v[22:23], v[22:23], 0, v[24:25]
	s_waitcnt lgkmcnt(0)
	v_add_f32_e32 v20, v20, v21
	global_atomic_add_f32 v[22:23], v20, off offset:8

; #define FOR_AI_M _Pragma("unroll") for (int ai = 0; ai < 2; ++ai) _Pragma("unroll") for (int m = 0; m < 4; ++m)
; #define FOR_BJ_N _Pragma("unroll") for (int bj = 0; bj < 2; ++bj) _Pragma("unroll") for (int n = 0; n < 2; ++n)
;     __device__ __forceinline__ void operator()(EPI_ARGS) const {
;         FOR_AI_M {
;             const int row = u.pm * 256 + ai * 128 + wr * 64 + m * 16 + fr; float ss = 0.f;
;             const bf16_t* hrow = XH + (size_t)((row >> 11) * XHB + (row & 2047) + 2) * 2048;
;             FOR_BJ_N { const int col = u.pn * 256 + bj * 128 + wc * 32 + n * 16 + 4 * fq;
;                 const f32x4 v = unpack4(*(const u32x2*)(hrow + col)) + acc[ai][bj][m][n]; acc[ai][bj][m][n] = v;
;                 ss += v[0] * v[0] + v[1] * v[1] + v[2] * v[2] + v[3] * v[3]; }
;             ss += __shfl_xor(ss, 16); ss += __shfl_xor(ss, 32);
;             if (fq == 0) __hip_atomic_fetch_add(ssq_o + row, ss, __ATOMIC_RELAXED, __HIP_MEMORY_SCOPE_AGENT);
;         }
.LBB0_1306:
	v_and_b32_e32 v141, 64, v181
	v_mov_b32_e32 v136, v171
	v_mov_b32_e32 v137, v173
	s_mov_b32 s6, s28
	s_mov_b32 s7, s37
	v_xor_b32_e32 v139, 16, v181
	v_add_u32_e32 v142, 64, v141
	v_cmp_lt_i32_e32 vcc, v139, v142
	s_lshl_b32 s8, s26, 8
	s_lshl_b32 s6, s6, 6
	v_cndmask_b32_e32 v139, v181, v139, vcc
	s_add_i32 s6, s6, s8
	v_lshlrev_b32_e32 v141, 2, v139
	v_xor_b32_e32 v139, 32, v181
	v_add_u32_e32 v138, s6, v136
	v_cmp_lt_i32_e32 vcc, v139, v142
	v_lshlrev_b32_e32 v140, 2, v137
	s_lshl_b32 s6, s7, 5
	v_cndmask_b32_e32 v139, v181, v139, vcc
	v_cmp_eq_u32_e32 vcc, 0, v137
	v_ashrrev_i32_e32 v137, 11, v138
	v_lshlrev_b32_e32 v183, 2, v139
	v_mul_i32_i24_e32 v137, 0x802, v137
	v_and_b32_e32 v139, 0x7ff, v138
	v_add3_u32 v142, v139, v137, 2
	s_add_i32 s7, s6, s43
	v_ashrrev_i32_e32 v143, 31, v142
	v_add_u32_e32 v136, s7, v140
	v_lshlrev_b64 v[142:143], 12, v[142:143]
	v_lshl_add_u64 v[142:143], s[14:15], 0, v[142:143]
	v_ashrrev_i32_e32 v137, 31, v136
	v_lshl_add_u64 v[142:143], v[136:137], 1, v[142:143]
	global_load_dwordx2 v[144:145], v[142:143], off
	global_load_dwordx2 v[184:185], v[142:143], off offset:32
	global_load_dwordx2 v[186:187], v[142:143], off offset:256
	global_load_dwordx2 v[188:189], v[142:143], off offset:288
	s_waitcnt vmcnt(3)
	v_lshlrev_b32_e32 v146, 16, v144
	v_and_b32_e32 v147, 0xffff0000, v144
	v_lshlrev_b32_e32 v144, 16, v145
	v_and_b32_e32 v145, 0xffff0000, v145
	v_pk_add_f32 v[126:127], v[126:127], v[144:145]
	s_waitcnt vmcnt(2)
	v_mov_b64_e32 v[144:145], v[184:185]
	v_pk_add_f32 v[124:125], v[124:125], v[146:147]
	v_lshlrev_b32_e32 v146, 16, v144
	v_and_b32_e32 v147, 0xffff0000, v144
	v_lshlrev_b32_e32 v144, 16, v145
	v_and_b32_e32 v145, 0xffff0000, v145
	v_pk_add_f32 v[120:121], v[120:121], v[146:147]
	v_mul_f32_e32 v139, v125, v125
	v_pk_add_f32 v[122:123], v[122:123], v[144:145]
	v_mul_f32_e32 v144, v121, v121
	v_fmac_f32_e32 v139, v124, v124
	v_fmac_f32_e32 v144, v120, v120
	v_fmac_f32_e32 v139, v126, v126
	v_fmac_f32_e32 v144, v122, v122
	v_fmac_f32_e32 v139, v127, v127
	v_fmac_f32_e32 v144, v123, v123
	v_add_f32_e32 v139, v139, v144
	s_waitcnt vmcnt(1)
	v_mov_b64_e32 v[144:145], v[186:187]
	v_lshlrev_b32_e32 v146, 16, v144
	s_waitcnt vmcnt(0)
	v_mov_b64_e32 v[142:143], v[188:189]
	v_and_b32_e32 v147, 0xffff0000, v144
	v_lshlrev_b32_e32 v144, 16, v145
	v_and_b32_e32 v145, 0xffff0000, v145
	v_pk_add_f32 v[116:117], v[116:117], v[146:147]
	v_pk_add_f32 v[118:119], v[118:119], v[144:145]
	v_mul_f32_e32 v144, v117, v117
	v_fmac_f32_e32 v144, v116, v116
	v_fmac_f32_e32 v144, v118, v118
	v_fmac_f32_e32 v144, v119, v119
	v_add_f32_e32 v139, v139, v144
	v_lshlrev_b32_e32 v144, 16, v142
	v_and_b32_e32 v145, 0xffff0000, v142
	v_lshlrev_b32_e32 v142, 16, v143
	v_and_b32_e32 v143, 0xffff0000, v143
	v_pk_add_f32 v[114:115], v[114:115], v[142:143]
	v_pk_add_f32 v[142:143], v[112:113], v[144:145]
	s_nop 0
	v_mul_f32_e32 v112, v143, v143
	v_fmac_f32_e32 v112, v142, v142
	v_fmac_f32_e32 v112, v114, v114
	v_fmac_f32_e32 v112, v115, v115
	v_add_f32_e32 v112, v139, v112
	ds_bpermute_b32 v113, v141, v112
	v_ashrrev_i32_e32 v139, 31, v138
	s_waitcnt lgkmcnt(0)
	v_add_f32_e32 v112, v112, v113
	ds_bpermute_b32 v113, v183, v112
	s_and_saveexec_b64 s[8:9], vcc
	s_cbranch_execz .LBB0_1308
	v_lshl_add_u64 v[144:145], v[138:139], 2, s[4:5]
	s_waitcnt lgkmcnt(0)
	v_add_f32_e32 v112, v112, v113
	global_atomic_add_f32 v[144:145], v112, off
.LBB0_1308:
	s_or_b64 exec, exec, s[8:9]
	v_add_u32_e32 v112, 16, v138
	s_waitcnt lgkmcnt(0)
	v_ashrrev_i32_e32 v113, 11, v112
	v_mul_i32_i24_e32 v113, 0x802, v113
	v_and_b32_e32 v144, 0x7ff, v112
	v_add3_u32 v144, v144, v113, 2
	v_ashrrev_i32_e32 v145, 31, v144
	v_lshlrev_b64 v[144:145], 12, v[144:145]
	v_lshl_add_u64 v[144:145], s[14:15], 0, v[144:145]
	v_lshl_add_u64 v[144:145], v[136:137], 1, v[144:145]
	global_load_dwordx2 v[146:147], v[144:145], off
	global_load_dwordx2 v[184:185], v[144:145], off offset:32
	global_load_dwordx2 v[186:187], v[144:145], off offset:256
	global_load_dwordx2 v[188:189], v[144:145], off offset:288
	s_waitcnt vmcnt(3)
	v_lshlrev_b32_e32 v148, 16, v146
	v_and_b32_e32 v149, 0xffff0000, v146
	v_lshlrev_b32_e32 v146, 16, v147
	v_and_b32_e32 v147, 0xffff0000, v147
	v_pk_add_f32 v[110:111], v[110:111], v[146:147]
	s_waitcnt vmcnt(2)
	v_mov_b64_e32 v[146:147], v[184:185]
	v_pk_add_f32 v[108:109], v[108:109], v[148:149]
	v_lshlrev_b32_e32 v148, 16, v146
	v_and_b32_e32 v149, 0xffff0000, v146
	v_lshlrev_b32_e32 v146, 16, v147
	v_and_b32_e32 v147, 0xffff0000, v147
	v_pk_add_f32 v[104:105], v[104:105], v[148:149]
	v_mul_f32_e32 v113, v109, v109
	v_pk_add_f32 v[106:107], v[106:107], v[146:147]
	v_mul_f32_e32 v146, v105, v105
	v_fmac_f32_e32 v113, v108, v108
	v_fmac_f32_e32 v146, v104, v104
	v_fmac_f32_e32 v113, v110, v110
	v_fmac_f32_e32 v146, v106, v106
	v_fmac_f32_e32 v113, v111, v111
	v_fmac_f32_e32 v146, v107, v107
	v_add_f32_e32 v113, v113, v146
	s_waitcnt vmcnt(1)
	v_mov_b64_e32 v[146:147], v[186:187]
	v_lshlrev_b32_e32 v148, 16, v146
	s_waitcnt vmcnt(0)
	v_mov_b64_e32 v[144:145], v[188:189]
	v_and_b32_e32 v149, 0xffff0000, v146
	v_lshlrev_b32_e32 v146, 16, v147
	v_and_b32_e32 v147, 0xffff0000, v147
	v_pk_add_f32 v[100:101], v[100:101], v[148:149]
	v_pk_add_f32 v[102:103], v[102:103], v[146:147]
	v_mul_f32_e32 v146, v101, v101
	v_fmac_f32_e32 v146, v100, v100
	v_fmac_f32_e32 v146, v102, v102
	v_fmac_f32_e32 v146, v103, v103
	v_add_f32_e32 v113, v113, v146
	v_lshlrev_b32_e32 v146, 16, v144
	v_and_b32_e32 v147, 0xffff0000, v144
	v_lshlrev_b32_e32 v144, 16, v145
	v_and_b32_e32 v145, 0xffff0000, v145
	v_pk_add_f32 v[98:99], v[98:99], v[144:145]
	v_pk_add_f32 v[144:145], v[96:97], v[146:147]
	s_nop 0
	v_mul_f32_e32 v96, v145, v145
	v_fmac_f32_e32 v96, v144, v144
	v_fmac_f32_e32 v96, v98, v98
	v_fmac_f32_e32 v96, v99, v99
	v_add_f32_e32 v96, v113, v96
	ds_bpermute_b32 v97, v141, v96
	v_ashrrev_i32_e32 v113, 31, v112
	s_waitcnt lgkmcnt(0)
	v_add_f32_e32 v96, v96, v97
	ds_bpermute_b32 v97, v183, v96
	s_and_saveexec_b64 s[8:9], vcc
	s_cbranch_execz .LBB0_1310
	v_lshl_add_u64 v[146:147], v[112:113], 2, s[4:5]
	s_waitcnt lgkmcnt(0)
	v_add_f32_e32 v96, v96, v97
	global_atomic_add_f32 v[146:147], v96, off
; #define FOR_AI_M _Pragma("unroll") for (int ai = 0; ai < 2; ++ai) _Pragma("unroll") for (int m = 0; m < 4; ++m)
; #define FOR_BJ_N _Pragma("unroll") for (int bj = 0; bj < 2; ++bj) _Pragma("unroll") for (int n = 0; n < 2; ++n)
;     __device__ __forceinline__ void operator()(EPI_ARGS) const {
;         FOR_AI_M {
;             const int row = u.pm * 256 + ai * 128 + wr * 64 + m * 16 + fr; float ss = 0.f;
;             const bf16_t* hrow = XH + (size_t)((row >> 11) * XHB + (row & 2047) + 2) * 2048;
;             FOR_BJ_N { const int col = u.pn * 256 + bj * 128 + wc * 32 + n * 16 + 4 * fq;
;                 const f32x4 v = unpack4(*(const u32x2*)(hrow + col)) + acc[ai][bj][m][n]; acc[ai][bj][m][n] = v;
;                 ss += v[0] * v[0] + v[1] * v[1] + v[2] * v[2] + v[3] * v[3]; }
;             ss += __shfl_xor(ss, 16); ss += __shfl_xor(ss, 32);
;             if (fq == 0) __hip_atomic_fetch_add(ssq_o + row, ss, __ATOMIC_RELAXED, __HIP_MEMORY_SCOPE_AGENT);
;         }
.LBB0_1310:
	s_or_b64 exec, exec, s[8:9]
	v_add_u32_e32 v96, 32, v138
	s_waitcnt lgkmcnt(0)
	v_ashrrev_i32_e32 v97, 11, v96
	v_mul_i32_i24_e32 v97, 0x802, v97
	v_and_b32_e32 v146, 0x7ff, v96
	v_add3_u32 v146, v146, v97, 2
	v_ashrrev_i32_e32 v147, 31, v146
	v_lshlrev_b64 v[146:147], 12, v[146:147]
	v_lshl_add_u64 v[146:147], s[14:15], 0, v[146:147]
	v_lshl_add_u64 v[146:147], v[136:137], 1, v[146:147]
	global_load_dwordx2 v[148:149], v[146:147], off
	global_load_dwordx2 v[184:185], v[146:147], off offset:32
	global_load_dwordx2 v[186:187], v[146:147], off offset:256
	global_load_dwordx2 v[188:189], v[146:147], off offset:288
	s_waitcnt vmcnt(3)
	v_lshlrev_b32_e32 v150, 16, v148
	v_and_b32_e32 v151, 0xffff0000, v148
	v_lshlrev_b32_e32 v148, 16, v149
	v_and_b32_e32 v149, 0xffff0000, v149
	v_pk_add_f32 v[94:95], v[94:95], v[148:149]
	s_waitcnt vmcnt(2)
	v_mov_b64_e32 v[148:149], v[184:185]
	v_pk_add_f32 v[92:93], v[92:93], v[150:151]
	v_lshlrev_b32_e32 v150, 16, v148
	v_and_b32_e32 v151, 0xffff0000, v148
	v_lshlrev_b32_e32 v148, 16, v149
	v_and_b32_e32 v149, 0xffff0000, v149
	v_pk_add_f32 v[88:89], v[88:89], v[150:151]
	v_mul_f32_e32 v97, v93, v93
	v_pk_add_f32 v[90:91], v[90:91], v[148:149]
	v_mul_f32_e32 v148, v89, v89
	v_fmac_f32_e32 v97, v92, v92
	v_fmac_f32_e32 v148, v88, v88
	v_fmac_f32_e32 v97, v94, v94
	v_fmac_f32_e32 v148, v90, v90
	v_fmac_f32_e32 v97, v95, v95
	v_fmac_f32_e32 v148, v91, v91
	v_add_f32_e32 v97, v97, v148
	s_waitcnt vmcnt(1)
	v_mov_b64_e32 v[148:149], v[186:187]
	v_lshlrev_b32_e32 v150, 16, v148
	s_waitcnt vmcnt(0)
	v_mov_b64_e32 v[146:147], v[188:189]
	v_and_b32_e32 v151, 0xffff0000, v148
	v_lshlrev_b32_e32 v148, 16, v149
	v_and_b32_e32 v149, 0xffff0000, v149
	v_pk_add_f32 v[84:85], v[84:85], v[150:151]
	v_pk_add_f32 v[86:87], v[86:87], v[148:149]
	v_mul_f32_e32 v148, v85, v85
	v_fmac_f32_e32 v148, v84, v84
	v_fmac_f32_e32 v148, v86, v86
	v_fmac_f32_e32 v148, v87, v87
	v_add_f32_e32 v97, v97, v148
	v_lshlrev_b32_e32 v148, 16, v146
	v_and_b32_e32 v149, 0xffff0000, v146
	v_lshlrev_b32_e32 v146, 16, v147
	v_and_b32_e32 v147, 0xffff0000, v147
	v_pk_add_f32 v[82:83], v[82:83], v[146:147]
	v_pk_add_f32 v[146:147], v[80:81], v[148:149]
	s_nop 0
	v_mul_f32_e32 v80, v147, v147
	v_fmac_f32_e32 v80, v146, v146
	v_fmac_f32_e32 v80, v82, v82
	v_fmac_f32_e32 v80, v83, v83
	v_add_f32_e32 v80, v97, v80
	ds_bpermute_b32 v81, v141, v80
	v_ashrrev_i32_e32 v97, 31, v96
	s_waitcnt lgkmcnt(0)
	v_add_f32_e32 v80, v80, v81
	ds_bpermute_b32 v81, v183, v80
	s_and_saveexec_b64 s[8:9], vcc
	s_cbranch_execz .LBB0_1312
	v_lshl_add_u64 v[148:149], v[96:97], 2, s[4:5]
	s_waitcnt lgkmcnt(0)
	v_add_f32_e32 v80, v80, v81
	global_atomic_add_f32 v[148:149], v80, off
.LBB0_1312:
	s_or_b64 exec, exec, s[8:9]
	v_add_u32_e32 v80, 48, v138
	s_waitcnt lgkmcnt(0)
	v_ashrrev_i32_e32 v81, 11, v80
	v_mul_i32_i24_e32 v81, 0x802, v81
	v_and_b32_e32 v148, 0x7ff, v80
	v_add3_u32 v148, v148, v81, 2
	v_ashrrev_i32_e32 v149, 31, v148
	v_lshlrev_b64 v[148:149], 12, v[148:149]
	v_lshl_add_u64 v[148:149], s[14:15], 0, v[148:149]
	v_lshl_add_u64 v[148:149], v[136:137], 1, v[148:149]
	global_load_dwordx2 v[150:151], v[148:149], off
	global_load_dwordx2 v[184:185], v[148:149], off offset:32
	global_load_dwordx2 v[186:187], v[148:149], off offset:256
	global_load_dwordx2 v[188:189], v[148:149], off offset:288
	s_waitcnt vmcnt(3)
	v_lshlrev_b32_e32 v152, 16, v150
	v_and_b32_e32 v153, 0xffff0000, v150
	v_lshlrev_b32_e32 v150, 16, v151
	v_and_b32_e32 v151, 0xffff0000, v151
	v_pk_add_f32 v[78:79], v[78:79], v[150:151]
	s_waitcnt vmcnt(2)
	v_mov_b64_e32 v[150:151], v[184:185]
	v_pk_add_f32 v[76:77], v[76:77], v[152:153]
	v_lshlrev_b32_e32 v152, 16, v150
	v_and_b32_e32 v153, 0xffff0000, v150
	v_lshlrev_b32_e32 v150, 16, v151
	v_and_b32_e32 v151, 0xffff0000, v151
	v_pk_add_f32 v[72:73], v[72:73], v[152:153]
	v_mul_f32_e32 v81, v77, v77
	v_pk_add_f32 v[74:75], v[74:75], v[150:151]
	v_mul_f32_e32 v150, v73, v73
	v_fmac_f32_e32 v81, v76, v76
	v_fmac_f32_e32 v150, v72, v72
	v_fmac_f32_e32 v81, v78, v78
	v_fmac_f32_e32 v150, v74, v74
	v_fmac_f32_e32 v81, v79, v79
	v_fmac_f32_e32 v150, v75, v75
	v_add_f32_e32 v81, v81, v150
	s_waitcnt vmcnt(1)
	v_mov_b64_e32 v[150:151], v[186:187]
	v_lshlrev_b32_e32 v152, 16, v150
	s_waitcnt vmcnt(0)
	v_mov_b64_e32 v[148:149], v[188:189]
	v_and_b32_e32 v153, 0xffff0000, v150
	v_lshlrev_b32_e32 v150, 16, v151
	v_and_b32_e32 v151, 0xffff0000, v151
	v_pk_add_f32 v[68:69], v[68:69], v[152:153]
	v_pk_add_f32 v[70:71], v[70:71], v[150:151]
	v_mul_f32_e32 v150, v69, v69
	v_fmac_f32_e32 v150, v68, v68
	v_fmac_f32_e32 v150, v70, v70
	v_fmac_f32_e32 v150, v71, v71
	v_add_f32_e32 v81, v81, v150
	v_lshlrev_b32_e32 v150, 16, v148
	v_and_b32_e32 v151, 0xffff0000, v148
	v_lshlrev_b32_e32 v148, 16, v149
	v_and_b32_e32 v149, 0xffff0000, v149
	v_pk_add_f32 v[66:67], v[66:67], v[148:149]
	v_pk_add_f32 v[148:149], v[64:65], v[150:151]
	s_nop 0
	v_mul_f32_e32 v64, v149, v149
	v_fmac_f32_e32 v64, v148, v148
	v_fmac_f32_e32 v64, v66, v66
	v_fmac_f32_e32 v64, v67, v67
	v_add_f32_e32 v64, v81, v64
	ds_bpermute_b32 v65, v141, v64
	v_ashrrev_i32_e32 v81, 31, v80
	s_waitcnt lgkmcnt(0)
	v_add_f32_e32 v64, v64, v65
	ds_bpermute_b32 v65, v183, v64
	s_and_saveexec_b64 s[8:9], vcc
	s_cbranch_execz .LBB0_1314
	v_lshl_add_u64 v[150:151], v[80:81], 2, s[4:5]
	s_waitcnt lgkmcnt(0)
	v_add_f32_e32 v64, v64, v65
	global_atomic_add_f32 v[150:151], v64, off
; #define FOR_AI_M _Pragma("unroll") for (int ai = 0; ai < 2; ++ai) _Pragma("unroll") for (int m = 0; m < 4; ++m)
; #define FOR_BJ_N _Pragma("unroll") for (int bj = 0; bj < 2; ++bj) _Pragma("unroll") for (int n = 0; n < 2; ++n)
;     __device__ __forceinline__ void operator()(EPI_ARGS) const {
;         FOR_AI_M {
;             const int row = u.pm * 256 + ai * 128 + wr * 64 + m * 16 + fr; float ss = 0.f;
;             const bf16_t* hrow = XH + (size_t)((row >> 11) * XHB + (row & 2047) + 2) * 2048;
;             FOR_BJ_N { const int col = u.pn * 256 + bj * 128 + wc * 32 + n * 16 + 4 * fq;
;                 const f32x4 v = unpack4(*(const u32x2*)(hrow + col)) + acc[ai][bj][m][n]; acc[ai][bj][m][n] = v;
;                 ss += v[0] * v[0] + v[1] * v[1] + v[2] * v[2] + v[3] * v[3]; }
;             ss += __shfl_xor(ss, 16); ss += __shfl_xor(ss, 32);
;             if (fq == 0) __hip_atomic_fetch_add(ssq_o + row, ss, __ATOMIC_RELAXED, __HIP_MEMORY_SCOPE_AGENT);
;         }
.LBB0_1314:
	s_or_b64 exec, exec, s[8:9]
	v_add_u32_e32 v64, 0x80, v138
	s_waitcnt lgkmcnt(0)
	v_ashrrev_i32_e32 v65, 11, v64
	v_mul_i32_i24_e32 v65, 0x802, v65
	v_and_b32_e32 v150, 0x7ff, v64
	v_add3_u32 v150, v150, v65, 2
	v_ashrrev_i32_e32 v151, 31, v150
	v_lshlrev_b64 v[150:151], 12, v[150:151]
	v_lshl_add_u64 v[150:151], s[14:15], 0, v[150:151]
	v_lshl_add_u64 v[150:151], v[136:137], 1, v[150:151]
	global_load_dwordx2 v[152:153], v[150:151], off
	global_load_dwordx2 v[184:185], v[150:151], off offset:32
	global_load_dwordx2 v[186:187], v[150:151], off offset:256
	global_load_dwordx2 v[188:189], v[150:151], off offset:288
	s_waitcnt vmcnt(3)
	v_lshlrev_b32_e32 v154, 16, v152
	v_and_b32_e32 v155, 0xffff0000, v152
	v_lshlrev_b32_e32 v152, 16, v153
	v_and_b32_e32 v153, 0xffff0000, v153
	v_pk_add_f32 v[62:63], v[62:63], v[152:153]
	s_waitcnt vmcnt(2)
	v_mov_b64_e32 v[152:153], v[184:185]
	v_pk_add_f32 v[60:61], v[60:61], v[154:155]
	v_lshlrev_b32_e32 v154, 16, v152
	v_and_b32_e32 v155, 0xffff0000, v152
	v_lshlrev_b32_e32 v152, 16, v153
	v_and_b32_e32 v153, 0xffff0000, v153
	v_pk_add_f32 v[56:57], v[56:57], v[154:155]
	v_mul_f32_e32 v65, v61, v61
	v_pk_add_f32 v[58:59], v[58:59], v[152:153]
	v_mul_f32_e32 v152, v57, v57
	v_fmac_f32_e32 v65, v60, v60
	v_fmac_f32_e32 v152, v56, v56
	v_fmac_f32_e32 v65, v62, v62
	v_fmac_f32_e32 v152, v58, v58
	v_fmac_f32_e32 v65, v63, v63
	v_fmac_f32_e32 v152, v59, v59
	v_add_f32_e32 v65, v65, v152
	s_waitcnt vmcnt(1)
	v_mov_b64_e32 v[152:153], v[186:187]
	v_lshlrev_b32_e32 v154, 16, v152
	s_waitcnt vmcnt(0)
	v_mov_b64_e32 v[150:151], v[188:189]
	v_and_b32_e32 v155, 0xffff0000, v152
	v_lshlrev_b32_e32 v152, 16, v153
	v_and_b32_e32 v153, 0xffff0000, v153
	v_pk_add_f32 v[52:53], v[52:53], v[154:155]
	v_pk_add_f32 v[54:55], v[54:55], v[152:153]
	v_mul_f32_e32 v152, v53, v53
	v_fmac_f32_e32 v152, v52, v52
	v_fmac_f32_e32 v152, v54, v54
	v_fmac_f32_e32 v152, v55, v55
	v_add_f32_e32 v65, v65, v152
	v_lshlrev_b32_e32 v154, 16, v150
	v_and_b32_e32 v155, 0xffff0000, v150
	v_pk_add_f32 v[154:155], v[48:49], v[154:155]
	v_lshlrev_b32_e32 v150, 16, v151
	v_and_b32_e32 v151, 0xffff0000, v151
	v_mul_f32_e32 v48, v155, v155
	v_pk_add_f32 v[152:153], v[50:51], v[150:151]
	v_fmac_f32_e32 v48, v154, v154
	v_fmac_f32_e32 v48, v152, v152
	v_fmac_f32_e32 v48, v153, v153
	v_add_f32_e32 v48, v65, v48
	ds_bpermute_b32 v49, v141, v48
	v_ashrrev_i32_e32 v65, 31, v64
	s_waitcnt lgkmcnt(0)
	v_add_f32_e32 v48, v48, v49
	ds_bpermute_b32 v49, v183, v48
	s_and_saveexec_b64 s[8:9], vcc
	s_cbranch_execz .LBB0_1316
	v_lshl_add_u64 v[50:51], v[64:65], 2, s[4:5]
	s_waitcnt lgkmcnt(0)
	v_add_f32_e32 v48, v48, v49
	global_atomic_add_f32 v[50:51], v48, off
.LBB0_1316:
	s_or_b64 exec, exec, s[8:9]
	v_add_u32_e32 v48, 0x90, v138
	s_waitcnt lgkmcnt(0)
	v_ashrrev_i32_e32 v49, 11, v48
	v_mul_i32_i24_e32 v49, 0x802, v49
	v_and_b32_e32 v50, 0x7ff, v48
	v_add3_u32 v50, v50, v49, 2
	v_ashrrev_i32_e32 v51, 31, v50
	v_lshlrev_b64 v[50:51], 12, v[50:51]
	v_lshl_add_u64 v[50:51], s[14:15], 0, v[50:51]
	v_lshl_add_u64 v[50:51], v[136:137], 1, v[50:51]
	global_load_dwordx2 v[150:151], v[50:51], off
	global_load_dwordx2 v[184:185], v[50:51], off offset:32
	global_load_dwordx2 v[186:187], v[50:51], off offset:256
	global_load_dwordx2 v[188:189], v[50:51], off offset:288
	s_waitcnt vmcnt(3)
	v_lshlrev_b32_e32 v156, 16, v150
	v_and_b32_e32 v157, 0xffff0000, v150
	v_lshlrev_b32_e32 v150, 16, v151
	v_and_b32_e32 v151, 0xffff0000, v151
	v_pk_add_f32 v[46:47], v[46:47], v[150:151]
	s_waitcnt vmcnt(2)
	v_mov_b64_e32 v[150:151], v[184:185]
	v_pk_add_f32 v[44:45], v[44:45], v[156:157]
	v_lshlrev_b32_e32 v156, 16, v150
	v_and_b32_e32 v157, 0xffff0000, v150
	v_lshlrev_b32_e32 v150, 16, v151
	v_and_b32_e32 v151, 0xffff0000, v151
	v_pk_add_f32 v[40:41], v[40:41], v[156:157]
	v_mul_f32_e32 v49, v45, v45
	v_pk_add_f32 v[42:43], v[42:43], v[150:151]
	v_mul_f32_e32 v150, v41, v41
	v_fmac_f32_e32 v49, v44, v44
	v_fmac_f32_e32 v150, v40, v40
	v_fmac_f32_e32 v49, v46, v46
	v_fmac_f32_e32 v150, v42, v42
	v_fmac_f32_e32 v49, v47, v47
	v_fmac_f32_e32 v150, v43, v43
	v_add_f32_e32 v49, v49, v150
	s_waitcnt vmcnt(1)
	v_mov_b64_e32 v[150:151], v[186:187]
	v_lshlrev_b32_e32 v156, 16, v150
	s_waitcnt vmcnt(0)
	v_mov_b64_e32 v[50:51], v[188:189]
	v_and_b32_e32 v157, 0xffff0000, v150
	v_lshlrev_b32_e32 v150, 16, v151
	v_and_b32_e32 v151, 0xffff0000, v151
	v_pk_add_f32 v[36:37], v[36:37], v[156:157]
	v_pk_add_f32 v[38:39], v[38:39], v[150:151]
	v_mul_f32_e32 v150, v37, v37
	v_fmac_f32_e32 v150, v36, v36
	v_fmac_f32_e32 v150, v38, v38
	v_fmac_f32_e32 v150, v39, v39
	v_add_f32_e32 v49, v49, v150
	v_lshlrev_b32_e32 v150, 16, v50
	v_and_b32_e32 v151, 0xffff0000, v50
	v_pk_add_f32 v[162:163], v[32:33], v[150:151]
	v_lshlrev_b32_e32 v50, 16, v51
	v_and_b32_e32 v51, 0xffff0000, v51
	v_mul_f32_e32 v32, v163, v163
	v_pk_add_f32 v[160:161], v[34:35], v[50:51]
	v_fmac_f32_e32 v32, v162, v162
	v_fmac_f32_e32 v32, v160, v160
	v_fmac_f32_e32 v32, v161, v161
	v_add_f32_e32 v32, v49, v32
	ds_bpermute_b32 v33, v141, v32
	v_ashrrev_i32_e32 v49, 31, v48
	s_waitcnt lgkmcnt(0)
	v_add_f32_e32 v32, v32, v33
	ds_bpermute_b32 v33, v183, v32
	s_and_saveexec_b64 s[8:9], vcc
	s_cbranch_execz .LBB0_1318
	v_lshl_add_u64 v[34:35], v[48:49], 2, s[4:5]
	s_waitcnt lgkmcnt(0)
	v_add_f32_e32 v32, v32, v33
	global_atomic_add_f32 v[34:35], v32, off
; #define FOR_AI_M _Pragma("unroll") for (int ai = 0; ai < 2; ++ai) _Pragma("unroll") for (int m = 0; m < 4; ++m)
; #define FOR_BJ_N _Pragma("unroll") for (int bj = 0; bj < 2; ++bj) _Pragma("unroll") for (int n = 0; n < 2; ++n)
;     __device__ __forceinline__ void operator()(EPI_ARGS) const {
;         FOR_AI_M {
;             const int row = u.pm * 256 + ai * 128 + wr * 64 + m * 16 + fr; float ss = 0.f;
;             const bf16_t* hrow = XH + (size_t)((row >> 11) * XHB + (row & 2047) + 2) * 2048;
;             FOR_BJ_N { const int col = u.pn * 256 + bj * 128 + wc * 32 + n * 16 + 4 * fq;
;                 const f32x4 v = unpack4(*(const u32x2*)(hrow + col)) + acc[ai][bj][m][n]; acc[ai][bj][m][n] = v;
;                 ss += v[0] * v[0] + v[1] * v[1] + v[2] * v[2] + v[3] * v[3]; }
;             ss += __shfl_xor(ss, 16); ss += __shfl_xor(ss, 32);
;             if (fq == 0) __hip_atomic_fetch_add(ssq_o + row, ss, __ATOMIC_RELAXED, __HIP_MEMORY_SCOPE_AGENT);
;         }
.LBB0_1318:
	s_or_b64 exec, exec, s[8:9]
	v_add_u32_e32 v32, 0xa0, v138
	s_waitcnt lgkmcnt(0)
	v_ashrrev_i32_e32 v33, 11, v32
	v_mul_i32_i24_e32 v33, 0x802, v33
	v_and_b32_e32 v34, 0x7ff, v32
	v_add3_u32 v34, v34, v33, 2
	v_ashrrev_i32_e32 v35, 31, v34
	v_lshlrev_b64 v[34:35], 12, v[34:35]
	v_lshl_add_u64 v[34:35], s[14:15], 0, v[34:35]
	v_lshl_add_u64 v[34:35], v[136:137], 1, v[34:35]
	global_load_dwordx2 v[50:51], v[34:35], off
	global_load_dwordx2 v[184:185], v[34:35], off offset:32
	global_load_dwordx2 v[186:187], v[34:35], off offset:256
	global_load_dwordx2 v[188:189], v[34:35], off offset:288
	s_waitcnt vmcnt(3)
	v_lshlrev_b32_e32 v150, 16, v50
	v_and_b32_e32 v151, 0xffff0000, v50
	v_lshlrev_b32_e32 v50, 16, v51
	v_and_b32_e32 v51, 0xffff0000, v51
	v_pk_add_f32 v[30:31], v[30:31], v[50:51]
	s_waitcnt vmcnt(2)
	v_mov_b64_e32 v[50:51], v[184:185]
	v_pk_add_f32 v[28:29], v[28:29], v[150:151]
	v_lshlrev_b32_e32 v150, 16, v50
	v_and_b32_e32 v151, 0xffff0000, v50
	v_lshlrev_b32_e32 v50, 16, v51
	v_and_b32_e32 v51, 0xffff0000, v51
	v_pk_add_f32 v[24:25], v[24:25], v[150:151]
	v_mul_f32_e32 v33, v29, v29
	v_pk_add_f32 v[26:27], v[26:27], v[50:51]
	v_mul_f32_e32 v50, v25, v25
	v_fmac_f32_e32 v33, v28, v28
	v_fmac_f32_e32 v50, v24, v24
	v_fmac_f32_e32 v33, v30, v30
	v_fmac_f32_e32 v50, v26, v26
	v_fmac_f32_e32 v33, v31, v31
	v_fmac_f32_e32 v50, v27, v27
	v_add_f32_e32 v33, v33, v50
	s_waitcnt vmcnt(1)
	v_mov_b64_e32 v[50:51], v[186:187]
	v_lshlrev_b32_e32 v150, 16, v50
	v_and_b32_e32 v151, 0xffff0000, v50
	v_lshlrev_b32_e32 v50, 16, v51
	v_and_b32_e32 v51, 0xffff0000, v51
	v_pk_add_f32 v[22:23], v[22:23], v[50:51]
	v_pk_add_f32 v[50:51], v[20:21], v[150:151]
	s_nop 0
	v_mul_f32_e32 v20, v51, v51
	v_fmac_f32_e32 v20, v50, v50
	v_fmac_f32_e32 v20, v22, v22
	v_fmac_f32_e32 v20, v23, v23
	v_add_f32_e32 v33, v33, v20
	s_waitcnt vmcnt(0)
	v_mov_b64_e32 v[20:21], v[188:189]
	v_lshlrev_b32_e32 v34, 16, v20
	v_and_b32_e32 v35, 0xffff0000, v20
	v_pk_add_f32 v[166:167], v[16:17], v[34:35]
	v_lshlrev_b32_e32 v20, 16, v21
	v_and_b32_e32 v21, 0xffff0000, v21
	v_mul_f32_e32 v16, v167, v167
	v_pk_add_f32 v[164:165], v[18:19], v[20:21]
	v_fmac_f32_e32 v16, v166, v166
	v_fmac_f32_e32 v16, v164, v164
	v_fmac_f32_e32 v16, v165, v165
	v_add_f32_e32 v16, v33, v16
	ds_bpermute_b32 v17, v141, v16
	v_ashrrev_i32_e32 v33, 31, v32
	s_waitcnt lgkmcnt(0)
	v_add_f32_e32 v16, v16, v17
	ds_bpermute_b32 v17, v183, v16
	s_and_saveexec_b64 s[8:9], vcc
	s_cbranch_execz .LBB0_1320
	v_lshl_add_u64 v[18:19], v[32:33], 2, s[4:5]
	s_waitcnt lgkmcnt(0)
	v_add_f32_e32 v16, v16, v17
	global_atomic_add_f32 v[18:19], v16, off
.LBB0_1320:
	s_or_b64 exec, exec, s[8:9]
	v_add_u32_e32 v16, 0xb0, v138
	s_waitcnt lgkmcnt(0)
	v_ashrrev_i32_e32 v17, 11, v16
	v_mul_i32_i24_e32 v17, 0x802, v17
	v_and_b32_e32 v18, 0x7ff, v16
	v_add3_u32 v18, v18, v17, 2
	v_ashrrev_i32_e32 v19, 31, v18
	v_lshlrev_b64 v[18:19], 12, v[18:19]
	v_lshl_add_u64 v[18:19], s[14:15], 0, v[18:19]
	v_lshl_add_u64 v[168:169], v[136:137], 1, v[18:19]
	global_load_dwordx2 v[18:19], v[168:169], off
	global_load_dwordx2 v[184:185], v[168:169], off offset:32
	global_load_dwordx2 v[186:187], v[168:169], off offset:256
	global_load_dwordx2 v[188:189], v[168:169], off offset:288
	s_waitcnt vmcnt(3)
	v_lshlrev_b32_e32 v20, 16, v18
	v_and_b32_e32 v21, 0xffff0000, v18
	v_pk_add_f32 v[20:21], v[12:13], v[20:21]
	s_waitcnt vmcnt(2)
	v_mov_b64_e32 v[12:13], v[184:185]
	v_lshlrev_b32_e32 v18, 16, v19
	v_and_b32_e32 v19, 0xffff0000, v19
	v_pk_add_f32 v[18:19], v[14:15], v[18:19]
	v_mul_f32_e32 v17, v21, v21
	v_fmac_f32_e32 v17, v20, v20
	v_fmac_f32_e32 v17, v18, v18
	v_fmac_f32_e32 v17, v19, v19
	v_lshlrev_b32_e32 v14, 16, v12
	v_and_b32_e32 v15, 0xffff0000, v12
	v_pk_add_f32 v[150:151], v[8:9], v[14:15]
	v_lshlrev_b32_e32 v12, 16, v13
	v_and_b32_e32 v13, 0xffff0000, v13
	v_mul_f32_e32 v8, v151, v151
	v_pk_add_f32 v[34:35], v[10:11], v[12:13]
	v_fmac_f32_e32 v8, v150, v150
	v_fmac_f32_e32 v8, v34, v34
	v_fmac_f32_e32 v8, v35, v35
	v_add_f32_e32 v12, v17, v8
	s_waitcnt vmcnt(1)
	v_mov_b64_e32 v[8:9], v[186:187]
	v_ashrrev_i32_e32 v17, 31, v16
	v_lshlrev_b32_e32 v10, 16, v8
	v_and_b32_e32 v11, 0xffff0000, v8
	v_pk_add_f32 v[158:159], v[4:5], v[10:11]
	v_lshlrev_b32_e32 v8, 16, v9
	v_and_b32_e32 v9, 0xffff0000, v9
	v_mul_f32_e32 v4, v159, v159
	v_pk_add_f32 v[156:157], v[6:7], v[8:9]
	v_fmac_f32_e32 v4, v158, v158
	v_fmac_f32_e32 v4, v156, v156
	v_fmac_f32_e32 v4, v157, v157
	v_add_f32_e32 v8, v12, v4
	s_waitcnt vmcnt(0)
	v_mov_b64_e32 v[4:5], v[188:189]
	v_lshlrev_b32_e32 v6, 16, v4
	v_and_b32_e32 v7, 0xffff0000, v4
	v_pk_add_f32 v[176:177], v[0:1], v[6:7]
	v_lshlrev_b32_e32 v4, 16, v5
	v_and_b32_e32 v5, 0xffff0000, v5
	v_mul_f32_e32 v0, v177, v177
	v_pk_add_f32 v[168:169], v[2:3], v[4:5]
	v_fmac_f32_e32 v0, v176, v176
	v_fmac_f32_e32 v0, v168, v168
	v_fmac_f32_e32 v0, v169, v169
	v_add_f32_e32 v0, v8, v0
	ds_bpermute_b32 v1, v141, v0
	s_waitcnt lgkmcnt(0)
	v_add_f32_e32 v0, v0, v1
	ds_bpermute_b32 v1, v183, v0
	s_and_saveexec_b64 s[8:9], vcc
	s_cbranch_execz .LBB0_1322
	v_lshl_add_u64 v[2:3], v[16:17], 2, s[4:5]
	s_waitcnt lgkmcnt(0)
	v_add_f32_e32 v0, v0, v1
	global_atomic_add_f32 v[2:3], v0, off
